# speedup vs baseline: 1.0153x; 1.0153x over previous
; #define BIG_SYNC(N)                                              \
;   asm volatile("s_waitcnt vmcnt(%0)" ::"n"(N) : "memory");       \
;   __builtin_amdgcn_s_barrier();                                  \
;   asm volatile("" ::: "memory");                                 \
;   __builtin_amdgcn_sched_barrier(0);
; template <int NK, bool BNT = false> ...
;     ...
; #pragma unroll
;   for (int m = 0; m < 4; ++m)
; #pragma unroll
;     for (int n = 0; n < 8; ++n) acc[m][n] = f32x4{0.f, 0.f, 0.f, 0.f};
;   const int sb0 = tidf * 16;
;   const int sr0 = sb0 >> 6;
;   const unsigned soff = (unsigned)(sr0 * 64 + ((((sb0 >> 4) & 3) ^ (((sr0 >> 3) & 1) << 1)) * 16));
;   const unsigned char* Abase = reinterpret_cast<const unsigned char*>(A);
;   const unsigned char* Bbase = reinterpret_cast<const unsigned char*>(B);
;   auto stage = [&](int kt, int bufc) {
;     unsigned char* sa = smem + bufc * BIG_STAGE;
;     const unsigned char* Ab = Abase + (long)kt * 8192 + soff;
;     const unsigned char* Bb = Bbase + (long)kt * 8192 + soff;
;     glds16(Ab, sa + sb0);
;     glds16(Ab + astride * 2, sa + 8192 + sb0);
;     if constexpr (BNT) {
;       glds16_nt(Bb, sa + 16384 + sb0);
;       glds16_nt(Bb + bstride * 2, sa + 24576 + sb0);
;     } else {
;       glds16(Bb, sa + 16384 + sb0);
;       glds16(Bb + bstride * 2, sa + 24576 + sb0);
;     }
;   };
;     ...
;   stage(0, 0);
;   stage(1, 1);
;   stage(2, 2);
;   for (int it = 0; it < NK / 4 - 1; ++it) {
;     const int t = it * 4;
;     BIG_SYNC(2 * NG); kstep(t, 0, 3, true);
.LBB0_67:
	s_ashr_i32 s9, s15, 31
	s_lshr_b32 s9, s9, 27
	s_add_i32 s9, s15, s9
	s_ashr_i32 s10, s9, 5
	s_and_b32 s9, s9, 0xffe0
	s_sub_i32 s9, s15, s9
	s_bfe_i32 s11, s9, 0x80000
	s_bfe_u32 s11, s11, 0x2000d
	s_add_i32 s11, s9, s11
	s_bfe_i32 s14, s11, 0x80000
	s_and_b32 s11, s11, 0xfffc
	s_sext_i32_i16 s17, s14
	s_sub_i32 s14, s9, s11
	s_lshl_b32 s9, s10, 3
	s_ashr_i32 s10, s17, 2
	s_bfe_i64 s[18:19], s[14:15], 0x80000
	s_add_i32 s10, s9, s10
	s_lshl_b64 s[18:19], s[18:19], 19
	s_add_u32 s20, s6, s18
	s_addc_u32 s21, s7, s19
	s_ashr_i32 s11, s10, 31
	v_readlane_b32 s64, v252, 4
	s_lshl_b64 s[22:23], s[10:11], 19
	v_readlane_b32 s76, v252, 16
	v_readfirstlane_b32 s9, v166
	v_add_u32_e32 v146, 0x2000, v166
	v_readlane_b32 s77, v252, 17
	s_add_u32 s24, s76, s22
	v_lshl_add_u64 v[130:131], s[20:21], 0, v[132:133]
	s_mov_b32 m0, s9
	s_mov_b64 s[20:21], 0x40000
	v_readfirstlane_b32 s9, v146
	v_add_u32_e32 v147, 0x4000, v166
	s_addc_u32 s25, s77, s23
	global_load_lds_dwordx4 v[130:131], off
	v_lshl_add_u64 v[0:1], v[130:131], 0, s[20:21]
	s_mov_b32 m0, s9
	v_readfirstlane_b32 s9, v147
	v_add_u32_e32 v148, 0x6000, v166
	v_lshl_add_u64 v[128:129], s[24:25], 0, v[132:133]
	global_load_lds_dwordx4 v[0:1], off
	s_mov_b32 m0, s9
	v_readfirstlane_b32 s9, v148
	v_add_u32_e32 v149, 0x8000, v166
	global_load_lds_dwordx4 v[128:129], off
	v_lshl_add_u64 v[0:1], v[128:129], 0, s[20:21]
	s_mov_b32 m0, s9
	s_mov_b64 s[20:21], 0x2000
	v_readfirstlane_b32 s9, v149
	v_add_u32_e32 v150, 0xa000, v166
	global_load_lds_dwordx4 v[0:1], off
	v_lshl_add_u64 v[0:1], v[130:131], 0, s[20:21]
	v_lshl_add_u64 v[2:3], v[128:129], 0, s[20:21]
	s_mov_b32 m0, s9
	s_mov_b64 s[20:21], 0x42000
	v_readfirstlane_b32 s9, v150
	v_add_u32_e32 v151, 0xc000, v166
	global_load_lds_dwordx4 v[0:1], off
	v_lshl_add_u64 v[0:1], v[130:131], 0, s[20:21]
	s_mov_b32 m0, s9
	v_readfirstlane_b32 s9, v151
	v_add_u32_e32 v152, 0xe000, v166
	global_load_lds_dwordx4 v[0:1], off
	s_mov_b32 m0, s9
	v_readfirstlane_b32 s9, v152
	v_add_u32_e32 v154, 0x10000, v166
	global_load_lds_dwordx4 v[2:3], off
	v_lshl_add_u64 v[0:1], v[128:129], 0, s[20:21]
	s_mov_b32 m0, s9
	v_readfirstlane_b32 s9, v154
	v_add_u32_e32 v155, 0x12000, v166
	global_load_lds_dwordx4 v[0:1], off
	v_lshl_add_u64 v[0:1], v[130:131], 0, s[94:95]
	s_mov_b32 m0, s9
	s_mov_b64 s[20:21], 0x44000
	v_readfirstlane_b32 s9, v155
	v_add_u32_e32 v156, 0x14000, v166
	global_load_lds_dwordx4 v[0:1], off
	v_lshl_add_u64 v[0:1], v[130:131], 0, s[20:21]
	s_mov_b32 m0, s9
	v_readfirstlane_b32 s9, v156
	v_add_u32_e32 v157, 0x16000, v166
	v_lshl_add_u64 v[2:3], v[128:129], 0, s[94:95]
	global_load_lds_dwordx4 v[0:1], off
	s_mov_b32 m0, s9
	v_readfirstlane_b32 s9, v157
	global_load_lds_dwordx4 v[2:3], off
	v_lshl_add_u64 v[0:1], v[128:129], 0, s[20:21]
	s_mov_b32 m0, s9
	v_lshl_add_u64 v[138:139], v[134:135], 0, s[18:19]
	global_load_lds_dwordx4 v[0:1], off
	v_mov_b32_e32 v0, 0
	v_lshl_add_u64 v[140:141], v[136:137], 0, s[22:23]
	s_mov_b64 s[36:37], 0
	v_mov_b32_e32 v1, v0
	v_mov_b32_e32 v2, v0
	v_mov_b32_e32 v3, v0
	v_mov_b32_e32 v4, v0
	s_waitcnt lgkmcnt(0)
	v_mov_b32_e32 v5, v0
	v_mov_b32_e32 v6, v0
	v_mov_b32_e32 v7, v0
	v_mov_b32_e32 v8, v0
	v_mov_b32_e32 v9, v0
	v_mov_b32_e32 v10, v0
	v_mov_b32_e32 v11, v0
	v_mov_b32_e32 v12, v0
	v_mov_b32_e32 v13, v0
	v_mov_b32_e32 v14, v0
	v_mov_b32_e32 v15, v0
	v_mov_b32_e32 v32, v0
	v_mov_b32_e32 v33, v0
	v_mov_b32_e32 v34, v0
	v_mov_b32_e32 v35, v0
	v_mov_b32_e32 v36, v0
	v_mov_b32_e32 v37, v0
	v_mov_b32_e32 v38, v0
	v_mov_b32_e32 v39, v0
	v_mov_b32_e32 v40, v0
	v_mov_b32_e32 v41, v0
	v_mov_b32_e32 v42, v0
	v_mov_b32_e32 v43, v0
	v_mov_b32_e32 v44, v0
	v_mov_b32_e32 v45, v0
	v_mov_b32_e32 v46, v0
	v_mov_b32_e32 v47, v0
	v_mov_b32_e32 v16, v0
	v_mov_b32_e32 v17, v0
	v_mov_b32_e32 v18, v0
	v_mov_b32_e32 v19, v0
	v_mov_b32_e32 v20, v0
	v_mov_b32_e32 v21, v0
	v_mov_b32_e32 v22, v0
	v_mov_b32_e32 v23, v0
	v_mov_b32_e32 v24, v0
	v_mov_b32_e32 v25, v0
	v_mov_b32_e32 v26, v0
	v_mov_b32_e32 v27, v0
	v_mov_b32_e32 v28, v0
	v_mov_b32_e32 v29, v0
	v_mov_b32_e32 v30, v0
	v_mov_b32_e32 v31, v0
	v_mov_b32_e32 v64, v0
	v_mov_b32_e32 v65, v0
	v_mov_b32_e32 v66, v0
	v_mov_b32_e32 v67, v0
	v_mov_b32_e32 v68, v0
	v_mov_b32_e32 v69, v0
	v_mov_b32_e32 v70, v0
	v_mov_b32_e32 v71, v0
	v_mov_b32_e32 v76, v0
	v_mov_b32_e32 v77, v0
	v_mov_b32_e32 v78, v0
	v_mov_b32_e32 v79, v0
	v_mov_b32_e32 v88, v0
	v_mov_b32_e32 v89, v0
	v_mov_b32_e32 v90, v0
	v_mov_b32_e32 v91, v0
	v_mov_b32_e32 v48, v0
	v_mov_b32_e32 v49, v0
	v_mov_b32_e32 v50, v0
	v_mov_b32_e32 v51, v0
	v_mov_b32_e32 v52, v0
	v_mov_b32_e32 v53, v0
	v_mov_b32_e32 v54, v0
	v_mov_b32_e32 v55, v0
	v_mov_b32_e32 v56, v0
	v_mov_b32_e32 v57, v0
	v_mov_b32_e32 v58, v0
	v_mov_b32_e32 v59, v0
	v_mov_b32_e32 v60, v0
	v_mov_b32_e32 v61, v0
	v_mov_b32_e32 v62, v0
	v_mov_b32_e32 v63, v0
	v_mov_b32_e32 v96, v0
	v_mov_b32_e32 v97, v0
	v_mov_b32_e32 v98, v0
	v_mov_b32_e32 v99, v0
	v_mov_b32_e32 v100, v0
	v_mov_b32_e32 v101, v0
	v_mov_b32_e32 v102, v0
	v_mov_b32_e32 v103, v0
	v_mov_b32_e32 v104, v0
	v_mov_b32_e32 v105, v0
	v_mov_b32_e32 v106, v0
	v_mov_b32_e32 v107, v0
	v_mov_b32_e32 v108, v0
	v_mov_b32_e32 v109, v0
	v_mov_b32_e32 v110, v0
	v_mov_b32_e32 v111, v0
	v_mov_b32_e32 v72, v0
	v_mov_b32_e32 v73, v0
	v_mov_b32_e32 v74, v0
	v_mov_b32_e32 v75, v0
	v_mov_b32_e32 v80, v0
	v_mov_b32_e32 v81, v0
	v_mov_b32_e32 v82, v0
	v_mov_b32_e32 v83, v0
	v_mov_b32_e32 v84, v0
	v_mov_b32_e32 v85, v0
	v_mov_b32_e32 v86, v0
	v_mov_b32_e32 v87, v0
	v_mov_b32_e32 v92, v0
	v_mov_b32_e32 v93, v0
	v_mov_b32_e32 v94, v0
	v_mov_b32_e32 v95, v0
	v_mov_b32_e32 v112, v0
	v_mov_b32_e32 v113, v0
	v_mov_b32_e32 v114, v0
	v_mov_b32_e32 v115, v0
	v_mov_b32_e32 v116, v0
	v_mov_b32_e32 v117, v0
	v_mov_b32_e32 v118, v0
	v_mov_b32_e32 v119, v0
	v_mov_b32_e32 v120, v0
	v_mov_b32_e32 v121, v0
	v_mov_b32_e32 v122, v0
	v_mov_b32_e32 v123, v0
	v_mov_b32_e32 v124, v0
	v_mov_b32_e32 v125, v0
	v_mov_b32_e32 v126, v0
	v_mov_b32_e32 v127, v0
	v_readlane_b32 s65, v252, 5
	v_readlane_b32 s66, v252, 6
	v_readlane_b32 s67, v252, 7
	v_readlane_b32 s68, v252, 8
	v_readlane_b32 s69, v252, 9
	v_readlane_b32 s70, v252, 10
	v_readlane_b32 s71, v252, 11
	v_readlane_b32 s72, v252, 12
	v_readlane_b32 s73, v252, 13
	v_readlane_b32 s74, v252, 14
	v_readlane_b32 s75, v252, 15
	v_readlane_b32 s78, v252, 18
	v_readlane_b32 s79, v252, 19
	s_waitcnt vmcnt(8)
	s_barrier
	v_add_u32_e32 v162, 0x10000, v167
	v_or_b32_e32 v163, 0x10000, v169
	v_add_u32_e32 v176, 0x18000, v167
	v_or_b32_e32 v179, 0x18000, v169
	ds_read_b128 v[216:219], v167
	ds_read_b128 v[220:223], v167 offset:1024
	ds_read_b128 v[224:227], v167 offset:2048
	ds_read_b128 v[228:231], v167 offset:3072
	ds_read_b128 v[232:235], v168 offset:16384
	ds_read_b128 v[236:239], v168 offset:17408
	ds_read_b128 v[240:243], v168 offset:18432
	ds_read_b128 v[244:247], v168 offset:19456
; #define BIG_SYNC(N)                                              \
;   asm volatile("s_waitcnt vmcnt(%0)" ::"n"(N) : "memory");       \
;   __builtin_amdgcn_s_barrier();                                  \
;   asm volatile("" ::: "memory");                                 \
;   __builtin_amdgcn_sched_barrier(0);
; template <int NK, bool BNT = false> ...
;     ...
;   auto kstep = [&](int T, int cur, int nxt, bool do_stage) {
;     const unsigned char* sa = smem + cur * BIG_STAGE;
;     bf16x8 af[4], bfr[4];
; #pragma unroll
;     for (int m = 0; m < 4; ++m) af[m] = *reinterpret_cast<const bf16x8*>(sa + aoff + m * 1024);
; #pragma unroll
;     for (int n = 0; n < 4; ++n) bfr[n] = *reinterpret_cast<const bf16x8*>(sa + boff + n * 1024);
;     __builtin_amdgcn_sched_barrier(0);
;     if (do_stage) stage(T + 3, nxt);
; #pragma unroll
;     for (int m = 0; m < 4; ++m)
; #pragma unroll
;       for (int n = 0; n < 4; ++n) acc[m][n] = __builtin_amdgcn_mfma_f32_16x16x32_bf16(af[m], bfr[n], acc[m][n], 0, 0, 0);
;     if (do_stage) {
; #pragma unroll
;       for (int q = 0; q < NG; ++q) {
;         __builtin_amdgcn_sched_group_barrier(0x008, 3, 0);
;         __builtin_amdgcn_sched_group_barrier(0x010, 1, 0);
;       }
;       __builtin_amdgcn_sched_group_barrier(0x008, 16 - 3 * NG, 0);
;     }
;     __builtin_amdgcn_sched_barrier(0);
; #pragma unroll
;     for (int n = 0; n < 4; ++n) bfr[n] = *reinterpret_cast<const bf16x8*>(sa + boff + (4 + n) * 1024);
; #pragma unroll
;     for (int m = 0; m < 4; ++m)
; #pragma unroll
;       for (int n = 0; n < 4; ++n)
;         acc[m][4 + n] = __builtin_amdgcn_mfma_f32_16x16x32_bf16(af[m], bfr[n], acc[m][4 + n], 0, 0, 0);
;     __builtin_amdgcn_sched_barrier(0);
;     ...
;   for (int it = 0; it < NK / 4 - 1; ++it) {
;     const int t = it * 4;
;     BIG_SYNC(2 * NG); kstep(t, 0, 3, true);
;     BIG_SYNC(2 * NG); kstep(t + 1, 1, 0, true);
;     BIG_SYNC(2 * NG); kstep(t + 2, 2, 1, true);
;     BIG_SYNC(2 * NG); kstep(t + 3, 3, 2, true);
.LBB0_68:
	s_waitcnt vmcnt(4)
	s_barrier
	v_add_u32_e32 v158, 0x18000, v166
	v_lshl_add_u64 v[144:145], v[138:139], 0, s[36:37]
	v_readfirstlane_b32 s9, v158
	v_add_u32_e32 v159, 0x1a000, v166
	v_lshl_add_u64 v[160:161], v[144:145], 0, s[60:61]
	s_mov_b32 m0, s9
	v_readfirstlane_b32 s9, v159
	s_waitcnt lgkmcnt(3)
	v_mfma_f32_16x16x32_bf16 v[124:127], v[216:219], v[232:235], v[124:127]
	v_lshl_add_u64 v[142:143], v[140:141], 0, s[36:37]
	v_lshl_add_u64 v[182:183], v[142:143], 0, s[60:61]
	v_mfma_f32_16x16x32_bf16 v[108:111], v[220:223], v[232:235], v[108:111]
	v_mfma_f32_16x16x32_bf16 v[88:91], v[224:227], v[232:235], v[88:91]
	global_load_lds_dwordx4 v[160:161], off
	v_lshl_add_u64 v[160:161], v[144:145], 0, s[80:81]
	s_mov_b32 m0, s9
	v_mfma_f32_16x16x32_bf16 v[44:47], v[228:231], v[232:235], v[44:47]
	s_waitcnt lgkmcnt(2)
	v_mfma_f32_16x16x32_bf16 v[120:123], v[216:219], v[236:239], v[120:123]
	ds_read_b128 v[232:235], v168 offset:20480
	v_mfma_f32_16x16x32_bf16 v[104:107], v[220:223], v[236:239], v[104:107]
	global_load_lds_dwordx4 v[160:161], off
	v_add_u32_e32 v160, 0x1c000, v166
	v_add_u32_e32 v161, 0x1e000, v166
	v_readfirstlane_b32 s9, v160
	s_mov_b32 m0, s9
	v_readfirstlane_b32 s9, v161
	v_mfma_f32_16x16x32_bf16 v[76:79], v[224:227], v[236:239], v[76:79]
	v_mfma_f32_16x16x32_bf16 v[40:43], v[228:231], v[236:239], v[40:43]
	s_waitcnt lgkmcnt(2)
	v_mfma_f32_16x16x32_bf16 v[116:119], v[216:219], v[240:243], v[116:119]
	ds_read_b128 v[236:239], v168 offset:21504
	global_load_lds_dwordx4 v[182:183], off
	v_lshl_add_u64 v[182:183], v[142:143], 0, s[80:81]
	s_mov_b32 m0, s9
	v_mfma_f32_16x16x32_bf16 v[100:103], v[220:223], v[240:243], v[100:103]
	v_mfma_f32_16x16x32_bf16 v[68:71], v[224:227], v[240:243], v[68:71]
	v_mfma_f32_16x16x32_bf16 v[36:39], v[228:231], v[240:243], v[36:39]
	global_load_lds_dwordx4 v[182:183], off
	s_waitcnt lgkmcnt(2)
	v_mfma_f32_16x16x32_bf16 v[112:115], v[216:219], v[244:247], v[112:115]
	ds_read_b128 v[240:243], v168 offset:22528
	v_mfma_f32_16x16x32_bf16 v[96:99], v[220:223], v[244:247], v[96:99]
	v_mfma_f32_16x16x32_bf16 v[64:67], v[224:227], v[244:247], v[64:67]
	v_mfma_f32_16x16x32_bf16 v[32:35], v[228:231], v[244:247], v[32:35]
	s_waitcnt lgkmcnt(2)
	v_mfma_f32_16x16x32_bf16 v[92:95], v[216:219], v[232:235], v[92:95]
	ds_read_b128 v[244:247], v168 offset:23552
	v_mfma_f32_16x16x32_bf16 v[60:63], v[220:223], v[232:235], v[60:63]
	ds_read_b128 v[186:189], v167 offset:32768
	v_mfma_f32_16x16x32_bf16 v[28:31], v[224:227], v[232:235], v[28:31]
	ds_read_b128 v[190:193], v167 offset:33792
	v_mfma_f32_16x16x32_bf16 v[12:15], v[228:231], v[232:235], v[12:15]
	ds_read_b128 v[194:197], v167 offset:34816
	s_waitcnt lgkmcnt(5)
	v_mfma_f32_16x16x32_bf16 v[84:87], v[216:219], v[236:239], v[84:87]
	ds_read_b128 v[202:205], v167 offset:35840
	ds_read_b128 v[232:235], v168 offset:49152
	v_mfma_f32_16x16x32_bf16 v[56:59], v[220:223], v[236:239], v[56:59]
	v_mfma_f32_16x16x32_bf16 v[24:27], v[224:227], v[236:239], v[24:27]
	v_mfma_f32_16x16x32_bf16 v[8:11], v[228:231], v[236:239], v[8:11]
	s_waitcnt lgkmcnt(6)
	v_mfma_f32_16x16x32_bf16 v[80:83], v[216:219], v[240:243], v[80:83]
	ds_read_b128 v[236:239], v168 offset:50176
	v_mfma_f32_16x16x32_bf16 v[52:55], v[220:223], v[240:243], v[52:55]
	v_mfma_f32_16x16x32_bf16 v[20:23], v[224:227], v[240:243], v[20:23]
	v_mfma_f32_16x16x32_bf16 v[4:7], v[228:231], v[240:243], v[4:7]
	s_waitcnt lgkmcnt(6)
	v_mfma_f32_16x16x32_bf16 v[72:75], v[216:219], v[244:247], v[72:75]
	ds_read_b128 v[240:243], v168 offset:51200
	v_mfma_f32_16x16x32_bf16 v[48:51], v[220:223], v[244:247], v[48:51]
	v_mfma_f32_16x16x32_bf16 v[16:19], v[224:227], v[244:247], v[16:19]
	v_mfma_f32_16x16x32_bf16 v[0:3], v[228:231], v[244:247], v[0:3]
	ds_read_b128 v[244:247], v168 offset:52224
	s_waitcnt vmcnt(4)
	s_barrier
	v_readfirstlane_b32 s9, v166
	v_lshl_add_u64 v[182:183], v[144:145], 0, s[62:63]
	s_mov_b32 m0, s9
	v_readfirstlane_b32 s9, v146
	s_waitcnt lgkmcnt(3)
	v_mfma_f32_16x16x32_bf16 v[124:127], v[186:189], v[232:235], v[124:127]
	v_lshl_add_u64 v[198:199], v[142:143], 0, s[62:63]
	v_mfma_f32_16x16x32_bf16 v[108:111], v[190:193], v[232:235], v[108:111]
	v_mfma_f32_16x16x32_bf16 v[88:91], v[194:197], v[232:235], v[88:91]
	global_load_lds_dwordx4 v[182:183], off
	v_lshl_add_u64 v[182:183], v[144:145], 0, s[0:1]
	s_mov_b32 m0, s9
	v_readfirstlane_b32 s9, v147
	v_mfma_f32_16x16x32_bf16 v[44:47], v[202:205], v[232:235], v[44:47]
	s_waitcnt lgkmcnt(2)
	v_mfma_f32_16x16x32_bf16 v[120:123], v[186:189], v[236:239], v[120:123]
	ds_read_b128 v[232:235], v168 offset:53248
	v_mfma_f32_16x16x32_bf16 v[104:107], v[190:193], v[236:239], v[104:107]
	global_load_lds_dwordx4 v[182:183], off
	s_mov_b32 m0, s9
	v_readfirstlane_b32 s9, v148
	v_lshl_add_u64 v[182:183], v[142:143], 0, s[0:1]
	v_mfma_f32_16x16x32_bf16 v[76:79], v[194:197], v[236:239], v[76:79]
	v_mfma_f32_16x16x32_bf16 v[40:43], v[202:205], v[236:239], v[40:43]
	s_waitcnt lgkmcnt(2)
	v_mfma_f32_16x16x32_bf16 v[116:119], v[186:189], v[240:243], v[116:119]
	ds_read_b128 v[236:239], v168 offset:54272
	global_load_lds_dwordx4 v[198:199], off
	s_mov_b32 m0, s9
	v_mfma_f32_16x16x32_bf16 v[100:103], v[190:193], v[240:243], v[100:103]
	v_mfma_f32_16x16x32_bf16 v[68:71], v[194:197], v[240:243], v[68:71]
	v_mfma_f32_16x16x32_bf16 v[36:39], v[202:205], v[240:243], v[36:39]
	global_load_lds_dwordx4 v[182:183], off
	s_waitcnt lgkmcnt(2)
	v_mfma_f32_16x16x32_bf16 v[112:115], v[186:189], v[244:247], v[112:115]
	ds_read_b128 v[240:243], v168 offset:55296
	v_mfma_f32_16x16x32_bf16 v[96:99], v[190:193], v[244:247], v[96:99]
	v_mfma_f32_16x16x32_bf16 v[64:67], v[194:197], v[244:247], v[64:67]
	v_mfma_f32_16x16x32_bf16 v[32:35], v[202:205], v[244:247], v[32:35]
	v_add_u32_e32 v162, 0x10000, v167
	v_or_b32_e32 v163, 0x10000, v169
	s_waitcnt lgkmcnt(2)
; #define BIG_SYNC(N)                                              \
;   asm volatile("s_waitcnt vmcnt(%0)" ::"n"(N) : "memory");       \
;   __builtin_amdgcn_s_barrier();                                  \
;   asm volatile("" ::: "memory");                                 \
;   __builtin_amdgcn_sched_barrier(0);
; template <int NK, bool BNT = false> ...
;     ...
;   auto kstep = [&](int T, int cur, int nxt, bool do_stage) {
;     const unsigned char* sa = smem + cur * BIG_STAGE;
;     bf16x8 af[4], bfr[4];
; #pragma unroll
;     for (int m = 0; m < 4; ++m) af[m] = *reinterpret_cast<const bf16x8*>(sa + aoff + m * 1024);
; #pragma unroll
;     for (int n = 0; n < 4; ++n) bfr[n] = *reinterpret_cast<const bf16x8*>(sa + boff + n * 1024);
;     __builtin_amdgcn_sched_barrier(0);
;     if (do_stage) stage(T + 3, nxt);
; #pragma unroll
;     for (int m = 0; m < 4; ++m)
; #pragma unroll
;       for (int n = 0; n < 4; ++n) acc[m][n] = __builtin_amdgcn_mfma_f32_16x16x32_bf16(af[m], bfr[n], acc[m][n], 0, 0, 0);
;     if (do_stage) {
; #pragma unroll
;       for (int q = 0; q < NG; ++q) {
;         __builtin_amdgcn_sched_group_barrier(0x008, 3, 0);
;         __builtin_amdgcn_sched_group_barrier(0x010, 1, 0);
;       }
;       __builtin_amdgcn_sched_group_barrier(0x008, 16 - 3 * NG, 0);
;     }
;     __builtin_amdgcn_sched_barrier(0);
; #pragma unroll
;     for (int n = 0; n < 4; ++n) bfr[n] = *reinterpret_cast<const bf16x8*>(sa + boff + (4 + n) * 1024);
; #pragma unroll
;     for (int m = 0; m < 4; ++m)
; #pragma unroll
;       for (int n = 0; n < 4; ++n)
;         acc[m][4 + n] = __builtin_amdgcn_mfma_f32_16x16x32_bf16(af[m], bfr[n], acc[m][4 + n], 0, 0, 0);
;     __builtin_amdgcn_sched_barrier(0);
;     ...
;   for (int it = 0; it < NK / 4 - 1; ++it) {
;     const int t = it * 4;
;     BIG_SYNC(2 * NG); kstep(t, 0, 3, true);
;     BIG_SYNC(2 * NG); kstep(t + 1, 1, 0, true);
;     BIG_SYNC(2 * NG); kstep(t + 2, 2, 1, true);
;     BIG_SYNC(2 * NG); kstep(t + 3, 3, 2, true);
	v_mfma_f32_16x16x32_bf16 v[92:95], v[186:189], v[232:235], v[92:95]
	ds_read_b128 v[244:247], v168 offset:56320
	v_mfma_f32_16x16x32_bf16 v[60:63], v[190:193], v[232:235], v[60:63]
	ds_read_b128 v[216:219], v162
	v_mfma_f32_16x16x32_bf16 v[28:31], v[194:197], v[232:235], v[28:31]
	ds_read_b128 v[220:223], v162 offset:1024
	v_mfma_f32_16x16x32_bf16 v[12:15], v[202:205], v[232:235], v[12:15]
	ds_read_b128 v[224:227], v162 offset:2048
	s_waitcnt lgkmcnt(5)
	v_mfma_f32_16x16x32_bf16 v[84:87], v[186:189], v[236:239], v[84:87]
	ds_read_b128 v[228:231], v162 offset:3072
	ds_read_b128 v[232:235], v163
	v_mfma_f32_16x16x32_bf16 v[56:59], v[190:193], v[236:239], v[56:59]
	v_mfma_f32_16x16x32_bf16 v[24:27], v[194:197], v[236:239], v[24:27]
	v_mfma_f32_16x16x32_bf16 v[8:11], v[202:205], v[236:239], v[8:11]
	s_waitcnt lgkmcnt(6)
	v_mfma_f32_16x16x32_bf16 v[80:83], v[186:189], v[240:243], v[80:83]
	ds_read_b128 v[236:239], v163 offset:1024
	v_mfma_f32_16x16x32_bf16 v[52:55], v[190:193], v[240:243], v[52:55]
	v_mfma_f32_16x16x32_bf16 v[20:23], v[194:197], v[240:243], v[20:23]
	v_mfma_f32_16x16x32_bf16 v[4:7], v[202:205], v[240:243], v[4:7]
	s_waitcnt lgkmcnt(6)
	v_mfma_f32_16x16x32_bf16 v[72:75], v[186:189], v[244:247], v[72:75]
	ds_read_b128 v[240:243], v163 offset:2048
	v_mfma_f32_16x16x32_bf16 v[48:51], v[190:193], v[244:247], v[48:51]
	v_mfma_f32_16x16x32_bf16 v[16:19], v[194:197], v[244:247], v[16:19]
	v_mfma_f32_16x16x32_bf16 v[0:3], v[202:205], v[244:247], v[0:3]
	ds_read_b128 v[244:247], v163 offset:3072
	s_waitcnt vmcnt(4)
	s_barrier
	v_add_u32_e32 v162, 0x10000, v167
	v_or_b32_e32 v163, 0x10000, v169
	v_add_u32_e32 v164, 0x10400, v169
	v_add_u32_e32 v165, 0x10800, v169
	v_add_u32_e32 v172, 0x10c00, v169
	v_readfirstlane_b32 s9, v149
	v_lshl_add_u64 v[174:175], v[144:145], 0, s[2:3]
	s_mov_b32 m0, s9
	v_readfirstlane_b32 s9, v150
	s_waitcnt lgkmcnt(3)
	v_mfma_f32_16x16x32_bf16 v[124:127], v[216:219], v[232:235], v[124:127]
	v_lshl_add_u64 v[178:179], v[142:143], 0, s[2:3]
	v_mfma_f32_16x16x32_bf16 v[108:111], v[220:223], v[232:235], v[108:111]
	v_mfma_f32_16x16x32_bf16 v[88:91], v[224:227], v[232:235], v[88:91]
	global_load_lds_dwordx4 v[174:175], off
	v_lshl_add_u64 v[174:175], v[144:145], 0, s[52:53]
	s_mov_b32 m0, s9
	v_readfirstlane_b32 s9, v151
	v_mfma_f32_16x16x32_bf16 v[44:47], v[228:231], v[232:235], v[44:47]
	s_waitcnt lgkmcnt(2)
	v_mfma_f32_16x16x32_bf16 v[120:123], v[216:219], v[236:239], v[120:123]
	ds_read_b128 v[232:235], v163 offset:4096
	v_mfma_f32_16x16x32_bf16 v[104:107], v[220:223], v[236:239], v[104:107]
	global_load_lds_dwordx4 v[174:175], off
	s_mov_b32 m0, s9
	v_readfirstlane_b32 s9, v152
	v_lshl_add_u64 v[174:175], v[142:143], 0, s[52:53]
	v_mfma_f32_16x16x32_bf16 v[76:79], v[224:227], v[236:239], v[76:79]
	v_mfma_f32_16x16x32_bf16 v[40:43], v[228:231], v[236:239], v[40:43]
	s_waitcnt lgkmcnt(2)
	v_mfma_f32_16x16x32_bf16 v[116:119], v[216:219], v[240:243], v[116:119]
	ds_read_b128 v[236:239], v163 offset:5120
	global_load_lds_dwordx4 v[178:179], off
	s_mov_b32 m0, s9
	v_mfma_f32_16x16x32_bf16 v[100:103], v[220:223], v[240:243], v[100:103]
	v_mfma_f32_16x16x32_bf16 v[68:71], v[224:227], v[240:243], v[68:71]
	v_mfma_f32_16x16x32_bf16 v[36:39], v[228:231], v[240:243], v[36:39]
	global_load_lds_dwordx4 v[174:175], off
	s_waitcnt lgkmcnt(2)
	v_mfma_f32_16x16x32_bf16 v[112:115], v[216:219], v[244:247], v[112:115]
	ds_read_b128 v[240:243], v163 offset:6144
	v_mfma_f32_16x16x32_bf16 v[96:99], v[220:223], v[244:247], v[96:99]
	v_mfma_f32_16x16x32_bf16 v[64:67], v[224:227], v[244:247], v[64:67]
	v_mfma_f32_16x16x32_bf16 v[32:35], v[228:231], v[244:247], v[32:35]
	v_add_u32_e32 v173, 0x11000, v169
	v_add_u32_e32 v174, 0x11400, v169
	v_add_u32_e32 v175, 0x11800, v169
	v_add_u32_e32 v178, 0x11c00, v169
	v_add_u32_e32 v162, 0x10000, v167
	v_or_b32_e32 v163, 0x10000, v169
	s_waitcnt lgkmcnt(2)
	v_mfma_f32_16x16x32_bf16 v[92:95], v[216:219], v[232:235], v[92:95]
	ds_read_b128 v[244:247], v163 offset:7168
	v_mfma_f32_16x16x32_bf16 v[60:63], v[220:223], v[232:235], v[60:63]
	ds_read_b128 v[186:189], v162 offset:32768
	v_mfma_f32_16x16x32_bf16 v[28:31], v[224:227], v[232:235], v[28:31]
	ds_read_b128 v[190:193], v162 offset:33792
	v_mfma_f32_16x16x32_bf16 v[12:15], v[228:231], v[232:235], v[12:15]
	ds_read_b128 v[194:197], v162 offset:34816
	s_waitcnt lgkmcnt(5)
	v_mfma_f32_16x16x32_bf16 v[84:87], v[216:219], v[236:239], v[84:87]
	ds_read_b128 v[202:205], v162 offset:35840
	ds_read_b128 v[232:235], v163 offset:32768
	v_mfma_f32_16x16x32_bf16 v[56:59], v[220:223], v[236:239], v[56:59]
	v_mfma_f32_16x16x32_bf16 v[24:27], v[224:227], v[236:239], v[24:27]
	v_mfma_f32_16x16x32_bf16 v[8:11], v[228:231], v[236:239], v[8:11]
	s_waitcnt lgkmcnt(6)
	v_mfma_f32_16x16x32_bf16 v[80:83], v[216:219], v[240:243], v[80:83]
	ds_read_b128 v[236:239], v163 offset:33792
	v_mfma_f32_16x16x32_bf16 v[52:55], v[220:223], v[240:243], v[52:55]
	v_mfma_f32_16x16x32_bf16 v[20:23], v[224:227], v[240:243], v[20:23]
	v_mfma_f32_16x16x32_bf16 v[4:7], v[228:231], v[240:243], v[4:7]
	s_waitcnt lgkmcnt(6)
	v_mfma_f32_16x16x32_bf16 v[72:75], v[216:219], v[244:247], v[72:75]
	ds_read_b128 v[240:243], v163 offset:34816
	v_mfma_f32_16x16x32_bf16 v[48:51], v[220:223], v[244:247], v[48:51]
	v_mfma_f32_16x16x32_bf16 v[16:19], v[224:227], v[244:247], v[16:19]
	v_mfma_f32_16x16x32_bf16 v[0:3], v[228:231], v[244:247], v[0:3]
	ds_read_b128 v[244:247], v163 offset:35840
	s_waitcnt vmcnt(4)
	s_barrier
; #define BIG_SYNC(N)                                              \
;   asm volatile("s_waitcnt vmcnt(%0)" ::"n"(N) : "memory");       \
;   __builtin_amdgcn_s_barrier();                                  \
;   asm volatile("" ::: "memory");                                 \
;   __builtin_amdgcn_sched_barrier(0);
; template <int NK, bool BNT = false> ...
;     ...
;   auto kstep = [&](int T, int cur, int nxt, bool do_stage) {
;     const unsigned char* sa = smem + cur * BIG_STAGE;
;     bf16x8 af[4], bfr[4];
; #pragma unroll
;     for (int m = 0; m < 4; ++m) af[m] = *reinterpret_cast<const bf16x8*>(sa + aoff + m * 1024);
; #pragma unroll
;     for (int n = 0; n < 4; ++n) bfr[n] = *reinterpret_cast<const bf16x8*>(sa + boff + n * 1024);
;     __builtin_amdgcn_sched_barrier(0);
;     if (do_stage) stage(T + 3, nxt);
; #pragma unroll
;     for (int m = 0; m < 4; ++m)
; #pragma unroll
;       for (int n = 0; n < 4; ++n) acc[m][n] = __builtin_amdgcn_mfma_f32_16x16x32_bf16(af[m], bfr[n], acc[m][n], 0, 0, 0);
;     if (do_stage) {
; #pragma unroll
;       for (int q = 0; q < NG; ++q) {
;         __builtin_amdgcn_sched_group_barrier(0x008, 3, 0);
;         __builtin_amdgcn_sched_group_barrier(0x010, 1, 0);
;       }
;       __builtin_amdgcn_sched_group_barrier(0x008, 16 - 3 * NG, 0);
;     }
;     __builtin_amdgcn_sched_barrier(0);
; #pragma unroll
;     for (int n = 0; n < 4; ++n) bfr[n] = *reinterpret_cast<const bf16x8*>(sa + boff + (4 + n) * 1024);
; #pragma unroll
;     for (int m = 0; m < 4; ++m)
; #pragma unroll
;       for (int n = 0; n < 4; ++n)
;         acc[m][4 + n] = __builtin_amdgcn_mfma_f32_16x16x32_bf16(af[m], bfr[n], acc[m][4 + n], 0, 0, 0);
;     __builtin_amdgcn_sched_barrier(0);
;     ...
;   for (int it = 0; it < NK / 4 - 1; ++it) {
;     const int t = it * 4;
;     BIG_SYNC(2 * NG); kstep(t, 0, 3, true);
;     BIG_SYNC(2 * NG); kstep(t + 1, 1, 0, true);
;     BIG_SYNC(2 * NG); kstep(t + 2, 2, 1, true);
;     BIG_SYNC(2 * NG); kstep(t + 3, 3, 2, true);
;   }
;   BIG_SYNC(2 * NG); kstep(NK - 4, 0, 3, true);
	v_add_u32_e32 v176, 0x18000, v167
	v_or_b32_e32 v179, 0x18000, v169
	v_add_u32_e32 v180, 0x18400, v169
	v_add_u32_e32 v181, 0x18800, v169
	v_add_u32_e32 v182, 0x18c00, v169
	v_readfirstlane_b32 s9, v154
	v_lshl_add_u64 v[248:249], v[144:145], 0, s[54:55]
	s_mov_b32 m0, s9
	v_readfirstlane_b32 s9, v155
	v_lshl_add_u64 v[144:145], v[144:145], 0, s[56:57]
	s_waitcnt lgkmcnt(3)
	v_mfma_f32_16x16x32_bf16 v[124:127], v[186:189], v[232:235], v[124:127]
	v_lshl_add_u64 v[250:251], v[142:143], 0, s[54:55]
	v_lshl_add_u64 v[142:143], v[142:143], 0, s[56:57]
	v_mfma_f32_16x16x32_bf16 v[108:111], v[190:193], v[232:235], v[108:111]
	v_mfma_f32_16x16x32_bf16 v[88:91], v[194:197], v[232:235], v[88:91]
	global_load_lds_dwordx4 v[248:249], off
	s_mov_b32 m0, s9
	v_readfirstlane_b32 s9, v156
	v_mfma_f32_16x16x32_bf16 v[44:47], v[202:205], v[232:235], v[44:47]
	s_waitcnt lgkmcnt(2)
	v_mfma_f32_16x16x32_bf16 v[120:123], v[186:189], v[236:239], v[120:123]
	ds_read_b128 v[232:235], v163 offset:36864
	v_mfma_f32_16x16x32_bf16 v[104:107], v[190:193], v[236:239], v[104:107]
	global_load_lds_dwordx4 v[144:145], off
	s_mov_b32 m0, s9
	v_readfirstlane_b32 s9, v157
	v_mfma_f32_16x16x32_bf16 v[76:79], v[194:197], v[236:239], v[76:79]
	v_mfma_f32_16x16x32_bf16 v[40:43], v[202:205], v[236:239], v[40:43]
	s_waitcnt lgkmcnt(2)
	v_mfma_f32_16x16x32_bf16 v[116:119], v[186:189], v[240:243], v[116:119]
	ds_read_b128 v[236:239], v163 offset:37888
	global_load_lds_dwordx4 v[250:251], off
	s_mov_b32 m0, s9
	v_mfma_f32_16x16x32_bf16 v[100:103], v[190:193], v[240:243], v[100:103]
	v_mfma_f32_16x16x32_bf16 v[68:71], v[194:197], v[240:243], v[68:71]
	v_mfma_f32_16x16x32_bf16 v[36:39], v[202:205], v[240:243], v[36:39]
	global_load_lds_dwordx4 v[142:143], off
	s_waitcnt lgkmcnt(2)
	v_mfma_f32_16x16x32_bf16 v[112:115], v[186:189], v[244:247], v[112:115]
	ds_read_b128 v[240:243], v163 offset:38912
	v_mfma_f32_16x16x32_bf16 v[96:99], v[190:193], v[244:247], v[96:99]
	v_mfma_f32_16x16x32_bf16 v[64:67], v[194:197], v[244:247], v[64:67]
	v_mfma_f32_16x16x32_bf16 v[32:35], v[202:205], v[244:247], v[32:35]
	v_add_u32_e32 v142, 0x19000, v169
	v_add_u32_e32 v143, 0x19400, v169
	v_add_u32_e32 v144, 0x19800, v169
	v_add_u32_e32 v145, 0x19c00, v169
	s_waitcnt lgkmcnt(2)
	v_mfma_f32_16x16x32_bf16 v[92:95], v[186:189], v[232:235], v[92:95]
	ds_read_b128 v[244:247], v163 offset:39936
	v_mfma_f32_16x16x32_bf16 v[60:63], v[190:193], v[232:235], v[60:63]
	ds_read_b128 v[216:219], v167
	v_mfma_f32_16x16x32_bf16 v[28:31], v[194:197], v[232:235], v[28:31]
	ds_read_b128 v[220:223], v167 offset:1024
	v_mfma_f32_16x16x32_bf16 v[12:15], v[202:205], v[232:235], v[12:15]
	ds_read_b128 v[224:227], v167 offset:2048
	s_waitcnt lgkmcnt(5)
	v_mfma_f32_16x16x32_bf16 v[84:87], v[186:189], v[236:239], v[84:87]
	ds_read_b128 v[228:231], v167 offset:3072
	ds_read_b128 v[232:235], v168 offset:16384
	v_mfma_f32_16x16x32_bf16 v[56:59], v[190:193], v[236:239], v[56:59]
	v_mfma_f32_16x16x32_bf16 v[24:27], v[194:197], v[236:239], v[24:27]
	v_mfma_f32_16x16x32_bf16 v[8:11], v[202:205], v[236:239], v[8:11]
	s_waitcnt lgkmcnt(6)
	v_mfma_f32_16x16x32_bf16 v[80:83], v[186:189], v[240:243], v[80:83]
	ds_read_b128 v[236:239], v168 offset:17408
	v_mfma_f32_16x16x32_bf16 v[52:55], v[190:193], v[240:243], v[52:55]
	v_mfma_f32_16x16x32_bf16 v[20:23], v[194:197], v[240:243], v[20:23]
	v_mfma_f32_16x16x32_bf16 v[4:7], v[202:205], v[240:243], v[4:7]
	s_waitcnt lgkmcnt(6)
	v_mfma_f32_16x16x32_bf16 v[72:75], v[186:189], v[244:247], v[72:75]
	ds_read_b128 v[240:243], v168 offset:18432
	v_mfma_f32_16x16x32_bf16 v[48:51], v[190:193], v[244:247], v[48:51]
	v_mfma_f32_16x16x32_bf16 v[16:19], v[194:197], v[244:247], v[16:19]
	v_mfma_f32_16x16x32_bf16 v[0:3], v[202:205], v[244:247], v[0:3]
	ds_read_b128 v[244:247], v168 offset:19456
	s_add_u32 s36, s36, 0x8000
	s_addc_u32 s37, s37, 0
	s_cmp_lg_u32 s36, 0x38000
	s_cbranch_scc1 .LBB0_68
	s_waitcnt vmcnt(4)
	s_barrier
	s_sext_i32_i8 s9, s14
	s_mov_b64 s[18:19], 0x3e000
	v_readfirstlane_b32 s11, v158
	v_lshl_add_u64 v[150:151], v[130:131], 0, s[18:19]
	v_lshl_add_u64 v[198:199], v[128:129], 0, s[18:19]
	s_mov_b32 m0, s11
	s_mov_b64 s[18:19], 0x7e000
	v_readfirstlane_b32 s11, v159
	v_lshl_add_u64 v[130:131], v[130:131], 0, s[18:19]
	s_waitcnt lgkmcnt(3)
	v_mfma_f32_16x16x32_bf16 v[124:127], v[216:219], v[232:235], v[124:127]
	v_lshl_add_u64 v[128:129], v[128:129], 0, s[18:19]
	v_mfma_f32_16x16x32_bf16 v[108:111], v[220:223], v[232:235], v[108:111]
	v_mfma_f32_16x16x32_bf16 v[88:91], v[224:227], v[232:235], v[88:91]
	global_load_lds_dwordx4 v[150:151], off
	s_mov_b32 m0, s11
	v_readfirstlane_b32 s11, v160
	v_mfma_f32_16x16x32_bf16 v[44:47], v[228:231], v[232:235], v[44:47]
	s_waitcnt lgkmcnt(2)
	v_mfma_f32_16x16x32_bf16 v[120:123], v[216:219], v[236:239], v[120:123]
	ds_read_b128 v[232:235], v168 offset:20480
	v_mfma_f32_16x16x32_bf16 v[104:107], v[220:223], v[236:239], v[104:107]
	global_load_lds_dwordx4 v[130:131], off
	s_mov_b32 m0, s11
	v_readfirstlane_b32 s11, v161
	v_mfma_f32_16x16x32_bf16 v[76:79], v[224:227], v[236:239], v[76:79]
	v_mfma_f32_16x16x32_bf16 v[40:43], v[228:231], v[236:239], v[40:43]
	s_waitcnt lgkmcnt(2)
	v_mfma_f32_16x16x32_bf16 v[116:119], v[216:219], v[240:243], v[116:119]
	ds_read_b128 v[236:239], v168 offset:21504
	global_load_lds_dwordx4 v[198:199], off
	s_mov_b32 m0, s11
	v_mfma_f32_16x16x32_bf16 v[100:103], v[220:223], v[240:243], v[100:103]
	v_mfma_f32_16x16x32_bf16 v[68:71], v[224:227], v[240:243], v[68:71]
	v_mfma_f32_16x16x32_bf16 v[36:39], v[228:231], v[240:243], v[36:39]
	global_load_lds_dwordx4 v[128:129], off
	s_waitcnt lgkmcnt(2)
; #define BIG_SYNC(N)                                              \
;   asm volatile("s_waitcnt vmcnt(%0)" ::"n"(N) : "memory");       \
;   __builtin_amdgcn_s_barrier();                                  \
;   asm volatile("" ::: "memory");                                 \
;   __builtin_amdgcn_sched_barrier(0);
; template <int NK, bool BNT = false> ...
;     ...
;   auto kstep = [&](int T, int cur, int nxt, bool do_stage) {
;     const unsigned char* sa = smem + cur * BIG_STAGE;
;     bf16x8 af[4], bfr[4];
; #pragma unroll
;     for (int m = 0; m < 4; ++m) af[m] = *reinterpret_cast<const bf16x8*>(sa + aoff + m * 1024);
; #pragma unroll
;     for (int n = 0; n < 4; ++n) bfr[n] = *reinterpret_cast<const bf16x8*>(sa + boff + n * 1024);
;     __builtin_amdgcn_sched_barrier(0);
;     if (do_stage) stage(T + 3, nxt);
; #pragma unroll
;     for (int m = 0; m < 4; ++m)
; #pragma unroll
;       for (int n = 0; n < 4; ++n) acc[m][n] = __builtin_amdgcn_mfma_f32_16x16x32_bf16(af[m], bfr[n], acc[m][n], 0, 0, 0);
;     if (do_stage) {
; #pragma unroll
;       for (int q = 0; q < NG; ++q) {
;         __builtin_amdgcn_sched_group_barrier(0x008, 3, 0);
;         __builtin_amdgcn_sched_group_barrier(0x010, 1, 0);
;       }
;       __builtin_amdgcn_sched_group_barrier(0x008, 16 - 3 * NG, 0);
;     }
;     __builtin_amdgcn_sched_barrier(0);
; #pragma unroll
;     for (int n = 0; n < 4; ++n) bfr[n] = *reinterpret_cast<const bf16x8*>(sa + boff + (4 + n) * 1024);
; #pragma unroll
;     for (int m = 0; m < 4; ++m)
; #pragma unroll
;       for (int n = 0; n < 4; ++n)
;         acc[m][4 + n] = __builtin_amdgcn_mfma_f32_16x16x32_bf16(af[m], bfr[n], acc[m][4 + n], 0, 0, 0);
;     __builtin_amdgcn_sched_barrier(0);
;     ...
;   BIG_SYNC(2 * NG); kstep(NK - 4, 0, 3, true);
;   BIG_SYNC(2 * NG); kstep(NK - 3, 1, 0, false);
;   BIG_SYNC(NG);     kstep(NK - 2, 2, 0, false);
	v_mfma_f32_16x16x32_bf16 v[112:115], v[216:219], v[244:247], v[112:115]
	ds_read_b128 v[240:243], v168 offset:22528
	v_mfma_f32_16x16x32_bf16 v[96:99], v[220:223], v[244:247], v[96:99]
	v_mfma_f32_16x16x32_bf16 v[64:67], v[224:227], v[244:247], v[64:67]
	v_mfma_f32_16x16x32_bf16 v[32:35], v[228:231], v[244:247], v[32:35]
	s_waitcnt lgkmcnt(2)
	v_mfma_f32_16x16x32_bf16 v[92:95], v[216:219], v[232:235], v[92:95]
	ds_read_b128 v[244:247], v168 offset:23552
	v_mfma_f32_16x16x32_bf16 v[60:63], v[220:223], v[232:235], v[60:63]
	ds_read_b128 v[186:189], v167 offset:32768
	v_mfma_f32_16x16x32_bf16 v[28:31], v[224:227], v[232:235], v[28:31]
	ds_read_b128 v[190:193], v167 offset:33792
	v_mfma_f32_16x16x32_bf16 v[12:15], v[228:231], v[232:235], v[12:15]
	ds_read_b128 v[194:197], v167 offset:34816
	s_waitcnt lgkmcnt(5)
	v_mfma_f32_16x16x32_bf16 v[84:87], v[216:219], v[236:239], v[84:87]
	ds_read_b128 v[202:205], v167 offset:35840
	ds_read_b128 v[232:235], v168 offset:49152
	v_mfma_f32_16x16x32_bf16 v[56:59], v[220:223], v[236:239], v[56:59]
	v_mfma_f32_16x16x32_bf16 v[24:27], v[224:227], v[236:239], v[24:27]
	v_mfma_f32_16x16x32_bf16 v[8:11], v[228:231], v[236:239], v[8:11]
	s_waitcnt lgkmcnt(6)
	v_mfma_f32_16x16x32_bf16 v[80:83], v[216:219], v[240:243], v[80:83]
	ds_read_b128 v[236:239], v168 offset:50176
	v_mfma_f32_16x16x32_bf16 v[52:55], v[220:223], v[240:243], v[52:55]
	v_mfma_f32_16x16x32_bf16 v[20:23], v[224:227], v[240:243], v[20:23]
	v_mfma_f32_16x16x32_bf16 v[4:7], v[228:231], v[240:243], v[4:7]
	s_waitcnt lgkmcnt(6)
	v_mfma_f32_16x16x32_bf16 v[72:75], v[216:219], v[244:247], v[72:75]
	ds_read_b128 v[240:243], v168 offset:51200
	v_mfma_f32_16x16x32_bf16 v[48:51], v[220:223], v[244:247], v[48:51]
	v_mfma_f32_16x16x32_bf16 v[16:19], v[224:227], v[244:247], v[16:19]
	v_mfma_f32_16x16x32_bf16 v[0:3], v[228:231], v[244:247], v[0:3]
	ds_read_b128 v[244:247], v168 offset:52224
	s_waitcnt vmcnt(4)
	s_barrier
	s_waitcnt lgkmcnt(3)
	v_mfma_f32_16x16x32_bf16 v[124:127], v[186:189], v[232:235], v[124:127]
	v_mfma_f32_16x16x32_bf16 v[108:111], v[190:193], v[232:235], v[108:111]
	v_mfma_f32_16x16x32_bf16 v[88:91], v[194:197], v[232:235], v[88:91]
	v_mfma_f32_16x16x32_bf16 v[44:47], v[202:205], v[232:235], v[44:47]
	s_waitcnt lgkmcnt(2)
	v_mfma_f32_16x16x32_bf16 v[120:123], v[186:189], v[236:239], v[120:123]
	ds_read_b128 v[232:235], v168 offset:53248
	v_mfma_f32_16x16x32_bf16 v[104:107], v[190:193], v[236:239], v[104:107]
	v_mfma_f32_16x16x32_bf16 v[76:79], v[194:197], v[236:239], v[76:79]
	v_mfma_f32_16x16x32_bf16 v[40:43], v[202:205], v[236:239], v[40:43]
	s_waitcnt lgkmcnt(2)
	v_mfma_f32_16x16x32_bf16 v[116:119], v[186:189], v[240:243], v[116:119]
	ds_read_b128 v[236:239], v168 offset:54272
	v_mfma_f32_16x16x32_bf16 v[100:103], v[190:193], v[240:243], v[100:103]
	v_mfma_f32_16x16x32_bf16 v[68:71], v[194:197], v[240:243], v[68:71]
	v_mfma_f32_16x16x32_bf16 v[36:39], v[202:205], v[240:243], v[36:39]
	s_waitcnt lgkmcnt(2)
	v_mfma_f32_16x16x32_bf16 v[112:115], v[186:189], v[244:247], v[112:115]
	ds_read_b128 v[240:243], v168 offset:55296
	v_mfma_f32_16x16x32_bf16 v[96:99], v[190:193], v[244:247], v[96:99]
	v_mfma_f32_16x16x32_bf16 v[64:67], v[194:197], v[244:247], v[64:67]
	v_mfma_f32_16x16x32_bf16 v[32:35], v[202:205], v[244:247], v[32:35]
	s_waitcnt lgkmcnt(2)
	v_mfma_f32_16x16x32_bf16 v[92:95], v[186:189], v[232:235], v[92:95]
	ds_read_b128 v[244:247], v168 offset:56320
	v_mfma_f32_16x16x32_bf16 v[60:63], v[190:193], v[232:235], v[60:63]
	v_mfma_f32_16x16x32_bf16 v[28:31], v[194:197], v[232:235], v[28:31]
	v_mfma_f32_16x16x32_bf16 v[12:15], v[202:205], v[232:235], v[12:15]
	s_waitcnt lgkmcnt(2)
	v_mfma_f32_16x16x32_bf16 v[84:87], v[186:189], v[236:239], v[84:87]
	v_mfma_f32_16x16x32_bf16 v[56:59], v[190:193], v[236:239], v[56:59]
	v_mfma_f32_16x16x32_bf16 v[24:27], v[194:197], v[236:239], v[24:27]
	v_mfma_f32_16x16x32_bf16 v[8:11], v[202:205], v[236:239], v[8:11]
	s_waitcnt lgkmcnt(1)
	v_mfma_f32_16x16x32_bf16 v[80:83], v[186:189], v[240:243], v[80:83]
	v_mfma_f32_16x16x32_bf16 v[52:55], v[190:193], v[240:243], v[52:55]
	v_mfma_f32_16x16x32_bf16 v[20:23], v[194:197], v[240:243], v[20:23]
	v_mfma_f32_16x16x32_bf16 v[4:7], v[202:205], v[240:243], v[4:7]
	s_waitcnt lgkmcnt(0)
	v_mfma_f32_16x16x32_bf16 v[72:75], v[186:189], v[244:247], v[72:75]
	v_mfma_f32_16x16x32_bf16 v[48:51], v[190:193], v[244:247], v[48:51]
	v_mfma_f32_16x16x32_bf16 v[16:19], v[194:197], v[244:247], v[16:19]
	v_mfma_f32_16x16x32_bf16 v[0:3], v[202:205], v[244:247], v[0:3]
	v_mov_b32_e32 v186, 0xf149f2ca
	v_mov_b32_e32 v187, 0x3c0881c4
	v_mov_b32_e32 v188, 0xbab64f3b
	v_mov_b32_e32 v189, 0x24800
	v_mov_b32_e32 v190, 1
	v_mov_b32_e32 v191, 0x24804
	v_mov_b32_e32 v192, 0xfcf
	v_mov_b32_e32 v193, 0x7cf
	v_mov_b32_e32 v194, 0xfdf
	v_mov_b32_e32 v195, 0x7df
	v_mov_b32_e32 v196, 0xfef
	v_mov_b32_e32 v197, 0x7ef
	v_mov_b32_e32 v198, 0xfff
	v_mov_b32_e32 v199, 0x7ff
	v_mov_b32_e32 v200, 0x20000
	v_mov_b32_e32 v201, 0xf8f
	v_mov_b32_e32 v202, 0x78f
	v_mov_b32_e32 v203, 0xf9f
	v_mov_b32_e32 v204, 0x79f
	v_mov_b32_e32 v205, 0xfaf
	s_waitcnt vmcnt(4)
	s_barrier
; #define BIG_SYNC(N)                                              \
;   asm volatile("s_waitcnt vmcnt(%0)" ::"n"(N) : "memory");       \
;   __builtin_amdgcn_s_barrier();                                  \
;   asm volatile("" ::: "memory");                                 \
;   __builtin_amdgcn_sched_barrier(0);
; template <int NK, bool BNT = false> ...
;     ...
;   auto kstep = [&](int T, int cur, int nxt, bool do_stage) {
;     const unsigned char* sa = smem + cur * BIG_STAGE;
;     bf16x8 af[4], bfr[4];
; #pragma unroll
;     for (int m = 0; m < 4; ++m) af[m] = *reinterpret_cast<const bf16x8*>(sa + aoff + m * 1024);
; #pragma unroll
;     for (int n = 0; n < 4; ++n) bfr[n] = *reinterpret_cast<const bf16x8*>(sa + boff + n * 1024);
;     __builtin_amdgcn_sched_barrier(0);
;     if (do_stage) stage(T + 3, nxt);
; #pragma unroll
;     for (int m = 0; m < 4; ++m)
; #pragma unroll
;       for (int n = 0; n < 4; ++n) acc[m][n] = __builtin_amdgcn_mfma_f32_16x16x32_bf16(af[m], bfr[n], acc[m][n], 0, 0, 0);
;     if (do_stage) {
; #pragma unroll
;       for (int q = 0; q < NG; ++q) {
;         __builtin_amdgcn_sched_group_barrier(0x008, 3, 0);
;         __builtin_amdgcn_sched_group_barrier(0x010, 1, 0);
;       }
;       __builtin_amdgcn_sched_group_barrier(0x008, 16 - 3 * NG, 0);
;     }
;     __builtin_amdgcn_sched_barrier(0);
; #pragma unroll
;     for (int n = 0; n < 4; ++n) bfr[n] = *reinterpret_cast<const bf16x8*>(sa + boff + (4 + n) * 1024);
; #pragma unroll
;     for (int m = 0; m < 4; ++m)
; #pragma unroll
;       for (int n = 0; n < 4; ++n)
;         acc[m][4 + n] = __builtin_amdgcn_mfma_f32_16x16x32_bf16(af[m], bfr[n], acc[m][4 + n], 0, 0, 0);
;     __builtin_amdgcn_sched_barrier(0);
;     ...
;   BIG_SYNC(NG);     kstep(NK - 2, 2, 0, false);
;   BIG_SYNC(0);      kstep(NK - 1, 3, 0, false);
	ds_read_b128 v[128:131], v162
	ds_read_b128 v[138:141], v162 offset:1024
	ds_read_b128 v[146:149], v162 offset:2048
	ds_read_b128 v[154:157], v162 offset:3072
	ds_read_b128 v[158:161], v163
	ds_read_b128 v[216:219], v164
	ds_read_b128 v[162:165], v165
	ds_read_b128 v[220:223], v172
	s_waitcnt lgkmcnt(0)
	v_mfma_f32_16x16x32_bf16 v[124:127], v[128:131], v[158:161], v[124:127]
	v_mfma_f32_16x16x32_bf16 v[116:119], v[128:131], v[162:165], v[116:119]
	v_mfma_f32_16x16x32_bf16 v[112:115], v[128:131], v[220:223], v[112:115]
	v_mfma_f32_16x16x32_bf16 v[104:107], v[138:141], v[216:219], v[104:107]
	v_mfma_f32_16x16x32_bf16 v[100:103], v[138:141], v[162:165], v[100:103]
	v_mfma_f32_16x16x32_bf16 v[96:99], v[138:141], v[220:223], v[96:99]
	v_mfma_f32_16x16x32_bf16 v[68:71], v[146:149], v[162:165], v[68:71]
	v_mfma_f32_16x16x32_bf16 v[64:67], v[146:149], v[220:223], v[64:67]
	v_mfma_f32_16x16x32_bf16 v[44:47], v[154:157], v[158:161], v[44:47]
	v_mfma_f32_16x16x32_bf16 v[40:43], v[154:157], v[216:219], v[40:43]
	v_mfma_f32_16x16x32_bf16 v[36:39], v[154:157], v[162:165], v[36:39]
	v_mfma_f32_16x16x32_bf16 v[32:35], v[154:157], v[220:223], v[32:35]
	v_mfma_f32_16x16x32_bf16 v[120:123], v[128:131], v[216:219], v[120:123]
	v_mfma_f32_16x16x32_bf16 v[224:227], v[138:141], v[158:161], v[108:111]
	v_mfma_f32_16x16x32_bf16 v[228:231], v[146:149], v[158:161], v[88:91]
	v_mfma_f32_16x16x32_bf16 v[232:235], v[146:149], v[216:219], v[76:79]
	s_nop 2
	ds_read_b128 v[76:79], v173
	ds_read_b128 v[88:91], v174
	s_waitcnt lgkmcnt(0)
	v_mfma_f32_16x16x32_bf16 v[158:161], v[128:131], v[76:79], v[92:95]
	s_nop 2
	ds_read_b128 v[92:95], v178
	v_mfma_f32_16x16x32_bf16 v[162:165], v[128:131], v[88:91], v[84:87]
	s_nop 2
	ds_read_b128 v[84:87], v175
	s_waitcnt lgkmcnt(0)
	v_mfma_f32_16x16x32_bf16 v[172:175], v[128:131], v[84:87], v[80:83]
	v_mfma_f32_16x16x32_bf16 v[128:131], v[128:131], v[92:95], v[72:75]
	v_mfma_f32_16x16x32_bf16 v[216:219], v[138:141], v[76:79], v[60:63]
	v_mfma_f32_16x16x32_bf16 v[220:223], v[138:141], v[88:91], v[56:59]
	v_mfma_f32_16x16x32_bf16 v[52:55], v[138:141], v[84:87], v[52:55]
	v_mfma_f32_16x16x32_bf16 v[48:51], v[138:141], v[92:95], v[48:51]
	v_mfma_f32_16x16x32_bf16 v[138:141], v[146:149], v[76:79], v[28:31]
	v_mfma_f32_16x16x32_bf16 v[236:239], v[146:149], v[88:91], v[24:27]
	v_mfma_f32_16x16x32_bf16 v[20:23], v[146:149], v[84:87], v[20:23]
	v_mfma_f32_16x16x32_bf16 v[16:19], v[146:149], v[92:95], v[16:19]
	v_mfma_f32_16x16x32_bf16 v[146:149], v[154:157], v[76:79], v[12:15]
	v_mfma_f32_16x16x32_bf16 v[0:3], v[154:157], v[92:95], v[0:3]
	v_mfma_f32_16x16x32_bf16 v[240:243], v[154:157], v[88:91], v[8:11]
	v_mfma_f32_16x16x32_bf16 v[244:247], v[154:157], v[84:87], v[4:7]
	s_waitcnt vmcnt(0)
	s_barrier
	s_nop 1
	ds_read_b128 v[4:7], v176
	ds_read_b128 v[8:11], v176 offset:1024
	ds_read_b128 v[154:157], v176 offset:2048
	ds_read_b128 v[12:15], v179
	ds_read_b128 v[24:27], v180
	ds_read_b128 v[28:31], v181
	ds_read_b128 v[56:59], v182
	ds_read_b128 v[248:251], v176 offset:3072
	s_waitcnt lgkmcnt(0)
	v_mfma_f32_16x16x32_bf16 v[108:111], v[4:7], v[24:27], v[120:123]
	v_mfma_f32_16x16x32_bf16 v[92:95], v[4:7], v[28:31], v[116:119]
	v_mfma_f32_16x16x32_bf16 v[76:79], v[4:7], v[56:59], v[112:115]
	v_mfma_f32_16x16x32_bf16 v[104:107], v[8:11], v[24:27], v[104:107]
	v_mfma_f32_16x16x32_bf16 v[88:91], v[8:11], v[28:31], v[100:103]
	v_mfma_f32_16x16x32_bf16 v[72:75], v[8:11], v[56:59], v[96:99]
	v_mfma_f32_16x16x32_bf16 v[100:103], v[154:157], v[24:27], v[232:235]
	v_mfma_f32_16x16x32_bf16 v[84:87], v[154:157], v[28:31], v[68:71]
	v_mfma_f32_16x16x32_bf16 v[68:71], v[154:157], v[56:59], v[64:67]
	v_mfma_f32_16x16x32_bf16 v[116:119], v[248:251], v[12:15], v[44:47]
	v_mfma_f32_16x16x32_bf16 v[96:99], v[248:251], v[24:27], v[40:43]
	v_mfma_f32_16x16x32_bf16 v[80:83], v[248:251], v[28:31], v[36:39]
	v_mfma_f32_16x16x32_bf16 v[64:67], v[248:251], v[56:59], v[32:35]
	v_mfma_f32_16x16x32_bf16 v[178:181], v[4:7], v[12:15], v[124:127]
	v_mfma_f32_16x16x32_bf16 v[224:227], v[8:11], v[12:15], v[224:227]
	v_mfma_f32_16x16x32_bf16 v[120:123], v[154:157], v[12:15], v[228:231]
	ds_read_b128 v[32:35], v142
	ds_read_b128 v[112:115], v143
	ds_read_b128 v[124:127], v144
	ds_read_b128 v[142:145], v145
	s_waitcnt lgkmcnt(0)
; __device__ __forceinline__ float bf2f(bf16_t b) { return __uint_as_float(((unsigned)b) << 16); }
; __device__ __forceinline__ int widen_off(int fq) { return ((fq & 1) << 4) + ((fq >> 1) << 3); }
; template <int MODE, int NSUB>
; __device__ __forceinline__ void epilogue(const Params& p, int layer, f32x4 (&acc)[4][NSUB], int tm, int tn, int g,
;                                          const float* s_rstd, const int tid_in) {
;     ...
;     const int fb = tm * 128 + wr * 64 + fq * 4;
;     const int tb = tn * (NSUB * 32) + wc * (NSUB * 16) + fr;
;     const int fw = tm * 128 + wr * 64 + widen_off(fq);
;     u32x4 curw[2], nxtw[2];
; #pragma unroll
;     for (int mp = 0; mp < 2; ++mp) curw[mp] = *reinterpret_cast<const u32x4*>(p.xb + blk(tb, fw + mp * 32, 32));
; #pragma unroll
;     for (int n = 0; n < NSUB; ++n) {
;       if (n + 1 < NSUB) {
; #pragma unroll
;         for (int mp = 0; mp < 2; ++mp) nxtw[mp] = *reinterpret_cast<const u32x4*>(p.xb + blk(tb + (n + 1) * 16, fw + mp * 32, 32));
;       }
;       bf16x4 cur[4];
;       unwiden_pair(curw[0], cur[0], cur[1]);
;       unwiden_pair(curw[1], cur[2], cur[3]);
;       const int t = tb + n * 16;
;       float ss = 0.f;
; #pragma unroll
;       for (int mp = 0; mp < 2; ++mp) {
;         bf16x4 pk[2];
; #pragma unroll
;         for (int h2 = 0; h2 < 2; ++h2) {
;           const int m = mp * 2 + h2;
;           const float x0 = bf2f((bf16_t)cur[m][0]) + acc[m][n][0], x1 = bf2f((bf16_t)cur[m][1]) + acc[m][n][1];
;           const float x2 = bf2f((bf16_t)cur[m][2]) + acc[m][n][2], x3 = bf2f((bf16_t)cur[m][3]) + acc[m][n][3];
;           ss += x0 * x0 + x1 * x1 + x2 * x2 + x3 * x3;
;           pk[h2] = pack4(x0, x1, x2, x3);
;         }
;         const int f = tm * 128 + wr * 64 + mp * 32 + widen_off(fq);
;         *reinterpret_cast<u32x4*>(p.xb + blk(t, f, 32)) = widen_pair(pk[0], pk[1]);
;       }
;       ss = red_fq(ss);
;       if (fq == 0) p.part[(long)t * 16 + tm * 2 + wr] = ss;
;       curw[0] = nxtw[0];
;       curw[1] = nxtw[1];
;     }
	v_mfma_f32_16x16x32_bf16 v[60:63], v[4:7], v[32:35], v[158:161]
	v_mfma_f32_16x16x32_bf16 v[44:47], v[4:7], v[112:115], v[162:165]
	v_mfma_f32_16x16x32_bf16 v[28:31], v[4:7], v[124:127], v[172:175]
	v_mfma_f32_16x16x32_bf16 v[12:15], v[4:7], v[142:145], v[128:131]
	v_mfma_f32_16x16x32_bf16 v[56:59], v[8:11], v[32:35], v[216:219]
	v_mfma_f32_16x16x32_bf16 v[40:43], v[8:11], v[112:115], v[220:223]
	v_mfma_f32_16x16x32_bf16 v[24:27], v[8:11], v[124:127], v[52:55]
	v_mfma_f32_16x16x32_bf16 v[8:11], v[8:11], v[142:145], v[48:51]
	v_mfma_f32_16x16x32_bf16 v[52:55], v[154:157], v[32:35], v[138:141]
	v_mfma_f32_16x16x32_bf16 v[36:39], v[154:157], v[112:115], v[236:239]
	v_mfma_f32_16x16x32_bf16 v[20:23], v[154:157], v[124:127], v[20:23]
	v_mfma_f32_16x16x32_bf16 v[4:7], v[154:157], v[142:145], v[16:19]
	v_mfma_f32_16x16x32_bf16 v[48:51], v[248:251], v[32:35], v[146:149]
	v_mfma_f32_16x16x32_bf16 v[32:35], v[248:251], v[112:115], v[240:243]
	v_mfma_f32_16x16x32_bf16 v[16:19], v[248:251], v[124:127], v[244:247]
	v_mfma_f32_16x16x32_bf16 v[0:3], v[248:251], v[142:145], v[0:3]
	v_lshl_add_u32 v124, s9, 1, v170
	v_mov_b32_e32 v112, v215
	v_lshlrev_b32_e32 v113, 7, v124
	v_ashrrev_i32_e32 v138, 7, v112
	v_lshl_add_u32 v114, v138, 6, v113
	v_lshlrev_b32_e32 v113, 1, v112
	v_and_b32_e32 v113, 0x80, v113
	v_lshl_or_b32 v127, s10, 8, v113
	v_lshrrev_b32_e32 v113, 2, v112
	v_and_b32_e32 v125, 15, v112
	v_and_b32_e32 v113, 8, v113
	v_ashrrev_i32_e32 v115, 2, v127
	v_readlane_b32 s80, v253, 25
	v_ashrrev_i32_e32 v114, 5, v114
	v_bfe_u32 v126, v112, 4, 2
	v_and_or_b32 v112, v112, 16, v113
	v_lshlrev_b32_e32 v156, 6, v125
	v_mov_b32_e32 v157, v153
	v_readlane_b32 s84, v253, 29
	v_readlane_b32 s85, v253, 30
	v_add_u32_e32 v114, v114, v115
	v_lshlrev_b32_e32 v152, 1, v112
	v_lshl_add_u64 v[144:145], s[84:85], 0, v[156:157]
	v_ashrrev_i32_e32 v115, 31, v114
	v_lshl_add_u64 v[112:113], v[144:145], 0, v[152:153]
	v_lshlrev_b64 v[146:147], 13, v[114:115]
	v_or_b32_e32 v114, 1, v114
	v_lshl_add_u64 v[150:151], v[112:113], 0, v[146:147]
	v_ashrrev_i32_e32 v115, 31, v114
	global_load_dwordx4 v[158:161], v[150:151], off
	v_lshlrev_b64 v[148:149], 13, v[114:115]
	v_lshl_add_u64 v[154:155], v[112:113], 0, v[148:149]
	global_load_dwordx4 v[128:131], v[154:155], off
	v_and_b32_e32 v113, 64, v185
	v_xor_b32_e32 v112, 16, v185
	v_add_u32_e32 v113, 64, v113
	v_cmp_lt_i32_e32 vcc, v112, v113
	v_or_b32_e32 v142, v127, v125
	v_lshlrev_b32_e32 v140, 1, v124
	v_cndmask_b32_e32 v112, v185, v112, vcc
	v_lshlrev_b32_e32 v172, 2, v112
	v_xor_b32_e32 v112, 32, v185
	v_cmp_lt_i32_e32 vcc, v112, v113
	v_ashrrev_i32_e32 v141, 31, v140
	v_ashrrev_i32_e32 v139, 31, v138
	v_cndmask_b32_e32 v112, v185, v112, vcc
	v_lshlrev_b32_e32 v173, 2, v112
	v_cmp_eq_u32_e32 vcc, 0, v126
	global_load_dwordx4 v[124:127], v[150:151], off offset:1024
	global_load_dwordx4 v[112:115], v[154:155], off offset:1024
	v_readlane_b32 s81, v253, 26
	v_readlane_b32 s82, v253, 27
	v_readlane_b32 s83, v253, 28
	v_readlane_b32 s86, v253, 31
	v_readlane_b32 s87, v253, 32
	v_readlane_b32 s88, v253, 33
	v_readlane_b32 s89, v253, 34
	v_readlane_b32 s90, v253, 35
	v_readlane_b32 s91, v253, 36
	v_readlane_b32 s92, v253, 37
	v_readlane_b32 s93, v253, 38
	v_readlane_b32 s94, v253, 39
	v_readlane_b32 s95, v253, 40
	s_waitcnt vmcnt(0)
	v_mov_b32_e32 v143, v160
	s_nop 1
	v_permlane16_swap_b32_e32 v158, v143
	v_mov_b32_e32 v164, v161
	s_nop 1
	v_permlane16_swap_b32_e32 v159, v164
	v_mov_b32_e32 v176, v130
	v_mov_b32_e32 v182, v131
	v_and_b32_e32 v131, 0xffff0000, v158
	v_lshlrev_b32_e32 v130, 16, v158
	v_pk_add_f32 v[130:131], v[178:179], v[130:131]
	v_and_b32_e32 v161, 0xffff0000, v159
	v_lshlrev_b32_e32 v160, 16, v159
	v_pk_add_f32 v[162:163], v[180:181], v[160:161]
	v_pk_mul_f32 v[160:161], v[130:131], v[130:131]
	v_cvt_pk_bf16_f32 v178, v130, v131
	v_and_b32_e32 v131, 0xffff0000, v143
	v_lshlrev_b32_e32 v130, 16, v143
	v_pk_mul_f32 v[158:159], v[162:163], v[162:163]
	v_cvt_pk_bf16_f32 v179, v162, v163
	v_pk_add_f32 v[130:131], v[224:225], v[130:131]
	v_and_b32_e32 v163, 0xffff0000, v164
	v_lshlrev_b32_e32 v162, 16, v164
	v_pk_add_f32 v[174:175], v[226:227], v[162:163]
	v_pk_mul_f32 v[164:165], v[130:131], v[130:131]
	v_cvt_pk_bf16_f32 v180, v130, v131
	v_lshl_add_u64 v[130:131], s[84:85], 0, v[146:147]
	v_pk_mul_f32 v[162:163], v[174:175], v[174:175]
	v_cvt_pk_bf16_f32 v181, v174, v175
	v_lshl_add_u64 v[174:175], v[130:131], 0, v[156:157]
	v_permlane16_swap_b32_e32 v128, v176
	v_permlane16_swap_b32_e32 v178, v180
	v_permlane16_swap_b32_e32 v179, v181
	v_lshl_add_u64 v[174:175], v[174:175], 0, v[152:153]
	v_permlane16_swap_b32_e32 v129, v182
	global_store_dwordx4 v[174:175], v[178:181], off
	v_and_b32_e32 v175, 0xffff0000, v128
	v_lshlrev_b32_e32 v174, 16, v128
	v_pk_add_f32 v[120:121], v[120:121], v[174:175]
	v_and_b32_e32 v175, 0xffff0000, v129
	v_lshlrev_b32_e32 v174, 16, v129
	v_pk_add_f32 v[122:123], v[122:123], v[174:175]
	v_pk_mul_f32 v[128:129], v[120:121], v[120:121]
	v_pk_mul_f32 v[174:175], v[122:123], v[122:123]
	v_cvt_pk_bf16_f32 v120, v120, v121
	v_cvt_pk_bf16_f32 v121, v122, v123
	v_and_b32_e32 v123, 0xffff0000, v176
	v_lshlrev_b32_e32 v122, 16, v176
	v_pk_add_f32 v[116:117], v[116:117], v[122:123]
	v_and_b32_e32 v123, 0xffff0000, v182
	v_lshlrev_b32_e32 v122, 16, v182
	v_add_f32_e32 v143, v164, v165
	v_add_f32_e32 v160, v160, v161
	v_pk_add_f32 v[118:119], v[118:119], v[122:123]
	v_pk_mul_f32 v[122:123], v[116:117], v[116:117]
	v_add_f32_e32 v143, v162, v143
	v_add_f32_e32 v158, v158, v160
	v_add_f32_e32 v128, v128, v129
	v_pk_mul_f32 v[178:179], v[118:119], v[118:119]
	v_add_f32_e32 v143, v163, v143
	v_add_f32_e32 v158, v159, v158
	v_add_f32_e32 v128, v174, v128
	v_add_f32_e32 v122, v122, v123
	v_add_f32_e32 v143, v158, v143
	v_add_f32_e32 v128, v175, v128
	v_add_f32_e32 v122, v178, v122
	v_add_f32_e32 v128, v143, v128
	v_add_f32_e32 v122, v179, v122
	v_add_f32_e32 v143, v122, v128
	v_lshl_add_u64 v[128:129], s[84:85], 0, v[148:149]
	v_cvt_pk_bf16_f32 v122, v116, v117
	v_cvt_pk_bf16_f32 v123, v118, v119
	v_lshl_add_u64 v[116:117], v[128:129], 0, v[156:157]
	v_permlane16_swap_b32_e32 v120, v122
	v_permlane16_swap_b32_e32 v121, v123
	v_lshl_add_u64 v[116:117], v[116:117], 0, v[152:153]
	global_store_dwordx4 v[116:117], v[120:123], off
	ds_bpermute_b32 v116, v172, v143
	s_waitcnt lgkmcnt(0)
	v_add_f32_e32 v116, v143, v116
	ds_bpermute_b32 v117, v173, v116
	s_and_saveexec_b64 s[10:11], vcc
	s_cbranch_execz .LBB0_71
; template <int MODE, int NSUB>
; __device__ __forceinline__ void epilogue(const Params& p, int layer, f32x4 (&acc)[4][NSUB], int tm, int tn, int g,
;                                          const float* s_rstd, const int tid_in) {
;     ...
;       ss = red_fq(ss);
;       if (fq == 0) p.part[(long)t * 16 + tm * 2 + wr] = ss;
	v_ashrrev_i32_e32 v143, 31, v142
	v_readlane_b32 s64, v253, 25
	v_lshlrev_b64 v[118:119], 6, v[142:143]
	v_readlane_b32 s70, v253, 31
	v_readlane_b32 s71, v253, 32
	s_waitcnt lgkmcnt(0)
	v_add_f32_e32 v116, v116, v117
	v_readlane_b32 s65, v253, 26
	v_lshl_add_u64 v[118:119], s[70:71], 0, v[118:119]
	v_lshl_add_u64 v[118:119], v[140:141], 2, v[118:119]
	v_lshl_add_u64 v[118:119], v[138:139], 2, v[118:119]
	v_readlane_b32 s66, v253, 27
	v_readlane_b32 s67, v253, 28
	v_readlane_b32 s68, v253, 29
	v_readlane_b32 s69, v253, 30
	v_readlane_b32 s72, v253, 33
	v_readlane_b32 s73, v253, 34
	v_readlane_b32 s74, v253, 35
	v_readlane_b32 s75, v253, 36
	v_readlane_b32 s76, v253, 37
	v_readlane_b32 s77, v253, 38
	v_readlane_b32 s78, v253, 39
	v_readlane_b32 s79, v253, 40
	global_store_dword v[118:119], v116, off

; #define BIG_SYNC(N)                                              \
;   asm volatile("s_waitcnt vmcnt(%0)" ::"n"(N) : "memory");       \
;   __builtin_amdgcn_s_barrier();                                  \
;   asm volatile("" ::: "memory");                                 \
;   __builtin_amdgcn_sched_barrier(0);
; template <int NK, bool BNT = false> ...
;     ...
; #pragma unroll
;   for (int m = 0; m < 4; ++m)
; #pragma unroll
;     for (int n = 0; n < 8; ++n) acc[m][n] = f32x4{0.f, 0.f, 0.f, 0.f};
;   const int sb0 = tidf * 16;
;   const int sr0 = sb0 >> 6;
;   const unsigned soff = (unsigned)(sr0 * 64 + ((((sb0 >> 4) & 3) ^ (((sr0 >> 3) & 1) << 1)) * 16));
;   const unsigned char* Abase = reinterpret_cast<const unsigned char*>(A);
;   const unsigned char* Bbase = reinterpret_cast<const unsigned char*>(B);
;   auto stage = [&](int kt, int bufc) {
;     unsigned char* sa = smem + bufc * BIG_STAGE;
;     const unsigned char* Ab = Abase + (long)kt * 8192 + soff;
;     const unsigned char* Bb = Bbase + (long)kt * 8192 + soff;
;     glds16(Ab, sa + sb0);
;     glds16(Ab + astride * 2, sa + 8192 + sb0);
;     if constexpr (BNT) {
;       glds16_nt(Bb, sa + 16384 + sb0);
;       glds16_nt(Bb + bstride * 2, sa + 24576 + sb0);
;     } else {
;       glds16(Bb, sa + 16384 + sb0);
;       glds16(Bb + bstride * 2, sa + 24576 + sb0);
;     }
;   };
;     ...
;   stage(0, 0);
;   stage(1, 1);
;   stage(2, 2);
;   for (int it = 0; it < NK / 4 - 1; ++it) {
;     const int t = it * 4;
;     BIG_SYNC(2 * NG); kstep(t, 0, 3, true);
.LBB0_263:
	s_ashr_i32 s12, s9, 31
	s_lshr_b32 s12, s12, 27
	s_add_i32 s12, s9, s12
	s_ashr_i32 s13, s12, 5
	s_and_b32 s12, s12, 0xffe0
	s_sub_i32 s12, s9, s12
	s_bfe_i32 s14, s12, 0x80000
	s_bfe_u32 s14, s14, 0x2000d
	s_add_i32 s14, s12, s14
	s_bfe_i32 s17, s14, 0x80000
	s_and_b32 s14, s14, 0xfffc
	s_sext_i32_i16 s17, s17
	s_sub_i32 s14, s12, s14
	s_lshl_b32 s12, s13, 3
	s_ashr_i32 s13, s17, 2
	s_bfe_i64 s[18:19], s[14:15], 0x80000
	s_add_i32 s12, s12, s13
	s_lshl_b64 s[18:19], s[18:19], 21
	s_add_u32 s20, s10, s18
	s_addc_u32 s21, s11, s19
	s_ashr_i32 s13, s12, 31
	v_readlane_b32 s64, v252, 4
	s_lshl_b64 s[22:23], s[12:13], 21
	v_readlane_b32 s78, v252, 18
	v_readfirstlane_b32 s13, v166
	v_add_u32_e32 v146, 0x2000, v166
	v_readlane_b32 s79, v252, 19
	s_add_u32 s24, s78, s22
	v_lshl_add_u64 v[130:131], s[20:21], 0, v[132:133]
	s_mov_b32 m0, s13
	s_mov_b64 s[20:21], 0x100000
	v_readfirstlane_b32 s13, v146
	v_add_u32_e32 v147, 0x4000, v166
	s_addc_u32 s25, s79, s23
	global_load_lds_dwordx4 v[130:131], off
	v_lshl_add_u64 v[0:1], v[130:131], 0, s[20:21]
	s_mov_b32 m0, s13
	v_readfirstlane_b32 s13, v147
	v_add_u32_e32 v148, 0x6000, v166
	v_lshl_add_u64 v[128:129], s[24:25], 0, v[132:133]
	global_load_lds_dwordx4 v[0:1], off
	s_mov_b32 m0, s13
	v_readfirstlane_b32 s13, v148
	v_add_u32_e32 v149, 0x8000, v166
	global_load_lds_dwordx4 v[128:129], off nt
	v_lshl_add_u64 v[0:1], v[128:129], 0, s[20:21]
	s_mov_b32 m0, s13
	s_mov_b64 s[20:21], 0x2000
	v_readfirstlane_b32 s13, v149
	v_add_u32_e32 v150, 0xa000, v166
	global_load_lds_dwordx4 v[0:1], off nt
	v_lshl_add_u64 v[0:1], v[130:131], 0, s[20:21]
	v_lshl_add_u64 v[2:3], v[128:129], 0, s[20:21]
	s_mov_b32 m0, s13
	s_mov_b64 s[20:21], 0x102000
	v_readfirstlane_b32 s13, v150
	v_add_u32_e32 v151, 0xc000, v166
	global_load_lds_dwordx4 v[0:1], off
	v_lshl_add_u64 v[0:1], v[130:131], 0, s[20:21]
	s_mov_b32 m0, s13
	v_readfirstlane_b32 s13, v151
	v_add_u32_e32 v152, 0xe000, v166
	global_load_lds_dwordx4 v[0:1], off
	s_mov_b32 m0, s13
	v_readfirstlane_b32 s13, v152
	v_add_u32_e32 v154, 0x10000, v166
	global_load_lds_dwordx4 v[2:3], off nt
	v_lshl_add_u64 v[0:1], v[128:129], 0, s[20:21]
	s_mov_b32 m0, s13
	v_readfirstlane_b32 s13, v154
	v_add_u32_e32 v155, 0x12000, v166
	global_load_lds_dwordx4 v[0:1], off nt
	v_lshl_add_u64 v[0:1], v[130:131], 0, s[94:95]
	s_mov_b32 m0, s13
	s_mov_b64 s[20:21], 0x104000
	v_readfirstlane_b32 s13, v155
	v_add_u32_e32 v156, 0x14000, v166
	global_load_lds_dwordx4 v[0:1], off
	v_lshl_add_u64 v[0:1], v[130:131], 0, s[20:21]
	s_mov_b32 m0, s13
	v_readfirstlane_b32 s13, v156
	v_add_u32_e32 v157, 0x16000, v166
	v_lshl_add_u64 v[2:3], v[128:129], 0, s[94:95]
	global_load_lds_dwordx4 v[0:1], off
	s_mov_b32 m0, s13
	v_readfirstlane_b32 s13, v157
	global_load_lds_dwordx4 v[2:3], off nt
	v_lshl_add_u64 v[0:1], v[128:129], 0, s[20:21]
	s_mov_b32 m0, s13
	v_lshl_add_u64 v[138:139], v[134:135], 0, s[18:19]
	global_load_lds_dwordx4 v[0:1], off nt
	v_mov_b32_e32 v0, 0
	v_lshl_add_u64 v[140:141], v[136:137], 0, s[22:23]
	s_mov_b64 s[36:37], 0
	v_mov_b32_e32 v1, v0
	v_mov_b32_e32 v2, v0
	v_mov_b32_e32 v3, v0
	v_mov_b32_e32 v4, v0
	s_waitcnt lgkmcnt(0)
	v_mov_b32_e32 v5, v0
	v_mov_b32_e32 v6, v0
	v_mov_b32_e32 v7, v0
	v_mov_b32_e32 v8, v0
	v_mov_b32_e32 v9, v0
	v_mov_b32_e32 v10, v0
	v_mov_b32_e32 v11, v0
	v_mov_b32_e32 v12, v0
	v_mov_b32_e32 v13, v0
	v_mov_b32_e32 v14, v0
	v_mov_b32_e32 v15, v0
	v_mov_b32_e32 v32, v0
	v_mov_b32_e32 v33, v0
	v_mov_b32_e32 v34, v0
	v_mov_b32_e32 v35, v0
	v_mov_b32_e32 v36, v0
	v_mov_b32_e32 v37, v0
	v_mov_b32_e32 v38, v0
	v_mov_b32_e32 v39, v0
	v_mov_b32_e32 v40, v0
	v_mov_b32_e32 v41, v0
	v_mov_b32_e32 v42, v0
	v_mov_b32_e32 v43, v0
	v_mov_b32_e32 v44, v0
	v_mov_b32_e32 v45, v0
	v_mov_b32_e32 v46, v0
	v_mov_b32_e32 v47, v0
	v_mov_b32_e32 v16, v0
	v_mov_b32_e32 v17, v0
	v_mov_b32_e32 v18, v0
	v_mov_b32_e32 v19, v0
	v_mov_b32_e32 v20, v0
	v_mov_b32_e32 v21, v0
	v_mov_b32_e32 v22, v0
	v_mov_b32_e32 v23, v0
	v_mov_b32_e32 v24, v0
	v_mov_b32_e32 v25, v0
	v_mov_b32_e32 v26, v0
	v_mov_b32_e32 v27, v0
	v_mov_b32_e32 v28, v0
	v_mov_b32_e32 v29, v0
	v_mov_b32_e32 v30, v0
	v_mov_b32_e32 v31, v0
	v_mov_b32_e32 v64, v0
	v_mov_b32_e32 v65, v0
	v_mov_b32_e32 v66, v0
	v_mov_b32_e32 v67, v0
	v_mov_b32_e32 v68, v0
	v_mov_b32_e32 v69, v0
	v_mov_b32_e32 v70, v0
	v_mov_b32_e32 v71, v0
	v_mov_b32_e32 v76, v0
	v_mov_b32_e32 v77, v0
	v_mov_b32_e32 v78, v0
	v_mov_b32_e32 v79, v0
	v_mov_b32_e32 v88, v0
	v_mov_b32_e32 v89, v0
	v_mov_b32_e32 v90, v0
	v_mov_b32_e32 v91, v0
	v_mov_b32_e32 v48, v0
	v_mov_b32_e32 v49, v0
	v_mov_b32_e32 v50, v0
	v_mov_b32_e32 v51, v0
	v_mov_b32_e32 v52, v0
	v_mov_b32_e32 v53, v0
	v_mov_b32_e32 v54, v0
	v_mov_b32_e32 v55, v0
	v_mov_b32_e32 v56, v0
	v_mov_b32_e32 v57, v0
	v_mov_b32_e32 v58, v0
	v_mov_b32_e32 v59, v0
	v_mov_b32_e32 v60, v0
	v_mov_b32_e32 v61, v0
	v_mov_b32_e32 v62, v0
	v_mov_b32_e32 v63, v0
	v_mov_b32_e32 v96, v0
	v_mov_b32_e32 v97, v0
	v_mov_b32_e32 v98, v0
	v_mov_b32_e32 v99, v0
	v_mov_b32_e32 v100, v0
	v_mov_b32_e32 v101, v0
	v_mov_b32_e32 v102, v0
	v_mov_b32_e32 v103, v0
	v_mov_b32_e32 v104, v0
	v_mov_b32_e32 v105, v0
	v_mov_b32_e32 v106, v0
	v_mov_b32_e32 v107, v0
	v_mov_b32_e32 v108, v0
	v_mov_b32_e32 v109, v0
	v_mov_b32_e32 v110, v0
	v_mov_b32_e32 v111, v0
	v_mov_b32_e32 v72, v0
	v_mov_b32_e32 v73, v0
	v_mov_b32_e32 v74, v0
	v_mov_b32_e32 v75, v0
	v_mov_b32_e32 v80, v0
	v_mov_b32_e32 v81, v0
	v_mov_b32_e32 v82, v0
	v_mov_b32_e32 v83, v0
	v_mov_b32_e32 v84, v0
	v_mov_b32_e32 v85, v0
	v_mov_b32_e32 v86, v0
	v_mov_b32_e32 v87, v0
	v_mov_b32_e32 v92, v0
	v_mov_b32_e32 v93, v0
	v_mov_b32_e32 v94, v0
	v_mov_b32_e32 v95, v0
	v_mov_b32_e32 v112, v0
	v_mov_b32_e32 v113, v0
	v_mov_b32_e32 v114, v0
	v_mov_b32_e32 v115, v0
	v_mov_b32_e32 v116, v0
	v_mov_b32_e32 v117, v0
	v_mov_b32_e32 v118, v0
	v_mov_b32_e32 v119, v0
	v_mov_b32_e32 v120, v0
	v_mov_b32_e32 v121, v0
	v_mov_b32_e32 v122, v0
	v_mov_b32_e32 v123, v0
	v_mov_b32_e32 v124, v0
	v_mov_b32_e32 v125, v0
	v_mov_b32_e32 v126, v0
	v_mov_b32_e32 v127, v0
	s_mov_b64 s[18:19], 0x106000
	s_mov_b64 s[20:21], 0x108000
	s_mov_b64 s[22:23], 0x10a000
	s_mov_b64 s[24:25], 0x10c000
	v_readlane_b32 s65, v252, 5
	v_readlane_b32 s66, v252, 6
	v_readlane_b32 s67, v252, 7
	v_readlane_b32 s68, v252, 8
	v_readlane_b32 s69, v252, 9
	v_readlane_b32 s70, v252, 10
	v_readlane_b32 s71, v252, 11
	v_readlane_b32 s72, v252, 12
	v_readlane_b32 s73, v252, 13
	v_readlane_b32 s74, v252, 14
	v_readlane_b32 s75, v252, 15
	v_readlane_b32 s76, v252, 16
	v_readlane_b32 s77, v252, 17
	s_waitcnt vmcnt(8)
	s_barrier
	v_add_u32_e32 v162, 0x10000, v167
	v_or_b32_e32 v163, 0x10000, v169
	v_add_u32_e32 v176, 0x18000, v167
	v_or_b32_e32 v179, 0x18000, v169
	ds_read_b128 v[216:219], v167
	ds_read_b128 v[220:223], v167 offset:1024
	ds_read_b128 v[224:227], v167 offset:2048
	ds_read_b128 v[228:231], v167 offset:3072
	ds_read_b128 v[232:235], v168 offset:16384
	ds_read_b128 v[236:239], v168 offset:17408
	ds_read_b128 v[240:243], v168 offset:18432
	ds_read_b128 v[244:247], v168 offset:19456
; #define BIG_SYNC(N)                                              \
;   asm volatile("s_waitcnt vmcnt(%0)" ::"n"(N) : "memory");       \
;   __builtin_amdgcn_s_barrier();                                  \
;   asm volatile("" ::: "memory");                                 \
;   __builtin_amdgcn_sched_barrier(0);
; template <int NK, bool BNT = false> ...
;     ...
;   auto kstep = [&](int T, int cur, int nxt, bool do_stage) {
;     const unsigned char* sa = smem + cur * BIG_STAGE;
;     bf16x8 af[4], bfr[4];
; #pragma unroll
;     for (int m = 0; m < 4; ++m) af[m] = *reinterpret_cast<const bf16x8*>(sa + aoff + m * 1024);
; #pragma unroll
;     for (int n = 0; n < 4; ++n) bfr[n] = *reinterpret_cast<const bf16x8*>(sa + boff + n * 1024);
;     __builtin_amdgcn_sched_barrier(0);
;     if (do_stage) stage(T + 3, nxt);
; #pragma unroll
;     for (int m = 0; m < 4; ++m)
; #pragma unroll
;       for (int n = 0; n < 4; ++n) acc[m][n] = __builtin_amdgcn_mfma_f32_16x16x32_bf16(af[m], bfr[n], acc[m][n], 0, 0, 0);
;     if (do_stage) {
; #pragma unroll
;       for (int q = 0; q < NG; ++q) {
;         __builtin_amdgcn_sched_group_barrier(0x008, 3, 0);
;         __builtin_amdgcn_sched_group_barrier(0x010, 1, 0);
;       }
;       __builtin_amdgcn_sched_group_barrier(0x008, 16 - 3 * NG, 0);
;     }
;     __builtin_amdgcn_sched_barrier(0);
; #pragma unroll
;     for (int n = 0; n < 4; ++n) bfr[n] = *reinterpret_cast<const bf16x8*>(sa + boff + (4 + n) * 1024);
; #pragma unroll
;     for (int m = 0; m < 4; ++m)
; #pragma unroll
;       for (int n = 0; n < 4; ++n)
;         acc[m][4 + n] = __builtin_amdgcn_mfma_f32_16x16x32_bf16(af[m], bfr[n], acc[m][4 + n], 0, 0, 0);
;     __builtin_amdgcn_sched_barrier(0);
;     ...
;   for (int it = 0; it < NK / 4 - 1; ++it) {
;     const int t = it * 4;
;     BIG_SYNC(2 * NG); kstep(t, 0, 3, true);
;     BIG_SYNC(2 * NG); kstep(t + 1, 1, 0, true);
;     BIG_SYNC(2 * NG); kstep(t + 2, 2, 1, true);
;     BIG_SYNC(2 * NG); kstep(t + 3, 3, 2, true);
.LBB0_264:
	s_waitcnt vmcnt(4)
	s_barrier
	v_add_u32_e32 v158, 0x18000, v166
	v_lshl_add_u64 v[144:145], v[138:139], 0, s[36:37]
	v_readfirstlane_b32 s13, v158
	v_add_u32_e32 v159, 0x1a000, v166
	v_lshl_add_u64 v[160:161], v[144:145], 0, s[60:61]
	s_mov_b32 m0, s13
	v_readfirstlane_b32 s13, v159
	s_waitcnt lgkmcnt(3)
	v_mfma_f32_16x16x32_bf16 v[124:127], v[216:219], v[232:235], v[124:127]
	v_lshl_add_u64 v[142:143], v[140:141], 0, s[36:37]
	v_lshl_add_u64 v[182:183], v[142:143], 0, s[60:61]
	v_mfma_f32_16x16x32_bf16 v[108:111], v[220:223], v[232:235], v[108:111]
	v_mfma_f32_16x16x32_bf16 v[88:91], v[224:227], v[232:235], v[88:91]
	global_load_lds_dwordx4 v[160:161], off
	v_lshl_add_u64 v[160:161], v[144:145], 0, s[18:19]
	s_mov_b32 m0, s13
	v_mfma_f32_16x16x32_bf16 v[44:47], v[228:231], v[232:235], v[44:47]
	s_waitcnt lgkmcnt(2)
	v_mfma_f32_16x16x32_bf16 v[120:123], v[216:219], v[236:239], v[120:123]
	ds_read_b128 v[232:235], v168 offset:20480
	v_mfma_f32_16x16x32_bf16 v[104:107], v[220:223], v[236:239], v[104:107]
	global_load_lds_dwordx4 v[160:161], off
	v_add_u32_e32 v160, 0x1c000, v166
	v_add_u32_e32 v161, 0x1e000, v166
	v_readfirstlane_b32 s13, v160
	s_mov_b32 m0, s13
	v_readfirstlane_b32 s13, v161
	v_mfma_f32_16x16x32_bf16 v[76:79], v[224:227], v[236:239], v[76:79]
	v_mfma_f32_16x16x32_bf16 v[40:43], v[228:231], v[236:239], v[40:43]
	s_waitcnt lgkmcnt(2)
	v_mfma_f32_16x16x32_bf16 v[116:119], v[216:219], v[240:243], v[116:119]
	ds_read_b128 v[236:239], v168 offset:21504
	global_load_lds_dwordx4 v[182:183], off nt
	v_lshl_add_u64 v[182:183], v[142:143], 0, s[18:19]
	s_mov_b32 m0, s13
	v_mfma_f32_16x16x32_bf16 v[100:103], v[220:223], v[240:243], v[100:103]
	v_mfma_f32_16x16x32_bf16 v[68:71], v[224:227], v[240:243], v[68:71]
	v_mfma_f32_16x16x32_bf16 v[36:39], v[228:231], v[240:243], v[36:39]
	global_load_lds_dwordx4 v[182:183], off nt
	s_waitcnt lgkmcnt(2)
	v_mfma_f32_16x16x32_bf16 v[112:115], v[216:219], v[244:247], v[112:115]
	ds_read_b128 v[240:243], v168 offset:22528
	v_mfma_f32_16x16x32_bf16 v[96:99], v[220:223], v[244:247], v[96:99]
	v_mfma_f32_16x16x32_bf16 v[64:67], v[224:227], v[244:247], v[64:67]
	v_mfma_f32_16x16x32_bf16 v[32:35], v[228:231], v[244:247], v[32:35]
	s_waitcnt lgkmcnt(2)
	v_mfma_f32_16x16x32_bf16 v[92:95], v[216:219], v[232:235], v[92:95]
	ds_read_b128 v[244:247], v168 offset:23552
	v_mfma_f32_16x16x32_bf16 v[60:63], v[220:223], v[232:235], v[60:63]
	ds_read_b128 v[186:189], v167 offset:32768
	v_mfma_f32_16x16x32_bf16 v[28:31], v[224:227], v[232:235], v[28:31]
	ds_read_b128 v[190:193], v167 offset:33792
	v_mfma_f32_16x16x32_bf16 v[12:15], v[228:231], v[232:235], v[12:15]
	ds_read_b128 v[194:197], v167 offset:34816
	s_waitcnt lgkmcnt(5)
	v_mfma_f32_16x16x32_bf16 v[84:87], v[216:219], v[236:239], v[84:87]
	ds_read_b128 v[202:205], v167 offset:35840
	ds_read_b128 v[232:235], v168 offset:49152
	v_mfma_f32_16x16x32_bf16 v[56:59], v[220:223], v[236:239], v[56:59]
	v_mfma_f32_16x16x32_bf16 v[24:27], v[224:227], v[236:239], v[24:27]
	v_mfma_f32_16x16x32_bf16 v[8:11], v[228:231], v[236:239], v[8:11]
	s_waitcnt lgkmcnt(6)
	v_mfma_f32_16x16x32_bf16 v[80:83], v[216:219], v[240:243], v[80:83]
	ds_read_b128 v[236:239], v168 offset:50176
	v_mfma_f32_16x16x32_bf16 v[52:55], v[220:223], v[240:243], v[52:55]
	v_mfma_f32_16x16x32_bf16 v[20:23], v[224:227], v[240:243], v[20:23]
	v_mfma_f32_16x16x32_bf16 v[4:7], v[228:231], v[240:243], v[4:7]
	s_waitcnt lgkmcnt(6)
	v_mfma_f32_16x16x32_bf16 v[72:75], v[216:219], v[244:247], v[72:75]
	ds_read_b128 v[240:243], v168 offset:51200
	v_mfma_f32_16x16x32_bf16 v[48:51], v[220:223], v[244:247], v[48:51]
	v_mfma_f32_16x16x32_bf16 v[16:19], v[224:227], v[244:247], v[16:19]
	v_mfma_f32_16x16x32_bf16 v[0:3], v[228:231], v[244:247], v[0:3]
	ds_read_b128 v[244:247], v168 offset:52224
	s_waitcnt vmcnt(4)
	s_barrier
	v_readfirstlane_b32 s13, v166
	v_lshl_add_u64 v[182:183], v[144:145], 0, s[62:63]
	s_mov_b32 m0, s13
	v_readfirstlane_b32 s13, v146
	s_waitcnt lgkmcnt(3)
	v_mfma_f32_16x16x32_bf16 v[124:127], v[186:189], v[232:235], v[124:127]
	v_lshl_add_u64 v[198:199], v[142:143], 0, s[62:63]
	v_mfma_f32_16x16x32_bf16 v[108:111], v[190:193], v[232:235], v[108:111]
	v_mfma_f32_16x16x32_bf16 v[88:91], v[194:197], v[232:235], v[88:91]
	global_load_lds_dwordx4 v[182:183], off
	v_lshl_add_u64 v[182:183], v[144:145], 0, s[20:21]
	s_mov_b32 m0, s13
	v_readfirstlane_b32 s13, v147
	v_mfma_f32_16x16x32_bf16 v[44:47], v[202:205], v[232:235], v[44:47]
	s_waitcnt lgkmcnt(2)
	v_mfma_f32_16x16x32_bf16 v[120:123], v[186:189], v[236:239], v[120:123]
	ds_read_b128 v[232:235], v168 offset:53248
	v_mfma_f32_16x16x32_bf16 v[104:107], v[190:193], v[236:239], v[104:107]
	global_load_lds_dwordx4 v[182:183], off
	s_mov_b32 m0, s13
	v_readfirstlane_b32 s13, v148
	v_lshl_add_u64 v[182:183], v[142:143], 0, s[20:21]
	v_mfma_f32_16x16x32_bf16 v[76:79], v[194:197], v[236:239], v[76:79]
	v_mfma_f32_16x16x32_bf16 v[40:43], v[202:205], v[236:239], v[40:43]
	s_waitcnt lgkmcnt(2)
	v_mfma_f32_16x16x32_bf16 v[116:119], v[186:189], v[240:243], v[116:119]
	ds_read_b128 v[236:239], v168 offset:54272
	global_load_lds_dwordx4 v[198:199], off nt
	s_mov_b32 m0, s13
	v_mfma_f32_16x16x32_bf16 v[100:103], v[190:193], v[240:243], v[100:103]
	v_mfma_f32_16x16x32_bf16 v[68:71], v[194:197], v[240:243], v[68:71]
	v_mfma_f32_16x16x32_bf16 v[36:39], v[202:205], v[240:243], v[36:39]
	global_load_lds_dwordx4 v[182:183], off nt
	s_waitcnt lgkmcnt(2)
	v_mfma_f32_16x16x32_bf16 v[112:115], v[186:189], v[244:247], v[112:115]
	ds_read_b128 v[240:243], v168 offset:55296
	v_mfma_f32_16x16x32_bf16 v[96:99], v[190:193], v[244:247], v[96:99]
	v_mfma_f32_16x16x32_bf16 v[64:67], v[194:197], v[244:247], v[64:67]
	v_mfma_f32_16x16x32_bf16 v[32:35], v[202:205], v[244:247], v[32:35]
	v_add_u32_e32 v162, 0x10000, v167
	v_or_b32_e32 v163, 0x10000, v169
	s_waitcnt lgkmcnt(2)
; #define BIG_SYNC(N)                                              \
;   asm volatile("s_waitcnt vmcnt(%0)" ::"n"(N) : "memory");       \
;   __builtin_amdgcn_s_barrier();                                  \
;   asm volatile("" ::: "memory");                                 \
;   __builtin_amdgcn_sched_barrier(0);
; template <int NK, bool BNT = false> ...
;     ...
;   auto kstep = [&](int T, int cur, int nxt, bool do_stage) {
;     const unsigned char* sa = smem + cur * BIG_STAGE;
;     bf16x8 af[4], bfr[4];
; #pragma unroll
;     for (int m = 0; m < 4; ++m) af[m] = *reinterpret_cast<const bf16x8*>(sa + aoff + m * 1024);
; #pragma unroll
;     for (int n = 0; n < 4; ++n) bfr[n] = *reinterpret_cast<const bf16x8*>(sa + boff + n * 1024);
;     __builtin_amdgcn_sched_barrier(0);
;     if (do_stage) stage(T + 3, nxt);
; #pragma unroll
;     for (int m = 0; m < 4; ++m)
; #pragma unroll
;       for (int n = 0; n < 4; ++n) acc[m][n] = __builtin_amdgcn_mfma_f32_16x16x32_bf16(af[m], bfr[n], acc[m][n], 0, 0, 0);
;     if (do_stage) {
; #pragma unroll
;       for (int q = 0; q < NG; ++q) {
;         __builtin_amdgcn_sched_group_barrier(0x008, 3, 0);
;         __builtin_amdgcn_sched_group_barrier(0x010, 1, 0);
;       }
;       __builtin_amdgcn_sched_group_barrier(0x008, 16 - 3 * NG, 0);
;     }
;     __builtin_amdgcn_sched_barrier(0);
; #pragma unroll
;     for (int n = 0; n < 4; ++n) bfr[n] = *reinterpret_cast<const bf16x8*>(sa + boff + (4 + n) * 1024);
; #pragma unroll
;     for (int m = 0; m < 4; ++m)
; #pragma unroll
;       for (int n = 0; n < 4; ++n)
;         acc[m][4 + n] = __builtin_amdgcn_mfma_f32_16x16x32_bf16(af[m], bfr[n], acc[m][4 + n], 0, 0, 0);
;     __builtin_amdgcn_sched_barrier(0);
;     ...
;   for (int it = 0; it < NK / 4 - 1; ++it) {
;     const int t = it * 4;
;     BIG_SYNC(2 * NG); kstep(t, 0, 3, true);
;     BIG_SYNC(2 * NG); kstep(t + 1, 1, 0, true);
;     BIG_SYNC(2 * NG); kstep(t + 2, 2, 1, true);
;     BIG_SYNC(2 * NG); kstep(t + 3, 3, 2, true);
	v_mfma_f32_16x16x32_bf16 v[92:95], v[186:189], v[232:235], v[92:95]
	ds_read_b128 v[244:247], v168 offset:56320
	v_mfma_f32_16x16x32_bf16 v[60:63], v[190:193], v[232:235], v[60:63]
	ds_read_b128 v[216:219], v162
	v_mfma_f32_16x16x32_bf16 v[28:31], v[194:197], v[232:235], v[28:31]
	ds_read_b128 v[220:223], v162 offset:1024
	v_mfma_f32_16x16x32_bf16 v[12:15], v[202:205], v[232:235], v[12:15]
	ds_read_b128 v[224:227], v162 offset:2048
	s_waitcnt lgkmcnt(5)
	v_mfma_f32_16x16x32_bf16 v[84:87], v[186:189], v[236:239], v[84:87]
	ds_read_b128 v[228:231], v162 offset:3072
	ds_read_b128 v[232:235], v163
	v_mfma_f32_16x16x32_bf16 v[56:59], v[190:193], v[236:239], v[56:59]
	v_mfma_f32_16x16x32_bf16 v[24:27], v[194:197], v[236:239], v[24:27]
	v_mfma_f32_16x16x32_bf16 v[8:11], v[202:205], v[236:239], v[8:11]
	s_waitcnt lgkmcnt(6)
	v_mfma_f32_16x16x32_bf16 v[80:83], v[186:189], v[240:243], v[80:83]
	ds_read_b128 v[236:239], v163 offset:1024
	v_mfma_f32_16x16x32_bf16 v[52:55], v[190:193], v[240:243], v[52:55]
	v_mfma_f32_16x16x32_bf16 v[20:23], v[194:197], v[240:243], v[20:23]
	v_mfma_f32_16x16x32_bf16 v[4:7], v[202:205], v[240:243], v[4:7]
	s_waitcnt lgkmcnt(6)
	v_mfma_f32_16x16x32_bf16 v[72:75], v[186:189], v[244:247], v[72:75]
	ds_read_b128 v[240:243], v163 offset:2048
	v_mfma_f32_16x16x32_bf16 v[48:51], v[190:193], v[244:247], v[48:51]
	v_mfma_f32_16x16x32_bf16 v[16:19], v[194:197], v[244:247], v[16:19]
	v_mfma_f32_16x16x32_bf16 v[0:3], v[202:205], v[244:247], v[0:3]
	ds_read_b128 v[244:247], v163 offset:3072
	s_waitcnt vmcnt(4)
	s_barrier
	v_add_u32_e32 v162, 0x10000, v167
	v_or_b32_e32 v163, 0x10000, v169
	v_add_u32_e32 v164, 0x10400, v169
	v_add_u32_e32 v165, 0x10800, v169
	v_add_u32_e32 v172, 0x10c00, v169
	v_readfirstlane_b32 s13, v149
	v_lshl_add_u64 v[174:175], v[144:145], 0, s[2:3]
	s_mov_b32 m0, s13
	v_readfirstlane_b32 s13, v150
	s_waitcnt lgkmcnt(3)
	v_mfma_f32_16x16x32_bf16 v[124:127], v[216:219], v[232:235], v[124:127]
	v_lshl_add_u64 v[178:179], v[142:143], 0, s[2:3]
	v_mfma_f32_16x16x32_bf16 v[108:111], v[220:223], v[232:235], v[108:111]
	v_mfma_f32_16x16x32_bf16 v[88:91], v[224:227], v[232:235], v[88:91]
	global_load_lds_dwordx4 v[174:175], off
	v_lshl_add_u64 v[174:175], v[144:145], 0, s[22:23]
	s_mov_b32 m0, s13
	v_readfirstlane_b32 s13, v151
	v_mfma_f32_16x16x32_bf16 v[44:47], v[228:231], v[232:235], v[44:47]
	s_waitcnt lgkmcnt(2)
	v_mfma_f32_16x16x32_bf16 v[120:123], v[216:219], v[236:239], v[120:123]
	ds_read_b128 v[232:235], v163 offset:4096
	v_mfma_f32_16x16x32_bf16 v[104:107], v[220:223], v[236:239], v[104:107]
	global_load_lds_dwordx4 v[174:175], off
	s_mov_b32 m0, s13
	v_readfirstlane_b32 s13, v152
	v_lshl_add_u64 v[174:175], v[142:143], 0, s[22:23]
	v_mfma_f32_16x16x32_bf16 v[76:79], v[224:227], v[236:239], v[76:79]
	v_mfma_f32_16x16x32_bf16 v[40:43], v[228:231], v[236:239], v[40:43]
	s_waitcnt lgkmcnt(2)
	v_mfma_f32_16x16x32_bf16 v[116:119], v[216:219], v[240:243], v[116:119]
	ds_read_b128 v[236:239], v163 offset:5120
	global_load_lds_dwordx4 v[178:179], off nt
	s_mov_b32 m0, s13
	v_mfma_f32_16x16x32_bf16 v[100:103], v[220:223], v[240:243], v[100:103]
	v_mfma_f32_16x16x32_bf16 v[68:71], v[224:227], v[240:243], v[68:71]
	v_mfma_f32_16x16x32_bf16 v[36:39], v[228:231], v[240:243], v[36:39]
	global_load_lds_dwordx4 v[174:175], off nt
	s_waitcnt lgkmcnt(2)
	v_mfma_f32_16x16x32_bf16 v[112:115], v[216:219], v[244:247], v[112:115]
	ds_read_b128 v[240:243], v163 offset:6144
	v_mfma_f32_16x16x32_bf16 v[96:99], v[220:223], v[244:247], v[96:99]
	v_mfma_f32_16x16x32_bf16 v[64:67], v[224:227], v[244:247], v[64:67]
	v_mfma_f32_16x16x32_bf16 v[32:35], v[228:231], v[244:247], v[32:35]
	v_add_u32_e32 v173, 0x11000, v169
	v_add_u32_e32 v174, 0x11400, v169
	v_add_u32_e32 v175, 0x11800, v169
	v_add_u32_e32 v178, 0x11c00, v169
	v_add_u32_e32 v162, 0x10000, v167
	v_or_b32_e32 v163, 0x10000, v169
	s_waitcnt lgkmcnt(2)
	v_mfma_f32_16x16x32_bf16 v[92:95], v[216:219], v[232:235], v[92:95]
	ds_read_b128 v[244:247], v163 offset:7168
	v_mfma_f32_16x16x32_bf16 v[60:63], v[220:223], v[232:235], v[60:63]
	ds_read_b128 v[186:189], v162 offset:32768
	v_mfma_f32_16x16x32_bf16 v[28:31], v[224:227], v[232:235], v[28:31]
	ds_read_b128 v[190:193], v162 offset:33792
	v_mfma_f32_16x16x32_bf16 v[12:15], v[228:231], v[232:235], v[12:15]
	ds_read_b128 v[194:197], v162 offset:34816
	s_waitcnt lgkmcnt(5)
	v_mfma_f32_16x16x32_bf16 v[84:87], v[216:219], v[236:239], v[84:87]
	ds_read_b128 v[202:205], v162 offset:35840
	ds_read_b128 v[232:235], v163 offset:32768
	v_mfma_f32_16x16x32_bf16 v[56:59], v[220:223], v[236:239], v[56:59]
	v_mfma_f32_16x16x32_bf16 v[24:27], v[224:227], v[236:239], v[24:27]
	v_mfma_f32_16x16x32_bf16 v[8:11], v[228:231], v[236:239], v[8:11]
	s_waitcnt lgkmcnt(6)
	v_mfma_f32_16x16x32_bf16 v[80:83], v[216:219], v[240:243], v[80:83]
	ds_read_b128 v[236:239], v163 offset:33792
	v_mfma_f32_16x16x32_bf16 v[52:55], v[220:223], v[240:243], v[52:55]
	v_mfma_f32_16x16x32_bf16 v[20:23], v[224:227], v[240:243], v[20:23]
	v_mfma_f32_16x16x32_bf16 v[4:7], v[228:231], v[240:243], v[4:7]
	s_waitcnt lgkmcnt(6)
	v_mfma_f32_16x16x32_bf16 v[72:75], v[216:219], v[244:247], v[72:75]
	ds_read_b128 v[240:243], v163 offset:34816
	v_mfma_f32_16x16x32_bf16 v[48:51], v[220:223], v[244:247], v[48:51]
	v_mfma_f32_16x16x32_bf16 v[16:19], v[224:227], v[244:247], v[16:19]
	v_mfma_f32_16x16x32_bf16 v[0:3], v[228:231], v[244:247], v[0:3]
	ds_read_b128 v[244:247], v163 offset:35840
	s_waitcnt vmcnt(4)
	s_barrier
; #define BIG_SYNC(N)                                              \
;   asm volatile("s_waitcnt vmcnt(%0)" ::"n"(N) : "memory");       \
;   __builtin_amdgcn_s_barrier();                                  \
;   asm volatile("" ::: "memory");                                 \
;   __builtin_amdgcn_sched_barrier(0);
; template <int NK, bool BNT = false> ...
;     ...
;   auto kstep = [&](int T, int cur, int nxt, bool do_stage) {
;     const unsigned char* sa = smem + cur * BIG_STAGE;
;     bf16x8 af[4], bfr[4];
; #pragma unroll
;     for (int m = 0; m < 4; ++m) af[m] = *reinterpret_cast<const bf16x8*>(sa + aoff + m * 1024);
; #pragma unroll
;     for (int n = 0; n < 4; ++n) bfr[n] = *reinterpret_cast<const bf16x8*>(sa + boff + n * 1024);
;     __builtin_amdgcn_sched_barrier(0);
;     if (do_stage) stage(T + 3, nxt);
; #pragma unroll
;     for (int m = 0; m < 4; ++m)
; #pragma unroll
;       for (int n = 0; n < 4; ++n) acc[m][n] = __builtin_amdgcn_mfma_f32_16x16x32_bf16(af[m], bfr[n], acc[m][n], 0, 0, 0);
;     if (do_stage) {
; #pragma unroll
;       for (int q = 0; q < NG; ++q) {
;         __builtin_amdgcn_sched_group_barrier(0x008, 3, 0);
;         __builtin_amdgcn_sched_group_barrier(0x010, 1, 0);
;       }
;       __builtin_amdgcn_sched_group_barrier(0x008, 16 - 3 * NG, 0);
;     }
;     __builtin_amdgcn_sched_barrier(0);
; #pragma unroll
;     for (int n = 0; n < 4; ++n) bfr[n] = *reinterpret_cast<const bf16x8*>(sa + boff + (4 + n) * 1024);
; #pragma unroll
;     for (int m = 0; m < 4; ++m)
; #pragma unroll
;       for (int n = 0; n < 4; ++n)
;         acc[m][4 + n] = __builtin_amdgcn_mfma_f32_16x16x32_bf16(af[m], bfr[n], acc[m][4 + n], 0, 0, 0);
;     __builtin_amdgcn_sched_barrier(0);
;     ...
;   for (int it = 0; it < NK / 4 - 1; ++it) {
;     const int t = it * 4;
;     BIG_SYNC(2 * NG); kstep(t, 0, 3, true);
;     BIG_SYNC(2 * NG); kstep(t + 1, 1, 0, true);
;     BIG_SYNC(2 * NG); kstep(t + 2, 2, 1, true);
;     BIG_SYNC(2 * NG); kstep(t + 3, 3, 2, true);
;   }
;   BIG_SYNC(2 * NG); kstep(NK - 4, 0, 3, true);
	v_add_u32_e32 v176, 0x18000, v167
	v_or_b32_e32 v179, 0x18000, v169
	v_add_u32_e32 v180, 0x18400, v169
	v_add_u32_e32 v181, 0x18800, v169
	v_add_u32_e32 v182, 0x18c00, v169
	v_readfirstlane_b32 s13, v154
	v_lshl_add_u64 v[248:249], v[144:145], 0, s[54:55]
	s_mov_b32 m0, s13
	v_readfirstlane_b32 s13, v155
	v_lshl_add_u64 v[144:145], v[144:145], 0, s[24:25]
	s_waitcnt lgkmcnt(3)
	v_mfma_f32_16x16x32_bf16 v[124:127], v[186:189], v[232:235], v[124:127]
	v_lshl_add_u64 v[250:251], v[142:143], 0, s[54:55]
	v_lshl_add_u64 v[142:143], v[142:143], 0, s[24:25]
	v_mfma_f32_16x16x32_bf16 v[108:111], v[190:193], v[232:235], v[108:111]
	v_mfma_f32_16x16x32_bf16 v[88:91], v[194:197], v[232:235], v[88:91]
	global_load_lds_dwordx4 v[248:249], off
	s_mov_b32 m0, s13
	v_readfirstlane_b32 s13, v156
	v_mfma_f32_16x16x32_bf16 v[44:47], v[202:205], v[232:235], v[44:47]
	s_waitcnt lgkmcnt(2)
	v_mfma_f32_16x16x32_bf16 v[120:123], v[186:189], v[236:239], v[120:123]
	ds_read_b128 v[232:235], v163 offset:36864
	v_mfma_f32_16x16x32_bf16 v[104:107], v[190:193], v[236:239], v[104:107]
	global_load_lds_dwordx4 v[144:145], off
	s_mov_b32 m0, s13
	v_readfirstlane_b32 s13, v157
	v_mfma_f32_16x16x32_bf16 v[76:79], v[194:197], v[236:239], v[76:79]
	v_mfma_f32_16x16x32_bf16 v[40:43], v[202:205], v[236:239], v[40:43]
	s_waitcnt lgkmcnt(2)
	v_mfma_f32_16x16x32_bf16 v[116:119], v[186:189], v[240:243], v[116:119]
	ds_read_b128 v[236:239], v163 offset:37888
	global_load_lds_dwordx4 v[250:251], off nt
	s_mov_b32 m0, s13
	v_mfma_f32_16x16x32_bf16 v[100:103], v[190:193], v[240:243], v[100:103]
	v_mfma_f32_16x16x32_bf16 v[68:71], v[194:197], v[240:243], v[68:71]
	v_mfma_f32_16x16x32_bf16 v[36:39], v[202:205], v[240:243], v[36:39]
	global_load_lds_dwordx4 v[142:143], off nt
	s_waitcnt lgkmcnt(2)
	v_mfma_f32_16x16x32_bf16 v[112:115], v[186:189], v[244:247], v[112:115]
	ds_read_b128 v[240:243], v163 offset:38912
	v_mfma_f32_16x16x32_bf16 v[96:99], v[190:193], v[244:247], v[96:99]
	v_mfma_f32_16x16x32_bf16 v[64:67], v[194:197], v[244:247], v[64:67]
	v_mfma_f32_16x16x32_bf16 v[32:35], v[202:205], v[244:247], v[32:35]
	v_add_u32_e32 v142, 0x19000, v169
	v_add_u32_e32 v143, 0x19400, v169
	v_add_u32_e32 v144, 0x19800, v169
	v_add_u32_e32 v145, 0x19c00, v169
	s_waitcnt lgkmcnt(2)
	v_mfma_f32_16x16x32_bf16 v[92:95], v[186:189], v[232:235], v[92:95]
	ds_read_b128 v[244:247], v163 offset:39936
	v_mfma_f32_16x16x32_bf16 v[60:63], v[190:193], v[232:235], v[60:63]
	ds_read_b128 v[216:219], v167
	v_mfma_f32_16x16x32_bf16 v[28:31], v[194:197], v[232:235], v[28:31]
	ds_read_b128 v[220:223], v167 offset:1024
	v_mfma_f32_16x16x32_bf16 v[12:15], v[202:205], v[232:235], v[12:15]
	ds_read_b128 v[224:227], v167 offset:2048
	s_waitcnt lgkmcnt(5)
	v_mfma_f32_16x16x32_bf16 v[84:87], v[186:189], v[236:239], v[84:87]
	ds_read_b128 v[228:231], v167 offset:3072
	ds_read_b128 v[232:235], v168 offset:16384
	v_mfma_f32_16x16x32_bf16 v[56:59], v[190:193], v[236:239], v[56:59]
	v_mfma_f32_16x16x32_bf16 v[24:27], v[194:197], v[236:239], v[24:27]
	v_mfma_f32_16x16x32_bf16 v[8:11], v[202:205], v[236:239], v[8:11]
	s_waitcnt lgkmcnt(6)
	v_mfma_f32_16x16x32_bf16 v[80:83], v[186:189], v[240:243], v[80:83]
	ds_read_b128 v[236:239], v168 offset:17408
	v_mfma_f32_16x16x32_bf16 v[52:55], v[190:193], v[240:243], v[52:55]
	v_mfma_f32_16x16x32_bf16 v[20:23], v[194:197], v[240:243], v[20:23]
	v_mfma_f32_16x16x32_bf16 v[4:7], v[202:205], v[240:243], v[4:7]
	s_waitcnt lgkmcnt(6)
	v_mfma_f32_16x16x32_bf16 v[72:75], v[186:189], v[244:247], v[72:75]
	ds_read_b128 v[240:243], v168 offset:18432
	v_mfma_f32_16x16x32_bf16 v[48:51], v[190:193], v[244:247], v[48:51]
	v_mfma_f32_16x16x32_bf16 v[16:19], v[194:197], v[244:247], v[16:19]
	v_mfma_f32_16x16x32_bf16 v[0:3], v[202:205], v[244:247], v[0:3]
	ds_read_b128 v[244:247], v168 offset:19456
	s_add_u32 s36, s36, 0x8000
	s_addc_u32 s37, s37, 0
	s_cmp_lg_u32 s36, 0xf8000
	s_cbranch_scc1 .LBB0_264
	s_waitcnt vmcnt(4)
	s_barrier
	s_sext_i32_i8 s13, s14
	s_mov_b64 s[18:19], 0xfe000
	v_readfirstlane_b32 s14, v158
	v_lshl_add_u64 v[150:151], v[130:131], 0, s[18:19]
	v_lshl_add_u64 v[198:199], v[128:129], 0, s[18:19]
	s_mov_b32 m0, s14
	s_mov_b64 s[18:19], 0x1fe000
	v_readfirstlane_b32 s14, v159
	v_lshl_add_u64 v[130:131], v[130:131], 0, s[18:19]
	s_waitcnt lgkmcnt(3)
	v_mfma_f32_16x16x32_bf16 v[124:127], v[216:219], v[232:235], v[124:127]
	v_lshl_add_u64 v[128:129], v[128:129], 0, s[18:19]
	v_mfma_f32_16x16x32_bf16 v[108:111], v[220:223], v[232:235], v[108:111]
	v_mfma_f32_16x16x32_bf16 v[88:91], v[224:227], v[232:235], v[88:91]
	global_load_lds_dwordx4 v[150:151], off
	s_mov_b32 m0, s14
	v_readfirstlane_b32 s14, v160
	v_mfma_f32_16x16x32_bf16 v[44:47], v[228:231], v[232:235], v[44:47]
	s_waitcnt lgkmcnt(2)
	v_mfma_f32_16x16x32_bf16 v[120:123], v[216:219], v[236:239], v[120:123]
	ds_read_b128 v[232:235], v168 offset:20480
	v_mfma_f32_16x16x32_bf16 v[104:107], v[220:223], v[236:239], v[104:107]
	global_load_lds_dwordx4 v[130:131], off
	s_mov_b32 m0, s14
	v_readfirstlane_b32 s14, v161
	v_mfma_f32_16x16x32_bf16 v[76:79], v[224:227], v[236:239], v[76:79]
	v_mfma_f32_16x16x32_bf16 v[40:43], v[228:231], v[236:239], v[40:43]
	s_waitcnt lgkmcnt(2)
	v_mfma_f32_16x16x32_bf16 v[116:119], v[216:219], v[240:243], v[116:119]
	ds_read_b128 v[236:239], v168 offset:21504
	global_load_lds_dwordx4 v[198:199], off nt
	s_mov_b32 m0, s14
	v_mfma_f32_16x16x32_bf16 v[100:103], v[220:223], v[240:243], v[100:103]
	v_mfma_f32_16x16x32_bf16 v[68:71], v[224:227], v[240:243], v[68:71]
	v_mfma_f32_16x16x32_bf16 v[36:39], v[228:231], v[240:243], v[36:39]
	global_load_lds_dwordx4 v[128:129], off nt
	s_waitcnt lgkmcnt(2)
; #define BIG_SYNC(N)                                              \
;   asm volatile("s_waitcnt vmcnt(%0)" ::"n"(N) : "memory");       \
;   __builtin_amdgcn_s_barrier();                                  \
;   asm volatile("" ::: "memory");                                 \
;   __builtin_amdgcn_sched_barrier(0);
; template <int NK, bool BNT = false> ...
;     ...
;   auto kstep = [&](int T, int cur, int nxt, bool do_stage) {
;     const unsigned char* sa = smem + cur * BIG_STAGE;
;     bf16x8 af[4], bfr[4];
; #pragma unroll
;     for (int m = 0; m < 4; ++m) af[m] = *reinterpret_cast<const bf16x8*>(sa + aoff + m * 1024);
; #pragma unroll
;     for (int n = 0; n < 4; ++n) bfr[n] = *reinterpret_cast<const bf16x8*>(sa + boff + n * 1024);
;     __builtin_amdgcn_sched_barrier(0);
;     if (do_stage) stage(T + 3, nxt);
; #pragma unroll
;     for (int m = 0; m < 4; ++m)
; #pragma unroll
;       for (int n = 0; n < 4; ++n) acc[m][n] = __builtin_amdgcn_mfma_f32_16x16x32_bf16(af[m], bfr[n], acc[m][n], 0, 0, 0);
;     if (do_stage) {
; #pragma unroll
;       for (int q = 0; q < NG; ++q) {
;         __builtin_amdgcn_sched_group_barrier(0x008, 3, 0);
;         __builtin_amdgcn_sched_group_barrier(0x010, 1, 0);
;       }
;       __builtin_amdgcn_sched_group_barrier(0x008, 16 - 3 * NG, 0);
;     }
;     __builtin_amdgcn_sched_barrier(0);
; #pragma unroll
;     for (int n = 0; n < 4; ++n) bfr[n] = *reinterpret_cast<const bf16x8*>(sa + boff + (4 + n) * 1024);
; #pragma unroll
;     for (int m = 0; m < 4; ++m)
; #pragma unroll
;       for (int n = 0; n < 4; ++n)
;         acc[m][4 + n] = __builtin_amdgcn_mfma_f32_16x16x32_bf16(af[m], bfr[n], acc[m][4 + n], 0, 0, 0);
;     __builtin_amdgcn_sched_barrier(0);
;     ...
;   BIG_SYNC(2 * NG); kstep(NK - 4, 0, 3, true);
;   BIG_SYNC(2 * NG); kstep(NK - 3, 1, 0, false);
;   BIG_SYNC(NG);     kstep(NK - 2, 2, 0, false);
	v_mfma_f32_16x16x32_bf16 v[112:115], v[216:219], v[244:247], v[112:115]
	ds_read_b128 v[240:243], v168 offset:22528
	v_mfma_f32_16x16x32_bf16 v[96:99], v[220:223], v[244:247], v[96:99]
	v_mfma_f32_16x16x32_bf16 v[64:67], v[224:227], v[244:247], v[64:67]
	v_mfma_f32_16x16x32_bf16 v[32:35], v[228:231], v[244:247], v[32:35]
	s_waitcnt lgkmcnt(2)
	v_mfma_f32_16x16x32_bf16 v[92:95], v[216:219], v[232:235], v[92:95]
	ds_read_b128 v[244:247], v168 offset:23552
	v_mfma_f32_16x16x32_bf16 v[60:63], v[220:223], v[232:235], v[60:63]
	ds_read_b128 v[186:189], v167 offset:32768
	v_mfma_f32_16x16x32_bf16 v[28:31], v[224:227], v[232:235], v[28:31]
	ds_read_b128 v[190:193], v167 offset:33792
	v_mfma_f32_16x16x32_bf16 v[12:15], v[228:231], v[232:235], v[12:15]
	ds_read_b128 v[194:197], v167 offset:34816
	s_waitcnt lgkmcnt(5)
	v_mfma_f32_16x16x32_bf16 v[84:87], v[216:219], v[236:239], v[84:87]
	ds_read_b128 v[202:205], v167 offset:35840
	ds_read_b128 v[232:235], v168 offset:49152
	v_mfma_f32_16x16x32_bf16 v[56:59], v[220:223], v[236:239], v[56:59]
	v_mfma_f32_16x16x32_bf16 v[24:27], v[224:227], v[236:239], v[24:27]
	v_mfma_f32_16x16x32_bf16 v[8:11], v[228:231], v[236:239], v[8:11]
	s_waitcnt lgkmcnt(6)
	v_mfma_f32_16x16x32_bf16 v[80:83], v[216:219], v[240:243], v[80:83]
	ds_read_b128 v[236:239], v168 offset:50176
	v_mfma_f32_16x16x32_bf16 v[52:55], v[220:223], v[240:243], v[52:55]
	v_mfma_f32_16x16x32_bf16 v[20:23], v[224:227], v[240:243], v[20:23]
	v_mfma_f32_16x16x32_bf16 v[4:7], v[228:231], v[240:243], v[4:7]
	s_waitcnt lgkmcnt(6)
	v_mfma_f32_16x16x32_bf16 v[72:75], v[216:219], v[244:247], v[72:75]
	ds_read_b128 v[240:243], v168 offset:51200
	v_mfma_f32_16x16x32_bf16 v[48:51], v[220:223], v[244:247], v[48:51]
	v_mfma_f32_16x16x32_bf16 v[16:19], v[224:227], v[244:247], v[16:19]
	v_mfma_f32_16x16x32_bf16 v[0:3], v[228:231], v[244:247], v[0:3]
	ds_read_b128 v[244:247], v168 offset:52224
	s_waitcnt vmcnt(4)
	s_barrier
	s_waitcnt lgkmcnt(3)
	v_mfma_f32_16x16x32_bf16 v[124:127], v[186:189], v[232:235], v[124:127]
	v_mfma_f32_16x16x32_bf16 v[108:111], v[190:193], v[232:235], v[108:111]
	v_mfma_f32_16x16x32_bf16 v[88:91], v[194:197], v[232:235], v[88:91]
	v_mfma_f32_16x16x32_bf16 v[44:47], v[202:205], v[232:235], v[44:47]
	s_waitcnt lgkmcnt(2)
	v_mfma_f32_16x16x32_bf16 v[120:123], v[186:189], v[236:239], v[120:123]
	ds_read_b128 v[232:235], v168 offset:53248
	v_mfma_f32_16x16x32_bf16 v[104:107], v[190:193], v[236:239], v[104:107]
	v_mfma_f32_16x16x32_bf16 v[76:79], v[194:197], v[236:239], v[76:79]
	v_mfma_f32_16x16x32_bf16 v[40:43], v[202:205], v[236:239], v[40:43]
	s_waitcnt lgkmcnt(2)
	v_mfma_f32_16x16x32_bf16 v[116:119], v[186:189], v[240:243], v[116:119]
	ds_read_b128 v[236:239], v168 offset:54272
	v_mfma_f32_16x16x32_bf16 v[100:103], v[190:193], v[240:243], v[100:103]
	v_mfma_f32_16x16x32_bf16 v[68:71], v[194:197], v[240:243], v[68:71]
	v_mfma_f32_16x16x32_bf16 v[36:39], v[202:205], v[240:243], v[36:39]
	s_waitcnt lgkmcnt(2)
	v_mfma_f32_16x16x32_bf16 v[112:115], v[186:189], v[244:247], v[112:115]
	ds_read_b128 v[240:243], v168 offset:55296
	v_mfma_f32_16x16x32_bf16 v[96:99], v[190:193], v[244:247], v[96:99]
	v_mfma_f32_16x16x32_bf16 v[64:67], v[194:197], v[244:247], v[64:67]
	v_mfma_f32_16x16x32_bf16 v[32:35], v[202:205], v[244:247], v[32:35]
	s_waitcnt lgkmcnt(2)
	v_mfma_f32_16x16x32_bf16 v[92:95], v[186:189], v[232:235], v[92:95]
	ds_read_b128 v[244:247], v168 offset:56320
	v_mfma_f32_16x16x32_bf16 v[60:63], v[190:193], v[232:235], v[60:63]
	v_mfma_f32_16x16x32_bf16 v[28:31], v[194:197], v[232:235], v[28:31]
	v_mfma_f32_16x16x32_bf16 v[12:15], v[202:205], v[232:235], v[12:15]
	s_waitcnt lgkmcnt(2)
	v_mfma_f32_16x16x32_bf16 v[84:87], v[186:189], v[236:239], v[84:87]
	v_mfma_f32_16x16x32_bf16 v[56:59], v[190:193], v[236:239], v[56:59]
	v_mfma_f32_16x16x32_bf16 v[24:27], v[194:197], v[236:239], v[24:27]
	v_mfma_f32_16x16x32_bf16 v[8:11], v[202:205], v[236:239], v[8:11]
	s_waitcnt lgkmcnt(1)
	v_mfma_f32_16x16x32_bf16 v[80:83], v[186:189], v[240:243], v[80:83]
	v_mfma_f32_16x16x32_bf16 v[52:55], v[190:193], v[240:243], v[52:55]
	v_mfma_f32_16x16x32_bf16 v[20:23], v[194:197], v[240:243], v[20:23]
	v_mfma_f32_16x16x32_bf16 v[4:7], v[202:205], v[240:243], v[4:7]
	s_waitcnt lgkmcnt(0)
	v_mfma_f32_16x16x32_bf16 v[72:75], v[186:189], v[244:247], v[72:75]
	v_mfma_f32_16x16x32_bf16 v[48:51], v[190:193], v[244:247], v[48:51]
	v_mfma_f32_16x16x32_bf16 v[16:19], v[194:197], v[244:247], v[16:19]
	v_mfma_f32_16x16x32_bf16 v[0:3], v[202:205], v[244:247], v[0:3]
	v_mov_b32_e32 v186, 0xf149f2ca
	v_mov_b32_e32 v187, 0x3c0881c4
	v_mov_b32_e32 v188, 0xbab64f3b
	v_mov_b32_e32 v189, 0x24800
	v_mov_b32_e32 v190, 1
	v_mov_b32_e32 v191, 0x24804
	v_mov_b32_e32 v192, 0xfcf
	v_mov_b32_e32 v193, 0x7cf
	v_mov_b32_e32 v194, 0xfdf
	v_mov_b32_e32 v195, 0x7df
	v_mov_b32_e32 v196, 0xfef
	v_mov_b32_e32 v197, 0x7ef
	v_mov_b32_e32 v198, 0xfff
	v_mov_b32_e32 v199, 0x7ff
	v_mov_b32_e32 v200, 0x20000
	v_mov_b32_e32 v201, 0xf8f
	v_mov_b32_e32 v202, 0x78f
	v_mov_b32_e32 v203, 0xf9f
	v_mov_b32_e32 v204, 0x79f
	v_mov_b32_e32 v205, 0xfaf
	s_waitcnt vmcnt(4)
	s_barrier
; #define BIG_SYNC(N)                                              \
;   asm volatile("s_waitcnt vmcnt(%0)" ::"n"(N) : "memory");       \
;   __builtin_amdgcn_s_barrier();                                  \
;   asm volatile("" ::: "memory");                                 \
;   __builtin_amdgcn_sched_barrier(0);
; template <int NK, bool BNT = false> ...
;     ...
;   auto kstep = [&](int T, int cur, int nxt, bool do_stage) {
;     const unsigned char* sa = smem + cur * BIG_STAGE;
;     bf16x8 af[4], bfr[4];
; #pragma unroll
;     for (int m = 0; m < 4; ++m) af[m] = *reinterpret_cast<const bf16x8*>(sa + aoff + m * 1024);
; #pragma unroll
;     for (int n = 0; n < 4; ++n) bfr[n] = *reinterpret_cast<const bf16x8*>(sa + boff + n * 1024);
;     __builtin_amdgcn_sched_barrier(0);
;     if (do_stage) stage(T + 3, nxt);
; #pragma unroll
;     for (int m = 0; m < 4; ++m)
; #pragma unroll
;       for (int n = 0; n < 4; ++n) acc[m][n] = __builtin_amdgcn_mfma_f32_16x16x32_bf16(af[m], bfr[n], acc[m][n], 0, 0, 0);
;     if (do_stage) {
; #pragma unroll
;       for (int q = 0; q < NG; ++q) {
;         __builtin_amdgcn_sched_group_barrier(0x008, 3, 0);
;         __builtin_amdgcn_sched_group_barrier(0x010, 1, 0);
;       }
;       __builtin_amdgcn_sched_group_barrier(0x008, 16 - 3 * NG, 0);
;     }
;     __builtin_amdgcn_sched_barrier(0);
; #pragma unroll
;     for (int n = 0; n < 4; ++n) bfr[n] = *reinterpret_cast<const bf16x8*>(sa + boff + (4 + n) * 1024);
; #pragma unroll
;     for (int m = 0; m < 4; ++m)
; #pragma unroll
;       for (int n = 0; n < 4; ++n)
;         acc[m][4 + n] = __builtin_amdgcn_mfma_f32_16x16x32_bf16(af[m], bfr[n], acc[m][4 + n], 0, 0, 0);
;     __builtin_amdgcn_sched_barrier(0);
;     ...
;   BIG_SYNC(NG);     kstep(NK - 2, 2, 0, false);
;   BIG_SYNC(0);      kstep(NK - 1, 3, 0, false);
	ds_read_b128 v[128:131], v162
	ds_read_b128 v[138:141], v162 offset:1024
	ds_read_b128 v[146:149], v162 offset:2048
	ds_read_b128 v[154:157], v162 offset:3072
	ds_read_b128 v[158:161], v163
	ds_read_b128 v[216:219], v164
	ds_read_b128 v[162:165], v165
	ds_read_b128 v[220:223], v172
	s_waitcnt lgkmcnt(0)
	v_mfma_f32_16x16x32_bf16 v[124:127], v[128:131], v[158:161], v[124:127]
	v_mfma_f32_16x16x32_bf16 v[116:119], v[128:131], v[162:165], v[116:119]
	v_mfma_f32_16x16x32_bf16 v[112:115], v[128:131], v[220:223], v[112:115]
	v_mfma_f32_16x16x32_bf16 v[104:107], v[138:141], v[216:219], v[104:107]
	v_mfma_f32_16x16x32_bf16 v[100:103], v[138:141], v[162:165], v[100:103]
	v_mfma_f32_16x16x32_bf16 v[96:99], v[138:141], v[220:223], v[96:99]
	v_mfma_f32_16x16x32_bf16 v[68:71], v[146:149], v[162:165], v[68:71]
	v_mfma_f32_16x16x32_bf16 v[64:67], v[146:149], v[220:223], v[64:67]
	v_mfma_f32_16x16x32_bf16 v[44:47], v[154:157], v[158:161], v[44:47]
	v_mfma_f32_16x16x32_bf16 v[40:43], v[154:157], v[216:219], v[40:43]
	v_mfma_f32_16x16x32_bf16 v[36:39], v[154:157], v[162:165], v[36:39]
	v_mfma_f32_16x16x32_bf16 v[32:35], v[154:157], v[220:223], v[32:35]
	v_mfma_f32_16x16x32_bf16 v[120:123], v[128:131], v[216:219], v[120:123]
	v_mfma_f32_16x16x32_bf16 v[224:227], v[138:141], v[158:161], v[108:111]
	v_mfma_f32_16x16x32_bf16 v[228:231], v[146:149], v[158:161], v[88:91]
	v_mfma_f32_16x16x32_bf16 v[232:235], v[146:149], v[216:219], v[76:79]
	s_nop 2
	ds_read_b128 v[76:79], v173
	ds_read_b128 v[88:91], v174
	s_waitcnt lgkmcnt(0)
	v_mfma_f32_16x16x32_bf16 v[158:161], v[128:131], v[76:79], v[92:95]
	s_nop 2
	ds_read_b128 v[92:95], v178
	v_mfma_f32_16x16x32_bf16 v[162:165], v[128:131], v[88:91], v[84:87]
	s_nop 2
	ds_read_b128 v[84:87], v175
	s_waitcnt lgkmcnt(0)
	v_mfma_f32_16x16x32_bf16 v[172:175], v[128:131], v[84:87], v[80:83]
	v_mfma_f32_16x16x32_bf16 v[128:131], v[128:131], v[92:95], v[72:75]
	v_mfma_f32_16x16x32_bf16 v[216:219], v[138:141], v[76:79], v[60:63]
	v_mfma_f32_16x16x32_bf16 v[220:223], v[138:141], v[88:91], v[56:59]
	v_mfma_f32_16x16x32_bf16 v[52:55], v[138:141], v[84:87], v[52:55]
	v_mfma_f32_16x16x32_bf16 v[48:51], v[138:141], v[92:95], v[48:51]
	v_mfma_f32_16x16x32_bf16 v[138:141], v[146:149], v[76:79], v[28:31]
	v_mfma_f32_16x16x32_bf16 v[236:239], v[146:149], v[88:91], v[24:27]
	v_mfma_f32_16x16x32_bf16 v[20:23], v[146:149], v[84:87], v[20:23]
	v_mfma_f32_16x16x32_bf16 v[16:19], v[146:149], v[92:95], v[16:19]
	v_mfma_f32_16x16x32_bf16 v[146:149], v[154:157], v[76:79], v[12:15]
	v_mfma_f32_16x16x32_bf16 v[0:3], v[154:157], v[92:95], v[0:3]
	v_mfma_f32_16x16x32_bf16 v[240:243], v[154:157], v[88:91], v[8:11]
	v_mfma_f32_16x16x32_bf16 v[244:247], v[154:157], v[84:87], v[4:7]
	s_waitcnt vmcnt(0)
	s_barrier
	s_nop 1
	ds_read_b128 v[4:7], v176
	ds_read_b128 v[8:11], v176 offset:1024
	ds_read_b128 v[154:157], v176 offset:2048
	ds_read_b128 v[12:15], v179
	ds_read_b128 v[24:27], v180
	ds_read_b128 v[28:31], v181
	ds_read_b128 v[56:59], v182
	ds_read_b128 v[248:251], v176 offset:3072
	s_waitcnt lgkmcnt(0)
	v_mfma_f32_16x16x32_bf16 v[108:111], v[4:7], v[24:27], v[120:123]
	v_mfma_f32_16x16x32_bf16 v[92:95], v[4:7], v[28:31], v[116:119]
	v_mfma_f32_16x16x32_bf16 v[76:79], v[4:7], v[56:59], v[112:115]
	v_mfma_f32_16x16x32_bf16 v[104:107], v[8:11], v[24:27], v[104:107]
	v_mfma_f32_16x16x32_bf16 v[88:91], v[8:11], v[28:31], v[100:103]
	v_mfma_f32_16x16x32_bf16 v[72:75], v[8:11], v[56:59], v[96:99]
	v_mfma_f32_16x16x32_bf16 v[100:103], v[154:157], v[24:27], v[232:235]
	v_mfma_f32_16x16x32_bf16 v[84:87], v[154:157], v[28:31], v[68:71]
	v_mfma_f32_16x16x32_bf16 v[68:71], v[154:157], v[56:59], v[64:67]
	v_mfma_f32_16x16x32_bf16 v[116:119], v[248:251], v[12:15], v[44:47]
	v_mfma_f32_16x16x32_bf16 v[96:99], v[248:251], v[24:27], v[40:43]
	v_mfma_f32_16x16x32_bf16 v[80:83], v[248:251], v[28:31], v[36:39]
	v_mfma_f32_16x16x32_bf16 v[64:67], v[248:251], v[56:59], v[32:35]
	v_mfma_f32_16x16x32_bf16 v[178:181], v[4:7], v[12:15], v[124:127]
	v_mfma_f32_16x16x32_bf16 v[224:227], v[8:11], v[12:15], v[224:227]
	v_mfma_f32_16x16x32_bf16 v[120:123], v[154:157], v[12:15], v[228:231]
	ds_read_b128 v[32:35], v142
	ds_read_b128 v[112:115], v143
	ds_read_b128 v[124:127], v144
	ds_read_b128 v[142:145], v145
	s_waitcnt lgkmcnt(0)
; __device__ __forceinline__ float bf2f(bf16_t b) { return __uint_as_float(((unsigned)b) << 16); }
; __device__ __forceinline__ int widen_off(int fq) { return ((fq & 1) << 4) + ((fq >> 1) << 3); }
; template <int MODE, int NSUB>
; __device__ __forceinline__ void epilogue(const Params& p, int layer, f32x4 (&acc)[4][NSUB], int tm, int tn, int g,
;                                          const float* s_rstd, const int tid_in) {
;     ...
;     const int fb = tm * 128 + wr * 64 + fq * 4;
;     const int tb = tn * (NSUB * 32) + wc * (NSUB * 16) + fr;
;     const int fw = tm * 128 + wr * 64 + widen_off(fq);
;     u32x4 curw[2], nxtw[2];
; #pragma unroll
;     for (int mp = 0; mp < 2; ++mp) curw[mp] = *reinterpret_cast<const u32x4*>(p.xb + blk(tb, fw + mp * 32, 32));
; #pragma unroll
;     for (int n = 0; n < NSUB; ++n) {
;       if (n + 1 < NSUB) {
; #pragma unroll
;         for (int mp = 0; mp < 2; ++mp) nxtw[mp] = *reinterpret_cast<const u32x4*>(p.xb + blk(tb + (n + 1) * 16, fw + mp * 32, 32));
;       }
;       bf16x4 cur[4];
;       unwiden_pair(curw[0], cur[0], cur[1]);
;       unwiden_pair(curw[1], cur[2], cur[3]);
;       const int t = tb + n * 16;
;       float ss = 0.f;
; #pragma unroll
;       for (int mp = 0; mp < 2; ++mp) {
;         bf16x4 pk[2];
; #pragma unroll
;         for (int h2 = 0; h2 < 2; ++h2) {
;           const int m = mp * 2 + h2;
;           const float x0 = bf2f((bf16_t)cur[m][0]) + acc[m][n][0], x1 = bf2f((bf16_t)cur[m][1]) + acc[m][n][1];
;           const float x2 = bf2f((bf16_t)cur[m][2]) + acc[m][n][2], x3 = bf2f((bf16_t)cur[m][3]) + acc[m][n][3];
;           ss += x0 * x0 + x1 * x1 + x2 * x2 + x3 * x3;
;           pk[h2] = pack4(x0, x1, x2, x3);
;         }
;         const int f = tm * 128 + wr * 64 + mp * 32 + widen_off(fq);
;         *reinterpret_cast<u32x4*>(p.xb + blk(t, f, 32)) = widen_pair(pk[0], pk[1]);
;       }
;       ss = red_fq(ss);
;       if (fq == 0) p.part[(long)t * 16 + tm * 2 + wr] = ss;
;       curw[0] = nxtw[0];
;       curw[1] = nxtw[1];
;     }
	v_mfma_f32_16x16x32_bf16 v[60:63], v[4:7], v[32:35], v[158:161]
	v_mfma_f32_16x16x32_bf16 v[44:47], v[4:7], v[112:115], v[162:165]
	v_mfma_f32_16x16x32_bf16 v[28:31], v[4:7], v[124:127], v[172:175]
	v_mfma_f32_16x16x32_bf16 v[12:15], v[4:7], v[142:145], v[128:131]
	v_mfma_f32_16x16x32_bf16 v[56:59], v[8:11], v[32:35], v[216:219]
	v_mfma_f32_16x16x32_bf16 v[40:43], v[8:11], v[112:115], v[220:223]
	v_mfma_f32_16x16x32_bf16 v[24:27], v[8:11], v[124:127], v[52:55]
	v_mfma_f32_16x16x32_bf16 v[8:11], v[8:11], v[142:145], v[48:51]
	v_mfma_f32_16x16x32_bf16 v[52:55], v[154:157], v[32:35], v[138:141]
	v_mfma_f32_16x16x32_bf16 v[36:39], v[154:157], v[112:115], v[236:239]
	v_mfma_f32_16x16x32_bf16 v[20:23], v[154:157], v[124:127], v[20:23]
	v_mfma_f32_16x16x32_bf16 v[4:7], v[154:157], v[142:145], v[16:19]
	v_mfma_f32_16x16x32_bf16 v[48:51], v[248:251], v[32:35], v[146:149]
	v_mfma_f32_16x16x32_bf16 v[32:35], v[248:251], v[112:115], v[240:243]
	v_mfma_f32_16x16x32_bf16 v[16:19], v[248:251], v[124:127], v[244:247]
	v_mfma_f32_16x16x32_bf16 v[0:3], v[248:251], v[142:145], v[0:3]
	v_lshl_add_u32 v124, s13, 1, v170
	v_mov_b32_e32 v112, v215
	v_lshlrev_b32_e32 v113, 7, v124
	v_ashrrev_i32_e32 v138, 7, v112
	s_mul_i32 s13, s15, 0x140
	v_lshl_add_u32 v114, v138, 6, v113
	v_lshlrev_b32_e32 v113, 1, v112
	s_add_i32 s12, s12, s13
	v_and_b32_e32 v113, 0x80, v113
	v_lshl_or_b32 v127, s12, 8, v113
	v_lshrrev_b32_e32 v113, 2, v112
	v_and_b32_e32 v125, 15, v112
	v_and_b32_e32 v113, 8, v113
	v_ashrrev_i32_e32 v115, 2, v127
	v_readlane_b32 s80, v253, 25
	v_ashrrev_i32_e32 v114, 5, v114
	v_bfe_u32 v126, v112, 4, 2
	v_and_or_b32 v112, v112, 16, v113
	v_lshlrev_b32_e32 v156, 6, v125
	v_mov_b32_e32 v157, v153
	v_readlane_b32 s84, v253, 29
	v_readlane_b32 s85, v253, 30
	v_add_u32_e32 v114, v114, v115
	v_lshlrev_b32_e32 v152, 1, v112
	v_lshl_add_u64 v[144:145], s[84:85], 0, v[156:157]
	v_ashrrev_i32_e32 v115, 31, v114
	v_lshl_add_u64 v[112:113], v[144:145], 0, v[152:153]
	v_lshlrev_b64 v[146:147], 13, v[114:115]
	v_or_b32_e32 v114, 1, v114
	v_lshl_add_u64 v[150:151], v[112:113], 0, v[146:147]
	v_ashrrev_i32_e32 v115, 31, v114
	global_load_dwordx4 v[158:161], v[150:151], off
	v_lshlrev_b64 v[148:149], 13, v[114:115]
	v_lshl_add_u64 v[154:155], v[112:113], 0, v[148:149]
	global_load_dwordx4 v[128:131], v[154:155], off
	v_and_b32_e32 v113, 64, v185
	v_xor_b32_e32 v112, 16, v185
	v_add_u32_e32 v113, 64, v113
	v_cmp_lt_i32_e32 vcc, v112, v113
	v_or_b32_e32 v142, v127, v125
	v_lshlrev_b32_e32 v140, 1, v124
	v_cndmask_b32_e32 v112, v185, v112, vcc
	v_lshlrev_b32_e32 v172, 2, v112
	v_xor_b32_e32 v112, 32, v185
	v_cmp_lt_i32_e32 vcc, v112, v113
	v_ashrrev_i32_e32 v141, 31, v140
	v_ashrrev_i32_e32 v139, 31, v138
	v_cndmask_b32_e32 v112, v185, v112, vcc
	v_lshlrev_b32_e32 v173, 2, v112
	v_cmp_eq_u32_e32 vcc, 0, v126
	global_load_dwordx4 v[124:127], v[150:151], off offset:1024
	global_load_dwordx4 v[112:115], v[154:155], off offset:1024
	v_readlane_b32 s81, v253, 26
	v_readlane_b32 s82, v253, 27
	v_readlane_b32 s83, v253, 28
	v_readlane_b32 s86, v253, 31
	v_readlane_b32 s87, v253, 32
	v_readlane_b32 s88, v253, 33
	v_readlane_b32 s89, v253, 34
	v_readlane_b32 s90, v253, 35
	v_readlane_b32 s91, v253, 36
	v_readlane_b32 s92, v253, 37
	v_readlane_b32 s93, v253, 38
	v_readlane_b32 s94, v253, 39
	v_readlane_b32 s95, v253, 40
	s_waitcnt vmcnt(0)
	v_mov_b32_e32 v143, v160
	s_nop 1
	v_permlane16_swap_b32_e32 v158, v143
	v_mov_b32_e32 v164, v161
	s_nop 1
	v_permlane16_swap_b32_e32 v159, v164
	v_mov_b32_e32 v176, v130
	v_mov_b32_e32 v182, v131
	v_and_b32_e32 v131, 0xffff0000, v158
	v_lshlrev_b32_e32 v130, 16, v158
	v_pk_add_f32 v[130:131], v[178:179], v[130:131]
	v_and_b32_e32 v161, 0xffff0000, v159
	v_lshlrev_b32_e32 v160, 16, v159
	v_pk_add_f32 v[162:163], v[180:181], v[160:161]
	v_pk_mul_f32 v[160:161], v[130:131], v[130:131]
	v_cvt_pk_bf16_f32 v178, v130, v131
	v_and_b32_e32 v131, 0xffff0000, v143
	v_lshlrev_b32_e32 v130, 16, v143
	v_pk_mul_f32 v[158:159], v[162:163], v[162:163]
	v_cvt_pk_bf16_f32 v179, v162, v163
	v_pk_add_f32 v[130:131], v[224:225], v[130:131]
	v_and_b32_e32 v163, 0xffff0000, v164
	v_lshlrev_b32_e32 v162, 16, v164
	v_pk_add_f32 v[174:175], v[226:227], v[162:163]
	v_pk_mul_f32 v[164:165], v[130:131], v[130:131]
	v_cvt_pk_bf16_f32 v180, v130, v131
	v_lshl_add_u64 v[130:131], s[84:85], 0, v[146:147]
	v_pk_mul_f32 v[162:163], v[174:175], v[174:175]
	v_cvt_pk_bf16_f32 v181, v174, v175
	v_lshl_add_u64 v[174:175], v[130:131], 0, v[156:157]
	v_permlane16_swap_b32_e32 v128, v176
	v_permlane16_swap_b32_e32 v178, v180
	v_permlane16_swap_b32_e32 v179, v181
	v_lshl_add_u64 v[174:175], v[174:175], 0, v[152:153]
	v_permlane16_swap_b32_e32 v129, v182
	global_store_dwordx4 v[174:175], v[178:181], off
	v_and_b32_e32 v175, 0xffff0000, v128
	v_lshlrev_b32_e32 v174, 16, v128
	v_pk_add_f32 v[120:121], v[120:121], v[174:175]
	v_and_b32_e32 v175, 0xffff0000, v129
	v_lshlrev_b32_e32 v174, 16, v129
	v_pk_add_f32 v[122:123], v[122:123], v[174:175]
	v_pk_mul_f32 v[128:129], v[120:121], v[120:121]
	v_pk_mul_f32 v[174:175], v[122:123], v[122:123]
	v_cvt_pk_bf16_f32 v120, v120, v121
	v_cvt_pk_bf16_f32 v121, v122, v123
	v_and_b32_e32 v123, 0xffff0000, v176
	v_lshlrev_b32_e32 v122, 16, v176
	v_pk_add_f32 v[116:117], v[116:117], v[122:123]
	v_and_b32_e32 v123, 0xffff0000, v182
	v_lshlrev_b32_e32 v122, 16, v182
	v_add_f32_e32 v143, v164, v165
	v_add_f32_e32 v160, v160, v161
	v_pk_add_f32 v[118:119], v[118:119], v[122:123]
	v_pk_mul_f32 v[122:123], v[116:117], v[116:117]
	v_add_f32_e32 v143, v162, v143
	v_add_f32_e32 v158, v158, v160
	v_add_f32_e32 v128, v128, v129
	v_pk_mul_f32 v[178:179], v[118:119], v[118:119]
	v_add_f32_e32 v143, v163, v143
	v_add_f32_e32 v158, v159, v158
	v_add_f32_e32 v128, v174, v128
	v_add_f32_e32 v122, v122, v123
	v_add_f32_e32 v143, v158, v143
	v_add_f32_e32 v128, v175, v128
	v_add_f32_e32 v122, v178, v122
	v_add_f32_e32 v128, v143, v128
	v_add_f32_e32 v122, v179, v122
	v_add_f32_e32 v143, v122, v128
	v_lshl_add_u64 v[128:129], s[84:85], 0, v[148:149]
	v_cvt_pk_bf16_f32 v122, v116, v117
	v_cvt_pk_bf16_f32 v123, v118, v119
	v_lshl_add_u64 v[116:117], v[128:129], 0, v[156:157]
	v_permlane16_swap_b32_e32 v120, v122
	v_permlane16_swap_b32_e32 v121, v123
	v_lshl_add_u64 v[116:117], v[116:117], 0, v[152:153]
	global_store_dwordx4 v[116:117], v[120:123], off
	ds_bpermute_b32 v116, v172, v143
	s_waitcnt lgkmcnt(0)
	v_add_f32_e32 v116, v143, v116
	ds_bpermute_b32 v117, v173, v116
	s_and_saveexec_b64 s[12:13], vcc
	s_cbranch_execz .LBB0_267
; template <int MODE, int NSUB>
; __device__ __forceinline__ void epilogue(const Params& p, int layer, f32x4 (&acc)[4][NSUB], int tm, int tn, int g,
;                                          const float* s_rstd, const int tid_in) {
;     ...
;       ss = red_fq(ss);
;       if (fq == 0) p.part[(long)t * 16 + tm * 2 + wr] = ss;
	v_ashrrev_i32_e32 v143, 31, v142
	v_readlane_b32 s64, v253, 25
	v_lshlrev_b64 v[118:119], 6, v[142:143]
	v_readlane_b32 s70, v253, 31
	v_readlane_b32 s71, v253, 32
	s_waitcnt lgkmcnt(0)
	v_add_f32_e32 v116, v116, v117
	v_readlane_b32 s65, v253, 26
	v_lshl_add_u64 v[118:119], s[70:71], 0, v[118:119]
	v_lshl_add_u64 v[118:119], v[140:141], 2, v[118:119]
	v_lshl_add_u64 v[118:119], v[138:139], 2, v[118:119]
	v_readlane_b32 s66, v253, 27
	v_readlane_b32 s67, v253, 28
	v_readlane_b32 s68, v253, 29
	v_readlane_b32 s69, v253, 30
	v_readlane_b32 s72, v253, 33
	v_readlane_b32 s73, v253, 34
	v_readlane_b32 s74, v253, 35
	v_readlane_b32 s75, v253, 36
	v_readlane_b32 s76, v253, 37
	v_readlane_b32 s77, v253, 38
	v_readlane_b32 s78, v253, 39
	v_readlane_b32 s79, v253, 40
	global_store_dword v[118:119], v116, off

; template <int NK, bool BNT = false> ...
;     ...
;   auto stage = [&](int kt, int bufc) {
;     unsigned char* sa = smem + bufc * BIG_STAGE;
;     const unsigned char* Ab = Abase + (long)kt * 8192 + soff;
;     const unsigned char* Bb = Bbase + (long)kt * 8192 + soff;
;     glds16(Ab, sa + sb0);
;     glds16(Ab + astride * 2, sa + 8192 + sb0);
;     if constexpr (BNT) {
;       glds16_nt(Bb, sa + 16384 + sb0);
;       glds16_nt(Bb + bstride * 2, sa + 24576 + sb0);
;     } else {
;       glds16(Bb, sa + 16384 + sb0);
;       glds16(Bb + bstride * 2, sa + 24576 + sb0);
;     }
;   };
; __device__ __forceinline__ void compute_rstd(const float* __restrict__ part, int nslot, float invn, int t0, int ntok,
;                                              float* s_rstd, const int tid_in) {
;   int tid = tid_in;
;   asm volatile("" : "+v"(tid));
;   if (tid < ntok) {
;     const float* pp = part + (long)(t0 + tid) * nslot;
;     float s = 0.f;
;     for (int i = 0; i < nslot; ++i) s += pp[i];
;     s_rstd[tid] = rsqrtf(s * invn + 1e-6f);
;   }
; }
.LBB0_287:
	s_ashr_i32 s10, s9, 31
	s_lshr_b32 s11, s10, 27
	s_add_i32 s17, s9, s11
	s_and_b32 s11, s17, 0xffe0
	s_sub_i32 s13, s9, s11
	s_bfe_i32 s11, s13, 0x80000
	s_bfe_u32 s11, s11, 0x2000d
	s_add_i32 s11, s13, s11
	s_lshr_b32 s10, s10, 25
	s_bfe_i32 s11, s11, 0x80000
	s_add_i32 s10, s9, s10
	s_sext_i32_i16 s18, s11
	s_ashr_i32 s10, s10, 7
	s_lshl_b32 s15, s10, 3
	s_ashr_i32 s10, s18, 2
	s_add_i32 s15, s15, s10
	v_mov_b32_e32 v232, v214
	s_add_i32 s12, s15, s14
	s_nop 0
	v_cmp_gt_i32_e32 vcc, s30, v232
	s_and_saveexec_b64 s[10:11], vcc
	s_cbranch_execz .LBB0_289
	v_lshl_add_u32 v234, s12, 8, v232
	v_ashrrev_i32_e32 v235, 31, v234
	v_readlane_b32 s64, v253, 25
	v_lshlrev_b64 v[234:235], 6, v[234:235]
	v_readlane_b32 s70, v253, 31
	v_readlane_b32 s71, v253, 32
	s_mov_b32 s19, 0x800000
	v_lshl_add_u32 v232, v232, 2, v200
	v_lshl_add_u64 v[236:237], s[70:71], 0, v[234:235]
	s_waitcnt lgkmcnt(0)
	global_load_dwordx4 v[216:219], v[236:237], off
	global_load_dwordx4 v[220:223], v[236:237], off offset:16
	global_load_dwordx4 v[224:227], v[236:237], off offset:32
	s_nop 0
	global_load_dwordx4 v[228:231], v[236:237], off offset:48
	v_readlane_b32 s65, v253, 26
	v_readlane_b32 s66, v253, 27
	v_readlane_b32 s67, v253, 28
	v_readlane_b32 s68, v253, 29
	v_readlane_b32 s69, v253, 30
	v_readlane_b32 s72, v253, 33
	v_readlane_b32 s73, v253, 34
	v_readlane_b32 s74, v253, 35
	v_readlane_b32 s75, v253, 36
	v_readlane_b32 s76, v253, 37
	v_readlane_b32 s77, v253, 38
	v_readlane_b32 s78, v253, 39
	v_readlane_b32 s79, v253, 40
.LBB0_289:
	s_or_b64 exec, exec, s[10:11]
	s_ashr_i32 s10, s17, 5
	s_lshr_b32 s17, s10, 30
	s_lshr_b32 s11, s18, 2
	s_add_i32 s17, s10, s17
	s_and_b32 s17, s17, 0x3ffffffc
	s_lshl_b32 s11, s11, 2
	s_sub_i32 s10, s10, s17
	s_sub_i32 s11, s13, s11
	s_lshl_b32 s10, s10, 2
	s_sext_i32_i8 s11, s11
	s_add_i32 s10, s10, s11
	s_ashr_i32 s11, s10, 31
	s_lshl_b64 s[18:19], s[10:11], 19
	s_add_u32 s20, s6, s18
	s_addc_u32 s21, s7, s19
	s_ashr_i32 s13, s12, 31
	v_readlane_b32 s64, v253, 25
	s_lshl_b64 s[12:13], s[12:13], 19
	v_readlane_b32 s68, v253, 29
	v_readfirstlane_b32 s11, v146
	v_add_u32_e32 v151, 0x2000, v146
	v_readlane_b32 s69, v253, 30
	s_add_u32 s22, s68, s12
	v_lshl_add_u64 v[136:137], s[20:21], 0, v[128:129]
	s_mov_b32 m0, s11
	s_mov_b64 s[20:21], 0x40000
	v_readfirstlane_b32 s11, v151
	v_add_u32_e32 v152, 0x4000, v146
	s_addc_u32 s23, s69, s13
	global_load_lds_dwordx4 v[136:137], off
	v_lshl_add_u64 v[0:1], v[136:137], 0, s[20:21]
	s_mov_b32 m0, s11
	v_readfirstlane_b32 s11, v152
	v_add_u32_e32 v154, 0x6000, v146
	v_lshl_add_u64 v[134:135], s[22:23], 0, v[128:129]
	global_load_lds_dwordx4 v[0:1], off
	s_mov_b32 m0, s11
	v_readfirstlane_b32 s11, v154
	v_add_u32_e32 v155, 0x8000, v146
	global_load_lds_dwordx4 v[134:135], off
	v_lshl_add_u64 v[0:1], v[134:135], 0, s[20:21]
	s_mov_b32 m0, s11
	s_mov_b64 s[20:21], 0x2000
	v_readfirstlane_b32 s11, v155
	v_add_u32_e32 v156, 0xa000, v146
	global_load_lds_dwordx4 v[0:1], off
	v_lshl_add_u64 v[0:1], v[136:137], 0, s[20:21]
	v_lshl_add_u64 v[2:3], v[134:135], 0, s[20:21]
	s_mov_b32 m0, s11
	s_mov_b64 s[20:21], 0x42000
	v_readfirstlane_b32 s11, v156
	v_add_u32_e32 v157, 0xc000, v146
	global_load_lds_dwordx4 v[0:1], off
	v_lshl_add_u64 v[0:1], v[136:137], 0, s[20:21]
	s_mov_b32 m0, s11
	v_readfirstlane_b32 s11, v157
	v_add_u32_e32 v158, 0xe000, v146
	global_load_lds_dwordx4 v[0:1], off
	s_mov_b32 m0, s11
	v_readfirstlane_b32 s11, v158
	v_add_u32_e32 v159, 0x10000, v146
	global_load_lds_dwordx4 v[2:3], off
	v_lshl_add_u64 v[0:1], v[134:135], 0, s[20:21]
	s_mov_b32 m0, s11
	v_readfirstlane_b32 s11, v159
	v_add_u32_e32 v160, 0x12000, v146
	global_load_lds_dwordx4 v[0:1], off
	v_lshl_add_u64 v[0:1], v[136:137], 0, s[94:95]
	s_mov_b32 m0, s11
	s_mov_b64 s[20:21], 0x44000
	v_readfirstlane_b32 s11, v160
	v_add_u32_e32 v161, 0x14000, v146
	global_load_lds_dwordx4 v[0:1], off
	v_lshl_add_u64 v[0:1], v[136:137], 0, s[20:21]
	s_mov_b32 m0, s11
	v_readfirstlane_b32 s11, v161
	v_add_u32_e32 v162, 0x16000, v146
	v_lshl_add_u64 v[2:3], v[134:135], 0, s[94:95]
	global_load_lds_dwordx4 v[0:1], off
	s_mov_b32 m0, s11
	v_readfirstlane_b32 s11, v162
	global_load_lds_dwordx4 v[2:3], off
	v_lshl_add_u64 v[0:1], v[134:135], 0, s[20:21]
	s_mov_b32 m0, s11
	v_lshl_add_u64 v[138:139], v[130:131], 0, s[18:19]
	global_load_lds_dwordx4 v[0:1], off
	v_mov_b32_e32 v0, 0
	v_lshl_add_u64 v[140:141], v[132:133], 0, s[12:13]
	s_mov_b64 s[12:13], 0
	v_mov_b32_e32 v1, v0
	v_mov_b32_e32 v2, v0
	v_mov_b32_e32 v3, v0
	v_mov_b32_e32 v4, v0
	s_waitcnt lgkmcnt(0)
; template <int NK, bool BNT = false> ...
;     ...
; #pragma unroll
;   for (int m = 0; m < 4; ++m)
; #pragma unroll
;     for (int n = 0; n < 8; ++n) acc[m][n] = f32x4{0.f, 0.f, 0.f, 0.f};
;   const int sb0 = tidf * 16;
;   const int sr0 = sb0 >> 6;
;   const unsigned soff = (unsigned)(sr0 * 64 + ((((sb0 >> 4) & 3) ^ (((sr0 >> 3) & 1) << 1)) * 16));
;   const unsigned char* Abase = reinterpret_cast<const unsigned char*>(A);
;   const unsigned char* Bbase = reinterpret_cast<const unsigned char*>(B);
;   auto stage = [&](int kt, int bufc) {
;     unsigned char* sa = smem + bufc * BIG_STAGE;
;     const unsigned char* Ab = Abase + (long)kt * 8192 + soff;
;     const unsigned char* Bb = Bbase + (long)kt * 8192 + soff;
;     glds16(Ab, sa + sb0);
;     glds16(Ab + astride * 2, sa + 8192 + sb0);
;     if constexpr (BNT) {
;       glds16_nt(Bb, sa + 16384 + sb0);
;       glds16_nt(Bb + bstride * 2, sa + 24576 + sb0);
;     } else {
;       glds16(Bb, sa + 16384 + sb0);
;       glds16(Bb + bstride * 2, sa + 24576 + sb0);
;     }
;   };
;   const int rd = fr * 64 + ((fq ^ (((fr >> 3) & 1) << 1)) * 16);
;   const int aoff = wr * 64 * 64 + rd;
;   const int boff = 16384 + wc * 128 * 64 + rd;
;   auto kstep = [&](int T, int cur, int nxt, bool do_stage) {
;     const unsigned char* sa = smem + cur * BIG_STAGE;
;     bf16x8 af[4], bfr[4];
; #pragma unroll
;     for (int m = 0; m < 4; ++m) af[m] = *reinterpret_cast<const bf16x8*>(sa + aoff + m * 1024);
; #pragma unroll
;     for (int n = 0; n < 4; ++n) bfr[n] = *reinterpret_cast<const bf16x8*>(sa + boff + n * 1024);
; __device__ __forceinline__ void compute_rstd(const float* __restrict__ part, int nslot, float invn, int t0, int ntok,
;                                              float* s_rstd, const int tid_in) {
;   int tid = tid_in;
;   asm volatile("" : "+v"(tid));
;   if (tid < ntok) {
;     const float* pp = part + (long)(t0 + tid) * nslot;
;     float s = 0.f;
;     for (int i = 0; i < nslot; ++i) s += pp[i];
;     s_rstd[tid] = rsqrtf(s * invn + 1e-6f);
;   }
; }
	v_mov_b32_e32 v5, v0
	v_mov_b32_e32 v6, v0
	v_mov_b32_e32 v7, v0
	v_mov_b32_e32 v8, v0
	v_mov_b32_e32 v9, v0
	v_mov_b32_e32 v10, v0
	v_mov_b32_e32 v11, v0
	v_mov_b32_e32 v12, v0
	v_mov_b32_e32 v13, v0
	v_mov_b32_e32 v14, v0
	v_mov_b32_e32 v15, v0
	v_mov_b32_e32 v32, v0
	v_mov_b32_e32 v33, v0
	v_mov_b32_e32 v34, v0
	v_mov_b32_e32 v35, v0
	v_mov_b32_e32 v36, v0
	v_mov_b32_e32 v37, v0
	v_mov_b32_e32 v38, v0
	v_mov_b32_e32 v39, v0
	v_mov_b32_e32 v40, v0
	v_mov_b32_e32 v41, v0
	v_mov_b32_e32 v42, v0
	v_mov_b32_e32 v43, v0
	v_mov_b32_e32 v44, v0
	v_mov_b32_e32 v45, v0
	v_mov_b32_e32 v46, v0
	v_mov_b32_e32 v47, v0
	v_mov_b32_e32 v16, v0
	v_mov_b32_e32 v17, v0
	v_mov_b32_e32 v18, v0
	v_mov_b32_e32 v19, v0
	v_mov_b32_e32 v20, v0
	v_mov_b32_e32 v21, v0
	v_mov_b32_e32 v22, v0
	v_mov_b32_e32 v23, v0
	v_mov_b32_e32 v24, v0
	v_mov_b32_e32 v25, v0
	v_mov_b32_e32 v26, v0
	v_mov_b32_e32 v27, v0
	v_mov_b32_e32 v28, v0
	v_mov_b32_e32 v29, v0
	v_mov_b32_e32 v30, v0
	v_mov_b32_e32 v31, v0
	v_mov_b32_e32 v64, v0
	v_mov_b32_e32 v65, v0
	v_mov_b32_e32 v66, v0
	v_mov_b32_e32 v67, v0
	v_mov_b32_e32 v68, v0
	v_mov_b32_e32 v69, v0
	v_mov_b32_e32 v70, v0
	v_mov_b32_e32 v71, v0
	v_mov_b32_e32 v76, v0
	v_mov_b32_e32 v77, v0
	v_mov_b32_e32 v78, v0
	v_mov_b32_e32 v79, v0
	v_mov_b32_e32 v88, v0
	v_mov_b32_e32 v89, v0
	v_mov_b32_e32 v90, v0
	v_mov_b32_e32 v91, v0
	v_mov_b32_e32 v48, v0
	v_mov_b32_e32 v49, v0
	v_mov_b32_e32 v50, v0
	v_mov_b32_e32 v51, v0
	v_mov_b32_e32 v52, v0
	v_mov_b32_e32 v53, v0
	v_mov_b32_e32 v54, v0
	v_mov_b32_e32 v55, v0
	v_mov_b32_e32 v56, v0
	v_mov_b32_e32 v57, v0
	v_mov_b32_e32 v58, v0
	v_mov_b32_e32 v59, v0
	v_mov_b32_e32 v60, v0
	v_mov_b32_e32 v61, v0
	v_mov_b32_e32 v62, v0
	v_mov_b32_e32 v63, v0
	v_mov_b32_e32 v96, v0
	v_mov_b32_e32 v97, v0
	v_mov_b32_e32 v98, v0
	v_mov_b32_e32 v99, v0
	v_mov_b32_e32 v100, v0
	v_mov_b32_e32 v101, v0
	v_mov_b32_e32 v102, v0
	v_mov_b32_e32 v103, v0
	v_mov_b32_e32 v104, v0
	v_mov_b32_e32 v105, v0
	v_mov_b32_e32 v106, v0
	v_mov_b32_e32 v107, v0
	v_mov_b32_e32 v108, v0
	v_mov_b32_e32 v109, v0
	v_mov_b32_e32 v110, v0
	v_mov_b32_e32 v111, v0
	v_mov_b32_e32 v72, v0
	v_mov_b32_e32 v73, v0
	v_mov_b32_e32 v74, v0
	v_mov_b32_e32 v75, v0
	v_mov_b32_e32 v80, v0
	v_mov_b32_e32 v81, v0
	v_mov_b32_e32 v82, v0
	v_mov_b32_e32 v83, v0
	v_mov_b32_e32 v84, v0
	v_mov_b32_e32 v85, v0
	v_mov_b32_e32 v86, v0
	v_mov_b32_e32 v87, v0
	v_mov_b32_e32 v92, v0
	v_mov_b32_e32 v93, v0
	v_mov_b32_e32 v94, v0
	v_mov_b32_e32 v95, v0
	v_mov_b32_e32 v112, v0
	v_mov_b32_e32 v113, v0
	v_mov_b32_e32 v114, v0
	v_mov_b32_e32 v115, v0
	v_mov_b32_e32 v116, v0
	v_mov_b32_e32 v117, v0
	v_mov_b32_e32 v118, v0
	v_mov_b32_e32 v119, v0
	v_mov_b32_e32 v120, v0
	v_mov_b32_e32 v121, v0
	v_mov_b32_e32 v122, v0
	v_mov_b32_e32 v123, v0
	v_mov_b32_e32 v124, v0
	v_mov_b32_e32 v125, v0
	v_mov_b32_e32 v126, v0
	v_mov_b32_e32 v127, v0
	v_readlane_b32 s65, v253, 26
	v_readlane_b32 s66, v253, 27
	v_readlane_b32 s67, v253, 28
	v_readlane_b32 s70, v253, 31
	v_readlane_b32 s71, v253, 32
	v_readlane_b32 s72, v253, 33
	v_readlane_b32 s73, v253, 34
	v_readlane_b32 s74, v253, 35
	v_readlane_b32 s75, v253, 36
	v_readlane_b32 s76, v253, 37
	v_readlane_b32 s77, v253, 38
	v_readlane_b32 s78, v253, 39
	v_readlane_b32 s79, v253, 40
	v_cmp_gt_i32_e32 vcc, s30, v214
	s_and_saveexec_b64 s[100:101], vcc
	s_cbranch_execz .Lmy_up_rsdone
	s_waitcnt vmcnt(15)
	v_add_f32_e32 v233, 0, v216
	v_add_f32_e32 v233, v233, v217
	v_add_f32_e32 v233, v233, v218
	v_add_f32_e32 v233, v233, v219
	s_waitcnt vmcnt(14)
	v_add_f32_e32 v233, v233, v220
	v_add_f32_e32 v233, v233, v221
	v_add_f32_e32 v233, v233, v222
	v_add_f32_e32 v233, v233, v223
	s_waitcnt vmcnt(13)
	v_add_f32_e32 v233, v233, v224
	v_add_f32_e32 v233, v233, v225
	v_add_f32_e32 v233, v233, v226
	v_add_f32_e32 v233, v233, v227
	s_waitcnt vmcnt(12)
	v_add_f32_e32 v233, v233, v228
	v_add_f32_e32 v233, v233, v229
	v_add_f32_e32 v233, v233, v230
	v_add_f32_e32 v233, v233, v231
	v_fmamk_f32 v233, v233, 0x3a800000, v184
	v_mul_f32_e32 v234, 0x4b800000, v233
	v_cmp_gt_f32_e32 vcc, 0x800000, v233
	s_nop 1
	v_cndmask_b32_e32 v233, v233, v234, vcc
	v_rsq_f32_e32 v233, v233
	s_nop 0
	v_mul_f32_e32 v234, 0x45800000, v233
	v_cndmask_b32_e32 v233, v233, v234, vcc
	ds_write_b32 v232, v233
.Lmy_up_rsdone:
	s_or_b64 exec, exec, s[100:101]
	s_waitcnt vmcnt(8)
	s_barrier
	v_add_u32_e32 v167, 0x10000, v147
	v_or_b32_e32 v168, 0x10000, v149
	v_add_u32_e32 v176, 0x18000, v147
	v_or_b32_e32 v179, 0x18000, v149
	ds_read_b128 v[216:219], v147
	ds_read_b128 v[220:223], v147 offset:1024
	ds_read_b128 v[224:227], v147 offset:2048
	ds_read_b128 v[228:231], v147 offset:3072
	ds_read_b128 v[232:235], v148 offset:16384
	ds_read_b128 v[236:239], v148 offset:17408
	ds_read_b128 v[240:243], v148 offset:18432
	ds_read_b128 v[244:247], v148 offset:19456
; #define BIG_SYNC(N)                                              \
;   asm volatile("s_waitcnt vmcnt(%0)" ::"n"(N) : "memory");       \
;   __builtin_amdgcn_s_barrier();                                  \
;   asm volatile("" ::: "memory");                                 \
;   __builtin_amdgcn_sched_barrier(0);
; template <int NK, bool BNT = false> ...
;     ...
;   auto kstep = [&](int T, int cur, int nxt, bool do_stage) {
;     const unsigned char* sa = smem + cur * BIG_STAGE;
;     bf16x8 af[4], bfr[4];
; #pragma unroll
;     for (int m = 0; m < 4; ++m) af[m] = *reinterpret_cast<const bf16x8*>(sa + aoff + m * 1024);
; #pragma unroll
;     for (int n = 0; n < 4; ++n) bfr[n] = *reinterpret_cast<const bf16x8*>(sa + boff + n * 1024);
;     __builtin_amdgcn_sched_barrier(0);
;     if (do_stage) stage(T + 3, nxt);
; #pragma unroll
;     for (int m = 0; m < 4; ++m)
; #pragma unroll
;       for (int n = 0; n < 4; ++n) acc[m][n] = __builtin_amdgcn_mfma_f32_16x16x32_bf16(af[m], bfr[n], acc[m][n], 0, 0, 0);
;     if (do_stage) {
; #pragma unroll
;       for (int q = 0; q < NG; ++q) {
;         __builtin_amdgcn_sched_group_barrier(0x008, 3, 0);
;         __builtin_amdgcn_sched_group_barrier(0x010, 1, 0);
;       }
;       __builtin_amdgcn_sched_group_barrier(0x008, 16 - 3 * NG, 0);
;     }
;     __builtin_amdgcn_sched_barrier(0);
; #pragma unroll
;     for (int n = 0; n < 4; ++n) bfr[n] = *reinterpret_cast<const bf16x8*>(sa + boff + (4 + n) * 1024);
; #pragma unroll
;     for (int m = 0; m < 4; ++m)
; #pragma unroll
;       for (int n = 0; n < 4; ++n)
;         acc[m][4 + n] = __builtin_amdgcn_mfma_f32_16x16x32_bf16(af[m], bfr[n], acc[m][4 + n], 0, 0, 0);
;     __builtin_amdgcn_sched_barrier(0);
;   };
;     ...
;   for (int it = 0; it < NK / 4 - 1; ++it) {
;     const int t = it * 4;
;     BIG_SYNC(2 * NG); kstep(t, 0, 3, true);
;     BIG_SYNC(2 * NG); kstep(t + 1, 1, 0, true);
;     BIG_SYNC(2 * NG); kstep(t + 2, 2, 1, true);
;     BIG_SYNC(2 * NG); kstep(t + 3, 3, 2, true);
;   }
.LBB0_290:
	s_waitcnt vmcnt(4)
	s_barrier
	v_add_u32_e32 v163, 0x18000, v146
	v_lshl_add_u64 v[144:145], v[138:139], 0, s[12:13]
	v_readfirstlane_b32 s11, v163
	v_lshl_add_u64 v[164:165], v[144:145], 0, s[60:61]
	s_mov_b32 m0, s11
	s_waitcnt lgkmcnt(3)
	v_mfma_f32_16x16x32_bf16 v[124:127], v[216:219], v[232:235], v[124:127]
	v_lshl_add_u64 v[142:143], v[140:141], 0, s[12:13]
	v_lshl_add_u64 v[168:169], v[144:145], 0, s[80:81]
	v_lshl_add_u64 v[166:167], v[142:143], 0, s[60:61]
	v_mfma_f32_16x16x32_bf16 v[108:111], v[220:223], v[232:235], v[108:111]
	v_mfma_f32_16x16x32_bf16 v[88:91], v[224:227], v[232:235], v[88:91]
	global_load_lds_dwordx4 v[164:165], off
	v_add_u32_e32 v164, 0x1a000, v146
	v_add_u32_e32 v165, 0x1c000, v146
	v_readfirstlane_b32 s11, v164
	s_mov_b32 m0, s11
	v_readfirstlane_b32 s11, v165
	v_mfma_f32_16x16x32_bf16 v[44:47], v[228:231], v[232:235], v[44:47]
	s_waitcnt lgkmcnt(2)
	v_mfma_f32_16x16x32_bf16 v[120:123], v[216:219], v[236:239], v[120:123]
	ds_read_b128 v[232:235], v148 offset:20480
	v_mfma_f32_16x16x32_bf16 v[104:107], v[220:223], v[236:239], v[104:107]
	global_load_lds_dwordx4 v[168:169], off
	s_mov_b32 m0, s11
	v_mfma_f32_16x16x32_bf16 v[76:79], v[224:227], v[236:239], v[76:79]
	v_lshl_add_u64 v[168:169], v[142:143], 0, s[80:81]
	v_mfma_f32_16x16x32_bf16 v[40:43], v[228:231], v[236:239], v[40:43]
	s_waitcnt lgkmcnt(2)
	v_mfma_f32_16x16x32_bf16 v[116:119], v[216:219], v[240:243], v[116:119]
	ds_read_b128 v[236:239], v148 offset:21504
	global_load_lds_dwordx4 v[166:167], off
	v_add_u32_e32 v166, 0x1e000, v146
	v_mfma_f32_16x16x32_bf16 v[100:103], v[220:223], v[240:243], v[100:103]
	v_readfirstlane_b32 s11, v166
	s_mov_b32 m0, s11
	v_mfma_f32_16x16x32_bf16 v[68:71], v[224:227], v[240:243], v[68:71]
	v_mfma_f32_16x16x32_bf16 v[36:39], v[228:231], v[240:243], v[36:39]
	global_load_lds_dwordx4 v[168:169], off
	s_waitcnt lgkmcnt(2)
	v_mfma_f32_16x16x32_bf16 v[112:115], v[216:219], v[244:247], v[112:115]
	ds_read_b128 v[240:243], v148 offset:22528
	v_mfma_f32_16x16x32_bf16 v[96:99], v[220:223], v[244:247], v[96:99]
	v_mfma_f32_16x16x32_bf16 v[64:67], v[224:227], v[244:247], v[64:67]
	v_mfma_f32_16x16x32_bf16 v[32:35], v[228:231], v[244:247], v[32:35]
	s_waitcnt lgkmcnt(2)
	v_mfma_f32_16x16x32_bf16 v[92:95], v[216:219], v[232:235], v[92:95]
	ds_read_b128 v[244:247], v148 offset:23552
	v_mfma_f32_16x16x32_bf16 v[60:63], v[220:223], v[232:235], v[60:63]
	ds_read_b128 v[186:189], v147 offset:32768
	v_mfma_f32_16x16x32_bf16 v[28:31], v[224:227], v[232:235], v[28:31]
	ds_read_b128 v[190:193], v147 offset:33792
	v_mfma_f32_16x16x32_bf16 v[12:15], v[228:231], v[232:235], v[12:15]
	ds_read_b128 v[194:197], v147 offset:34816
	s_waitcnt lgkmcnt(5)
	v_mfma_f32_16x16x32_bf16 v[84:87], v[216:219], v[236:239], v[84:87]
	ds_read_b128 v[202:205], v147 offset:35840
	ds_read_b128 v[232:235], v148 offset:49152
	v_mfma_f32_16x16x32_bf16 v[56:59], v[220:223], v[236:239], v[56:59]
	v_mfma_f32_16x16x32_bf16 v[24:27], v[224:227], v[236:239], v[24:27]
	v_mfma_f32_16x16x32_bf16 v[8:11], v[228:231], v[236:239], v[8:11]
	s_waitcnt lgkmcnt(6)
	v_mfma_f32_16x16x32_bf16 v[80:83], v[216:219], v[240:243], v[80:83]
	ds_read_b128 v[236:239], v148 offset:50176
	v_mfma_f32_16x16x32_bf16 v[52:55], v[220:223], v[240:243], v[52:55]
	v_mfma_f32_16x16x32_bf16 v[20:23], v[224:227], v[240:243], v[20:23]
	v_mfma_f32_16x16x32_bf16 v[4:7], v[228:231], v[240:243], v[4:7]
	s_waitcnt lgkmcnt(6)
	v_mfma_f32_16x16x32_bf16 v[72:75], v[216:219], v[244:247], v[72:75]
	ds_read_b128 v[240:243], v148 offset:51200
	v_mfma_f32_16x16x32_bf16 v[48:51], v[220:223], v[244:247], v[48:51]
	v_mfma_f32_16x16x32_bf16 v[16:19], v[224:227], v[244:247], v[16:19]
	v_mfma_f32_16x16x32_bf16 v[0:3], v[228:231], v[244:247], v[0:3]
	ds_read_b128 v[244:247], v148 offset:52224
	s_waitcnt vmcnt(4)
	s_barrier
	v_readfirstlane_b32 s11, v146
	v_lshl_add_u64 v[168:169], v[144:145], 0, s[62:63]
	s_mov_b32 m0, s11
	v_readfirstlane_b32 s11, v151
	s_waitcnt lgkmcnt(3)
	v_mfma_f32_16x16x32_bf16 v[124:127], v[186:189], v[232:235], v[124:127]
	v_lshl_add_u64 v[182:183], v[142:143], 0, s[62:63]
	v_mfma_f32_16x16x32_bf16 v[108:111], v[190:193], v[232:235], v[108:111]
	v_mfma_f32_16x16x32_bf16 v[88:91], v[194:197], v[232:235], v[88:91]
	global_load_lds_dwordx4 v[168:169], off
	v_lshl_add_u64 v[168:169], v[144:145], 0, s[0:1]
	s_mov_b32 m0, s11
	v_readfirstlane_b32 s11, v152
	v_mfma_f32_16x16x32_bf16 v[44:47], v[202:205], v[232:235], v[44:47]
	s_waitcnt lgkmcnt(2)
	v_mfma_f32_16x16x32_bf16 v[120:123], v[186:189], v[236:239], v[120:123]
	ds_read_b128 v[232:235], v148 offset:53248
	v_mfma_f32_16x16x32_bf16 v[104:107], v[190:193], v[236:239], v[104:107]
	global_load_lds_dwordx4 v[168:169], off
	s_mov_b32 m0, s11
	v_readfirstlane_b32 s11, v154
	v_lshl_add_u64 v[168:169], v[142:143], 0, s[0:1]
	v_mfma_f32_16x16x32_bf16 v[76:79], v[194:197], v[236:239], v[76:79]
	v_mfma_f32_16x16x32_bf16 v[40:43], v[202:205], v[236:239], v[40:43]
	s_waitcnt lgkmcnt(2)
	v_mfma_f32_16x16x32_bf16 v[116:119], v[186:189], v[240:243], v[116:119]
	ds_read_b128 v[236:239], v148 offset:54272
	global_load_lds_dwordx4 v[182:183], off
	s_mov_b32 m0, s11
	v_mfma_f32_16x16x32_bf16 v[100:103], v[190:193], v[240:243], v[100:103]
	v_mfma_f32_16x16x32_bf16 v[68:71], v[194:197], v[240:243], v[68:71]
	v_mfma_f32_16x16x32_bf16 v[36:39], v[202:205], v[240:243], v[36:39]
	global_load_lds_dwordx4 v[168:169], off
	s_waitcnt lgkmcnt(2)
	v_mfma_f32_16x16x32_bf16 v[112:115], v[186:189], v[244:247], v[112:115]
	ds_read_b128 v[240:243], v148 offset:55296
	v_mfma_f32_16x16x32_bf16 v[96:99], v[190:193], v[244:247], v[96:99]
	v_mfma_f32_16x16x32_bf16 v[64:67], v[194:197], v[244:247], v[64:67]
	v_mfma_f32_16x16x32_bf16 v[32:35], v[202:205], v[244:247], v[32:35]
	v_add_u32_e32 v167, 0x10000, v147
	v_or_b32_e32 v168, 0x10000, v149
	s_waitcnt lgkmcnt(2)
; #define BIG_SYNC(N)                                              \
;   asm volatile("s_waitcnt vmcnt(%0)" ::"n"(N) : "memory");       \
;   __builtin_amdgcn_s_barrier();                                  \
;   asm volatile("" ::: "memory");                                 \
;   __builtin_amdgcn_sched_barrier(0);
; template <int NK, bool BNT = false> ...
;     ...
;   auto kstep = [&](int T, int cur, int nxt, bool do_stage) {
;     const unsigned char* sa = smem + cur * BIG_STAGE;
;     bf16x8 af[4], bfr[4];
; #pragma unroll
;     for (int m = 0; m < 4; ++m) af[m] = *reinterpret_cast<const bf16x8*>(sa + aoff + m * 1024);
; #pragma unroll
;     for (int n = 0; n < 4; ++n) bfr[n] = *reinterpret_cast<const bf16x8*>(sa + boff + n * 1024);
;     __builtin_amdgcn_sched_barrier(0);
;     if (do_stage) stage(T + 3, nxt);
; #pragma unroll
;     for (int m = 0; m < 4; ++m)
; #pragma unroll
;       for (int n = 0; n < 4; ++n) acc[m][n] = __builtin_amdgcn_mfma_f32_16x16x32_bf16(af[m], bfr[n], acc[m][n], 0, 0, 0);
;     if (do_stage) {
; #pragma unroll
;       for (int q = 0; q < NG; ++q) {
;         __builtin_amdgcn_sched_group_barrier(0x008, 3, 0);
;         __builtin_amdgcn_sched_group_barrier(0x010, 1, 0);
;       }
;       __builtin_amdgcn_sched_group_barrier(0x008, 16 - 3 * NG, 0);
;     }
;     __builtin_amdgcn_sched_barrier(0);
; #pragma unroll
;     for (int n = 0; n < 4; ++n) bfr[n] = *reinterpret_cast<const bf16x8*>(sa + boff + (4 + n) * 1024);
; #pragma unroll
;     for (int m = 0; m < 4; ++m)
; #pragma unroll
;       for (int n = 0; n < 4; ++n)
;         acc[m][4 + n] = __builtin_amdgcn_mfma_f32_16x16x32_bf16(af[m], bfr[n], acc[m][4 + n], 0, 0, 0);
;     __builtin_amdgcn_sched_barrier(0);
;   };
;     ...
;   for (int it = 0; it < NK / 4 - 1; ++it) {
;     const int t = it * 4;
;     BIG_SYNC(2 * NG); kstep(t, 0, 3, true);
;     BIG_SYNC(2 * NG); kstep(t + 1, 1, 0, true);
;     BIG_SYNC(2 * NG); kstep(t + 2, 2, 1, true);
;     BIG_SYNC(2 * NG); kstep(t + 3, 3, 2, true);
;   }
	v_mfma_f32_16x16x32_bf16 v[92:95], v[186:189], v[232:235], v[92:95]
	ds_read_b128 v[244:247], v148 offset:56320
	v_mfma_f32_16x16x32_bf16 v[60:63], v[190:193], v[232:235], v[60:63]
	ds_read_b128 v[216:219], v167
	v_mfma_f32_16x16x32_bf16 v[28:31], v[194:197], v[232:235], v[28:31]
	ds_read_b128 v[220:223], v167 offset:1024
	v_mfma_f32_16x16x32_bf16 v[12:15], v[202:205], v[232:235], v[12:15]
	ds_read_b128 v[224:227], v167 offset:2048
	s_waitcnt lgkmcnt(5)
	v_mfma_f32_16x16x32_bf16 v[84:87], v[186:189], v[236:239], v[84:87]
	ds_read_b128 v[228:231], v167 offset:3072
	ds_read_b128 v[232:235], v168
	v_mfma_f32_16x16x32_bf16 v[56:59], v[190:193], v[236:239], v[56:59]
	v_mfma_f32_16x16x32_bf16 v[24:27], v[194:197], v[236:239], v[24:27]
	v_mfma_f32_16x16x32_bf16 v[8:11], v[202:205], v[236:239], v[8:11]
	s_waitcnt lgkmcnt(6)
	v_mfma_f32_16x16x32_bf16 v[80:83], v[186:189], v[240:243], v[80:83]
	ds_read_b128 v[236:239], v168 offset:1024
	v_mfma_f32_16x16x32_bf16 v[52:55], v[190:193], v[240:243], v[52:55]
	v_mfma_f32_16x16x32_bf16 v[20:23], v[194:197], v[240:243], v[20:23]
	v_mfma_f32_16x16x32_bf16 v[4:7], v[202:205], v[240:243], v[4:7]
	s_waitcnt lgkmcnt(6)
	v_mfma_f32_16x16x32_bf16 v[72:75], v[186:189], v[244:247], v[72:75]
	ds_read_b128 v[240:243], v168 offset:2048
	v_mfma_f32_16x16x32_bf16 v[48:51], v[190:193], v[244:247], v[48:51]
	v_mfma_f32_16x16x32_bf16 v[16:19], v[194:197], v[244:247], v[16:19]
	v_mfma_f32_16x16x32_bf16 v[0:3], v[202:205], v[244:247], v[0:3]
	ds_read_b128 v[244:247], v168 offset:3072
	s_waitcnt vmcnt(4)
	s_barrier
	v_add_u32_e32 v167, 0x10000, v147
	v_or_b32_e32 v168, 0x10000, v149
	v_add_u32_e32 v169, 0x10400, v149
	v_add_u32_e32 v170, 0x10800, v149
	v_add_u32_e32 v172, 0x10c00, v149
	v_readfirstlane_b32 s11, v155
	v_lshl_add_u64 v[174:175], v[144:145], 0, s[2:3]
	s_mov_b32 m0, s11
	v_readfirstlane_b32 s11, v156
	s_waitcnt lgkmcnt(3)
	v_mfma_f32_16x16x32_bf16 v[124:127], v[216:219], v[232:235], v[124:127]
	v_lshl_add_u64 v[178:179], v[142:143], 0, s[2:3]
	v_mfma_f32_16x16x32_bf16 v[108:111], v[220:223], v[232:235], v[108:111]
	v_mfma_f32_16x16x32_bf16 v[88:91], v[224:227], v[232:235], v[88:91]
	global_load_lds_dwordx4 v[174:175], off
	v_lshl_add_u64 v[174:175], v[144:145], 0, s[52:53]
	s_mov_b32 m0, s11
	v_readfirstlane_b32 s11, v157
	v_mfma_f32_16x16x32_bf16 v[44:47], v[228:231], v[232:235], v[44:47]
	s_waitcnt lgkmcnt(2)
	v_mfma_f32_16x16x32_bf16 v[120:123], v[216:219], v[236:239], v[120:123]
	ds_read_b128 v[232:235], v168 offset:4096
	v_mfma_f32_16x16x32_bf16 v[104:107], v[220:223], v[236:239], v[104:107]
	global_load_lds_dwordx4 v[174:175], off
	s_mov_b32 m0, s11
	v_readfirstlane_b32 s11, v158
	v_lshl_add_u64 v[174:175], v[142:143], 0, s[52:53]
	v_mfma_f32_16x16x32_bf16 v[76:79], v[224:227], v[236:239], v[76:79]
	v_mfma_f32_16x16x32_bf16 v[40:43], v[228:231], v[236:239], v[40:43]
	s_waitcnt lgkmcnt(2)
	v_mfma_f32_16x16x32_bf16 v[116:119], v[216:219], v[240:243], v[116:119]
	ds_read_b128 v[236:239], v168 offset:5120
	global_load_lds_dwordx4 v[178:179], off
	s_mov_b32 m0, s11
	v_mfma_f32_16x16x32_bf16 v[100:103], v[220:223], v[240:243], v[100:103]
	v_mfma_f32_16x16x32_bf16 v[68:71], v[224:227], v[240:243], v[68:71]
	v_mfma_f32_16x16x32_bf16 v[36:39], v[228:231], v[240:243], v[36:39]
	global_load_lds_dwordx4 v[174:175], off
	s_waitcnt lgkmcnt(2)
	v_mfma_f32_16x16x32_bf16 v[112:115], v[216:219], v[244:247], v[112:115]
	ds_read_b128 v[240:243], v168 offset:6144
	v_mfma_f32_16x16x32_bf16 v[96:99], v[220:223], v[244:247], v[96:99]
	v_mfma_f32_16x16x32_bf16 v[64:67], v[224:227], v[244:247], v[64:67]
	v_mfma_f32_16x16x32_bf16 v[32:35], v[228:231], v[244:247], v[32:35]
	v_add_u32_e32 v173, 0x11000, v149
	v_add_u32_e32 v174, 0x11400, v149
	v_add_u32_e32 v175, 0x11800, v149
	v_add_u32_e32 v178, 0x11c00, v149
	v_add_u32_e32 v167, 0x10000, v147
	v_or_b32_e32 v168, 0x10000, v149
	s_waitcnt lgkmcnt(2)
	v_mfma_f32_16x16x32_bf16 v[92:95], v[216:219], v[232:235], v[92:95]
	ds_read_b128 v[244:247], v168 offset:7168
	v_mfma_f32_16x16x32_bf16 v[60:63], v[220:223], v[232:235], v[60:63]
	ds_read_b128 v[186:189], v167 offset:32768
	v_mfma_f32_16x16x32_bf16 v[28:31], v[224:227], v[232:235], v[28:31]
	ds_read_b128 v[190:193], v167 offset:33792
	v_mfma_f32_16x16x32_bf16 v[12:15], v[228:231], v[232:235], v[12:15]
	ds_read_b128 v[194:197], v167 offset:34816
	s_waitcnt lgkmcnt(5)
	v_mfma_f32_16x16x32_bf16 v[84:87], v[216:219], v[236:239], v[84:87]
	ds_read_b128 v[202:205], v167 offset:35840
	ds_read_b128 v[232:235], v168 offset:32768
	v_mfma_f32_16x16x32_bf16 v[56:59], v[220:223], v[236:239], v[56:59]
	v_mfma_f32_16x16x32_bf16 v[24:27], v[224:227], v[236:239], v[24:27]
	v_mfma_f32_16x16x32_bf16 v[8:11], v[228:231], v[236:239], v[8:11]
	s_waitcnt lgkmcnt(6)
	v_mfma_f32_16x16x32_bf16 v[80:83], v[216:219], v[240:243], v[80:83]
	ds_read_b128 v[236:239], v168 offset:33792
	v_mfma_f32_16x16x32_bf16 v[52:55], v[220:223], v[240:243], v[52:55]
	v_mfma_f32_16x16x32_bf16 v[20:23], v[224:227], v[240:243], v[20:23]
	v_mfma_f32_16x16x32_bf16 v[4:7], v[228:231], v[240:243], v[4:7]
	s_waitcnt lgkmcnt(6)
	v_mfma_f32_16x16x32_bf16 v[72:75], v[216:219], v[244:247], v[72:75]
	ds_read_b128 v[240:243], v168 offset:34816
	v_mfma_f32_16x16x32_bf16 v[48:51], v[220:223], v[244:247], v[48:51]
	v_mfma_f32_16x16x32_bf16 v[16:19], v[224:227], v[244:247], v[16:19]
	v_mfma_f32_16x16x32_bf16 v[0:3], v[228:231], v[244:247], v[0:3]
	ds_read_b128 v[244:247], v168 offset:35840
	s_waitcnt vmcnt(4)
	s_barrier
; #define BIG_SYNC(N)                                              \
;   asm volatile("s_waitcnt vmcnt(%0)" ::"n"(N) : "memory");       \
;   __builtin_amdgcn_s_barrier();                                  \
;   asm volatile("" ::: "memory");                                 \
;   __builtin_amdgcn_sched_barrier(0);
; template <int NK, bool BNT = false> ...
;     ...
;   auto kstep = [&](int T, int cur, int nxt, bool do_stage) {
;     const unsigned char* sa = smem + cur * BIG_STAGE;
;     bf16x8 af[4], bfr[4];
; #pragma unroll
;     for (int m = 0; m < 4; ++m) af[m] = *reinterpret_cast<const bf16x8*>(sa + aoff + m * 1024);
; #pragma unroll
;     for (int n = 0; n < 4; ++n) bfr[n] = *reinterpret_cast<const bf16x8*>(sa + boff + n * 1024);
;     __builtin_amdgcn_sched_barrier(0);
;     if (do_stage) stage(T + 3, nxt);
; #pragma unroll
;     for (int m = 0; m < 4; ++m)
; #pragma unroll
;       for (int n = 0; n < 4; ++n) acc[m][n] = __builtin_amdgcn_mfma_f32_16x16x32_bf16(af[m], bfr[n], acc[m][n], 0, 0, 0);
;     if (do_stage) {
; #pragma unroll
;       for (int q = 0; q < NG; ++q) {
;         __builtin_amdgcn_sched_group_barrier(0x008, 3, 0);
;         __builtin_amdgcn_sched_group_barrier(0x010, 1, 0);
;       }
;       __builtin_amdgcn_sched_group_barrier(0x008, 16 - 3 * NG, 0);
;     }
;     __builtin_amdgcn_sched_barrier(0);
; #pragma unroll
;     for (int n = 0; n < 4; ++n) bfr[n] = *reinterpret_cast<const bf16x8*>(sa + boff + (4 + n) * 1024);
; #pragma unroll
;     for (int m = 0; m < 4; ++m)
; #pragma unroll
;       for (int n = 0; n < 4; ++n)
;         acc[m][4 + n] = __builtin_amdgcn_mfma_f32_16x16x32_bf16(af[m], bfr[n], acc[m][4 + n], 0, 0, 0);
;     __builtin_amdgcn_sched_barrier(0);
;   };
;     ...
;   stage(0, 0);
;   stage(1, 1);
;   stage(2, 2);
;   for (int it = 0; it < NK / 4 - 1; ++it) {
;     const int t = it * 4;
;     BIG_SYNC(2 * NG); kstep(t, 0, 3, true);
;     BIG_SYNC(2 * NG); kstep(t + 1, 1, 0, true);
;     BIG_SYNC(2 * NG); kstep(t + 2, 2, 1, true);
;     BIG_SYNC(2 * NG); kstep(t + 3, 3, 2, true);
;   }
;   BIG_SYNC(2 * NG); kstep(NK - 4, 0, 3, true);
;   BIG_SYNC(2 * NG); kstep(NK - 3, 1, 0, false);
;   BIG_SYNC(NG);     kstep(NK - 2, 2, 0, false);
;   BIG_SYNC(0);      kstep(NK - 1, 3, 0, false);
	v_add_u32_e32 v176, 0x18000, v147
	v_or_b32_e32 v179, 0x18000, v149
	v_add_u32_e32 v180, 0x18400, v149
	v_add_u32_e32 v181, 0x18800, v149
	v_add_u32_e32 v182, 0x18c00, v149
	v_readfirstlane_b32 s11, v159
	v_lshl_add_u64 v[248:249], v[144:145], 0, s[54:55]
	s_mov_b32 m0, s11
	v_readfirstlane_b32 s11, v160
	v_lshl_add_u64 v[144:145], v[144:145], 0, s[56:57]
	s_waitcnt lgkmcnt(3)
	v_mfma_f32_16x16x32_bf16 v[124:127], v[186:189], v[232:235], v[124:127]
	v_lshl_add_u64 v[250:251], v[142:143], 0, s[54:55]
	v_lshl_add_u64 v[142:143], v[142:143], 0, s[56:57]
	v_mfma_f32_16x16x32_bf16 v[108:111], v[190:193], v[232:235], v[108:111]
	v_mfma_f32_16x16x32_bf16 v[88:91], v[194:197], v[232:235], v[88:91]
	global_load_lds_dwordx4 v[248:249], off
	s_mov_b32 m0, s11
	v_readfirstlane_b32 s11, v161
	v_mfma_f32_16x16x32_bf16 v[44:47], v[202:205], v[232:235], v[44:47]
	s_waitcnt lgkmcnt(2)
	v_mfma_f32_16x16x32_bf16 v[120:123], v[186:189], v[236:239], v[120:123]
	ds_read_b128 v[232:235], v168 offset:36864
	v_mfma_f32_16x16x32_bf16 v[104:107], v[190:193], v[236:239], v[104:107]
	global_load_lds_dwordx4 v[144:145], off
	s_mov_b32 m0, s11
	v_readfirstlane_b32 s11, v162
	v_mfma_f32_16x16x32_bf16 v[76:79], v[194:197], v[236:239], v[76:79]
	v_mfma_f32_16x16x32_bf16 v[40:43], v[202:205], v[236:239], v[40:43]
	s_waitcnt lgkmcnt(2)
	v_mfma_f32_16x16x32_bf16 v[116:119], v[186:189], v[240:243], v[116:119]
	ds_read_b128 v[236:239], v168 offset:37888
	global_load_lds_dwordx4 v[250:251], off
	s_mov_b32 m0, s11
	v_mfma_f32_16x16x32_bf16 v[100:103], v[190:193], v[240:243], v[100:103]
	v_mfma_f32_16x16x32_bf16 v[68:71], v[194:197], v[240:243], v[68:71]
	v_mfma_f32_16x16x32_bf16 v[36:39], v[202:205], v[240:243], v[36:39]
	global_load_lds_dwordx4 v[142:143], off
	s_waitcnt lgkmcnt(2)
	v_mfma_f32_16x16x32_bf16 v[112:115], v[186:189], v[244:247], v[112:115]
	ds_read_b128 v[240:243], v168 offset:38912
	v_mfma_f32_16x16x32_bf16 v[96:99], v[190:193], v[244:247], v[96:99]
	v_mfma_f32_16x16x32_bf16 v[64:67], v[194:197], v[244:247], v[64:67]
	v_mfma_f32_16x16x32_bf16 v[32:35], v[202:205], v[244:247], v[32:35]
	v_add_u32_e32 v142, 0x19000, v149
	v_add_u32_e32 v143, 0x19400, v149
	v_add_u32_e32 v144, 0x19800, v149
	v_add_u32_e32 v145, 0x19c00, v149
	s_waitcnt lgkmcnt(2)
	v_mfma_f32_16x16x32_bf16 v[92:95], v[186:189], v[232:235], v[92:95]
	ds_read_b128 v[244:247], v168 offset:39936
	v_mfma_f32_16x16x32_bf16 v[60:63], v[190:193], v[232:235], v[60:63]
	ds_read_b128 v[216:219], v147
	v_mfma_f32_16x16x32_bf16 v[28:31], v[194:197], v[232:235], v[28:31]
	ds_read_b128 v[220:223], v147 offset:1024
	v_mfma_f32_16x16x32_bf16 v[12:15], v[202:205], v[232:235], v[12:15]
	ds_read_b128 v[224:227], v147 offset:2048
	s_waitcnt lgkmcnt(5)
	v_mfma_f32_16x16x32_bf16 v[84:87], v[186:189], v[236:239], v[84:87]
	ds_read_b128 v[228:231], v147 offset:3072
	ds_read_b128 v[232:235], v148 offset:16384
	v_mfma_f32_16x16x32_bf16 v[56:59], v[190:193], v[236:239], v[56:59]
	v_mfma_f32_16x16x32_bf16 v[24:27], v[194:197], v[236:239], v[24:27]
	v_mfma_f32_16x16x32_bf16 v[8:11], v[202:205], v[236:239], v[8:11]
	s_waitcnt lgkmcnt(6)
	v_mfma_f32_16x16x32_bf16 v[80:83], v[186:189], v[240:243], v[80:83]
	ds_read_b128 v[236:239], v148 offset:17408
	v_mfma_f32_16x16x32_bf16 v[52:55], v[190:193], v[240:243], v[52:55]
	v_mfma_f32_16x16x32_bf16 v[20:23], v[194:197], v[240:243], v[20:23]
	v_mfma_f32_16x16x32_bf16 v[4:7], v[202:205], v[240:243], v[4:7]
	s_waitcnt lgkmcnt(6)
	v_mfma_f32_16x16x32_bf16 v[72:75], v[186:189], v[244:247], v[72:75]
	ds_read_b128 v[240:243], v148 offset:18432
	v_mfma_f32_16x16x32_bf16 v[48:51], v[190:193], v[244:247], v[48:51]
	v_mfma_f32_16x16x32_bf16 v[16:19], v[194:197], v[244:247], v[16:19]
	v_mfma_f32_16x16x32_bf16 v[0:3], v[202:205], v[244:247], v[0:3]
	ds_read_b128 v[244:247], v148 offset:19456
	s_add_u32 s12, s12, 0x8000
	s_addc_u32 s13, s13, 0
	s_cmp_lg_u32 s12, 0x38000
	s_cbranch_scc1 .LBB0_290
	s_waitcnt vmcnt(4)
	s_barrier
	s_mov_b64 s[12:13], 0x3e000
	v_readfirstlane_b32 s11, v163
	v_lshl_add_u64 v[198:199], v[136:137], 0, s[12:13]
	v_lshl_add_u64 v[200:201], v[134:135], 0, s[12:13]
	s_mov_b32 m0, s11
	s_mov_b64 s[12:13], 0x7e000
	v_readfirstlane_b32 s11, v164
	v_lshl_add_u64 v[136:137], v[136:137], 0, s[12:13]
	s_waitcnt lgkmcnt(3)
	v_mfma_f32_16x16x32_bf16 v[124:127], v[216:219], v[232:235], v[124:127]
	v_lshl_add_u64 v[134:135], v[134:135], 0, s[12:13]
	v_mfma_f32_16x16x32_bf16 v[108:111], v[220:223], v[232:235], v[108:111]
	v_mfma_f32_16x16x32_bf16 v[88:91], v[224:227], v[232:235], v[88:91]
	global_load_lds_dwordx4 v[198:199], off
	s_mov_b32 m0, s11
	v_readfirstlane_b32 s11, v165
	v_mfma_f32_16x16x32_bf16 v[44:47], v[228:231], v[232:235], v[44:47]
	s_waitcnt lgkmcnt(2)
	v_mfma_f32_16x16x32_bf16 v[120:123], v[216:219], v[236:239], v[120:123]
	ds_read_b128 v[232:235], v148 offset:20480
	v_mfma_f32_16x16x32_bf16 v[104:107], v[220:223], v[236:239], v[104:107]
	global_load_lds_dwordx4 v[136:137], off
	s_mov_b32 m0, s11
	v_readfirstlane_b32 s11, v166
	v_mfma_f32_16x16x32_bf16 v[76:79], v[224:227], v[236:239], v[76:79]
	v_mfma_f32_16x16x32_bf16 v[40:43], v[228:231], v[236:239], v[40:43]
	s_waitcnt lgkmcnt(2)
	v_mfma_f32_16x16x32_bf16 v[116:119], v[216:219], v[240:243], v[116:119]
	ds_read_b128 v[236:239], v148 offset:21504
	global_load_lds_dwordx4 v[200:201], off
	s_mov_b32 m0, s11
	v_mfma_f32_16x16x32_bf16 v[100:103], v[220:223], v[240:243], v[100:103]
	v_mfma_f32_16x16x32_bf16 v[68:71], v[224:227], v[240:243], v[68:71]
	v_mfma_f32_16x16x32_bf16 v[36:39], v[228:231], v[240:243], v[36:39]
	global_load_lds_dwordx4 v[134:135], off
	s_waitcnt lgkmcnt(2)
; #define BIG_SYNC(N)                                              \
;   asm volatile("s_waitcnt vmcnt(%0)" ::"n"(N) : "memory");       \
;   __builtin_amdgcn_s_barrier();                                  \
;   asm volatile("" ::: "memory");                                 \
;   __builtin_amdgcn_sched_barrier(0);
; template <int NK, bool BNT = false> ...
;     ...
;   auto kstep = [&](int T, int cur, int nxt, bool do_stage) {
;     const unsigned char* sa = smem + cur * BIG_STAGE;
;     bf16x8 af[4], bfr[4];
; #pragma unroll
;     for (int m = 0; m < 4; ++m) af[m] = *reinterpret_cast<const bf16x8*>(sa + aoff + m * 1024);
; #pragma unroll
;     for (int n = 0; n < 4; ++n) bfr[n] = *reinterpret_cast<const bf16x8*>(sa + boff + n * 1024);
;     __builtin_amdgcn_sched_barrier(0);
;     if (do_stage) stage(T + 3, nxt);
; #pragma unroll
;     for (int m = 0; m < 4; ++m)
; #pragma unroll
;       for (int n = 0; n < 4; ++n) acc[m][n] = __builtin_amdgcn_mfma_f32_16x16x32_bf16(af[m], bfr[n], acc[m][n], 0, 0, 0);
;     if (do_stage) {
; #pragma unroll
;       for (int q = 0; q < NG; ++q) {
;         __builtin_amdgcn_sched_group_barrier(0x008, 3, 0);
;         __builtin_amdgcn_sched_group_barrier(0x010, 1, 0);
;       }
;       __builtin_amdgcn_sched_group_barrier(0x008, 16 - 3 * NG, 0);
;     }
;     __builtin_amdgcn_sched_barrier(0);
; #pragma unroll
;     for (int n = 0; n < 4; ++n) bfr[n] = *reinterpret_cast<const bf16x8*>(sa + boff + (4 + n) * 1024);
; #pragma unroll
;     for (int m = 0; m < 4; ++m)
; #pragma unroll
;       for (int n = 0; n < 4; ++n)
;         acc[m][4 + n] = __builtin_amdgcn_mfma_f32_16x16x32_bf16(af[m], bfr[n], acc[m][4 + n], 0, 0, 0);
;     __builtin_amdgcn_sched_barrier(0);
;   };
;     ...
;   BIG_SYNC(2 * NG); kstep(NK - 4, 0, 3, true);
;   BIG_SYNC(2 * NG); kstep(NK - 3, 1, 0, false);
;   BIG_SYNC(NG);     kstep(NK - 2, 2, 0, false);
;   BIG_SYNC(0);      kstep(NK - 1, 3, 0, false);
	v_mfma_f32_16x16x32_bf16 v[112:115], v[216:219], v[244:247], v[112:115]
	ds_read_b128 v[240:243], v148 offset:22528
	v_mfma_f32_16x16x32_bf16 v[96:99], v[220:223], v[244:247], v[96:99]
	v_mfma_f32_16x16x32_bf16 v[64:67], v[224:227], v[244:247], v[64:67]
	v_mfma_f32_16x16x32_bf16 v[32:35], v[228:231], v[244:247], v[32:35]
	s_waitcnt lgkmcnt(2)
	v_mfma_f32_16x16x32_bf16 v[92:95], v[216:219], v[232:235], v[92:95]
	ds_read_b128 v[244:247], v148 offset:23552
	v_mfma_f32_16x16x32_bf16 v[60:63], v[220:223], v[232:235], v[60:63]
	ds_read_b128 v[186:189], v147 offset:32768
	v_mfma_f32_16x16x32_bf16 v[28:31], v[224:227], v[232:235], v[28:31]
	ds_read_b128 v[190:193], v147 offset:33792
	v_mfma_f32_16x16x32_bf16 v[12:15], v[228:231], v[232:235], v[12:15]
	ds_read_b128 v[194:197], v147 offset:34816
	s_waitcnt lgkmcnt(5)
	v_mfma_f32_16x16x32_bf16 v[84:87], v[216:219], v[236:239], v[84:87]
	ds_read_b128 v[202:205], v147 offset:35840
	ds_read_b128 v[232:235], v148 offset:49152
	v_mfma_f32_16x16x32_bf16 v[56:59], v[220:223], v[236:239], v[56:59]
	v_mfma_f32_16x16x32_bf16 v[24:27], v[224:227], v[236:239], v[24:27]
	v_mfma_f32_16x16x32_bf16 v[8:11], v[228:231], v[236:239], v[8:11]
	s_waitcnt lgkmcnt(6)
	v_mfma_f32_16x16x32_bf16 v[80:83], v[216:219], v[240:243], v[80:83]
	ds_read_b128 v[236:239], v148 offset:50176
	v_mfma_f32_16x16x32_bf16 v[52:55], v[220:223], v[240:243], v[52:55]
	v_mfma_f32_16x16x32_bf16 v[20:23], v[224:227], v[240:243], v[20:23]
	v_mfma_f32_16x16x32_bf16 v[4:7], v[228:231], v[240:243], v[4:7]
	s_waitcnt lgkmcnt(6)
	v_mfma_f32_16x16x32_bf16 v[72:75], v[216:219], v[244:247], v[72:75]
	ds_read_b128 v[240:243], v148 offset:51200
	v_mfma_f32_16x16x32_bf16 v[48:51], v[220:223], v[244:247], v[48:51]
	v_mfma_f32_16x16x32_bf16 v[16:19], v[224:227], v[244:247], v[16:19]
	v_mfma_f32_16x16x32_bf16 v[0:3], v[228:231], v[244:247], v[0:3]
	ds_read_b128 v[244:247], v148 offset:52224
	s_waitcnt vmcnt(4)
	s_barrier
	s_waitcnt lgkmcnt(3)
	v_mfma_f32_16x16x32_bf16 v[124:127], v[186:189], v[232:235], v[124:127]
	v_mfma_f32_16x16x32_bf16 v[108:111], v[190:193], v[232:235], v[108:111]
	v_mfma_f32_16x16x32_bf16 v[88:91], v[194:197], v[232:235], v[88:91]
	v_mfma_f32_16x16x32_bf16 v[44:47], v[202:205], v[232:235], v[44:47]
	s_waitcnt lgkmcnt(2)
	v_mfma_f32_16x16x32_bf16 v[120:123], v[186:189], v[236:239], v[120:123]
	ds_read_b128 v[232:235], v148 offset:53248
	v_mfma_f32_16x16x32_bf16 v[104:107], v[190:193], v[236:239], v[104:107]
	v_mfma_f32_16x16x32_bf16 v[76:79], v[194:197], v[236:239], v[76:79]
	v_mfma_f32_16x16x32_bf16 v[40:43], v[202:205], v[236:239], v[40:43]
	s_waitcnt lgkmcnt(2)
	v_mfma_f32_16x16x32_bf16 v[116:119], v[186:189], v[240:243], v[116:119]
	ds_read_b128 v[236:239], v148 offset:54272
	v_mfma_f32_16x16x32_bf16 v[100:103], v[190:193], v[240:243], v[100:103]
	v_mfma_f32_16x16x32_bf16 v[68:71], v[194:197], v[240:243], v[68:71]
	v_mfma_f32_16x16x32_bf16 v[36:39], v[202:205], v[240:243], v[36:39]
	s_waitcnt lgkmcnt(2)
	v_mfma_f32_16x16x32_bf16 v[112:115], v[186:189], v[244:247], v[112:115]
	ds_read_b128 v[240:243], v148 offset:55296
	v_mfma_f32_16x16x32_bf16 v[96:99], v[190:193], v[244:247], v[96:99]
	v_mfma_f32_16x16x32_bf16 v[64:67], v[194:197], v[244:247], v[64:67]
	v_mfma_f32_16x16x32_bf16 v[32:35], v[202:205], v[244:247], v[32:35]
	s_waitcnt lgkmcnt(2)
	v_mfma_f32_16x16x32_bf16 v[92:95], v[186:189], v[232:235], v[92:95]
	ds_read_b128 v[244:247], v148 offset:56320
	v_mfma_f32_16x16x32_bf16 v[60:63], v[190:193], v[232:235], v[60:63]
	v_mfma_f32_16x16x32_bf16 v[28:31], v[194:197], v[232:235], v[28:31]
	v_mfma_f32_16x16x32_bf16 v[12:15], v[202:205], v[232:235], v[12:15]
	s_waitcnt lgkmcnt(2)
	v_mfma_f32_16x16x32_bf16 v[84:87], v[186:189], v[236:239], v[84:87]
	v_mfma_f32_16x16x32_bf16 v[56:59], v[190:193], v[236:239], v[56:59]
	v_mfma_f32_16x16x32_bf16 v[24:27], v[194:197], v[236:239], v[24:27]
	v_mfma_f32_16x16x32_bf16 v[8:11], v[202:205], v[236:239], v[8:11]
	s_waitcnt lgkmcnt(1)
	v_mfma_f32_16x16x32_bf16 v[80:83], v[186:189], v[240:243], v[80:83]
	v_mfma_f32_16x16x32_bf16 v[52:55], v[190:193], v[240:243], v[52:55]
	v_mfma_f32_16x16x32_bf16 v[20:23], v[194:197], v[240:243], v[20:23]
	v_mfma_f32_16x16x32_bf16 v[4:7], v[202:205], v[240:243], v[4:7]
	s_waitcnt lgkmcnt(0)
	v_mfma_f32_16x16x32_bf16 v[72:75], v[186:189], v[244:247], v[72:75]
	v_mfma_f32_16x16x32_bf16 v[48:51], v[190:193], v[244:247], v[48:51]
	v_mfma_f32_16x16x32_bf16 v[16:19], v[194:197], v[244:247], v[16:19]
	v_mfma_f32_16x16x32_bf16 v[0:3], v[202:205], v[244:247], v[0:3]
	v_mov_b32_e32 v186, 0xf149f2ca
	v_mov_b32_e32 v187, 0x3c0881c4
	v_mov_b32_e32 v188, 0xbab64f3b
	v_mov_b32_e32 v189, 0x24800
	v_mov_b32_e32 v190, 1
	v_mov_b32_e32 v191, 0x24804
	v_mov_b32_e32 v192, 0xfcf
	v_mov_b32_e32 v193, 0x7cf
	v_mov_b32_e32 v194, 0xfdf
	v_mov_b32_e32 v195, 0x7df
	v_mov_b32_e32 v196, 0xfef
	v_mov_b32_e32 v197, 0x7ef
	v_mov_b32_e32 v198, 0xfff
	v_mov_b32_e32 v199, 0x7ff
	v_mov_b32_e32 v200, 0x20000
	v_mov_b32_e32 v201, 0xf8f
	v_mov_b32_e32 v202, 0x78f
	v_mov_b32_e32 v203, 0xf9f
	v_mov_b32_e32 v204, 0x79f
	v_mov_b32_e32 v205, 0xfaf
	s_waitcnt vmcnt(4)
	s_barrier
; __device__ __forceinline__ int widen_off(int fq) { return ((fq & 1) << 4) + ((fq >> 1) << 3); }
; #define BIG_SYNC(N)                                              \
;   asm volatile("s_waitcnt vmcnt(%0)" ::"n"(N) : "memory");       \
;   __builtin_amdgcn_s_barrier();                                  \
;   asm volatile("" ::: "memory");                                 \
;   __builtin_amdgcn_sched_barrier(0);
; template <int NK, bool BNT = false> ...
;     ...
;   BIG_SYNC(NG);     kstep(NK - 2, 2, 0, false);
;   BIG_SYNC(0);      kstep(NK - 1, 3, 0, false);
; template <int MODE, int NSUB>
; __device__ __forceinline__ void epilogue(const Params& p, int layer, f32x4 (&acc)[4][NSUB], int tm, int tn, int g,
;                                          const float* s_rstd, const int tid_in) {
;     ...
;   } else if constexpr (MODE == EPI_UP) {
;     const int woff = widen_off(fq);
; #pragma unroll
;     for (int n = 0; n < NSUB; ++n) {
;       const int nl = wc * (NSUB * 16) + n * 16 + fr;
;       const int t = tn * (NSUB * 32) + nl;
;       const float rs = s_rstd[nl];
; #pragma unroll
;       for (int mp = 0; mp < 2; ++mp) {
	ds_read_b128 v[134:137], v167
	ds_read_b128 v[138:141], v167 offset:1024
	ds_read_b128 v[154:157], v167 offset:2048
	ds_read_b128 v[158:161], v167 offset:3072
	ds_read_b128 v[162:165], v168
	ds_read_b128 v[166:169], v169
	ds_read_b128 v[216:219], v170
	ds_read_b128 v[220:223], v172
	s_waitcnt lgkmcnt(0)
	v_mfma_f32_16x16x32_bf16 v[124:127], v[134:137], v[162:165], v[124:127]
	v_mfma_f32_16x16x32_bf16 v[120:123], v[134:137], v[166:169], v[120:123]
	v_mfma_f32_16x16x32_bf16 v[116:119], v[134:137], v[216:219], v[116:119]
	v_mfma_f32_16x16x32_bf16 v[112:115], v[134:137], v[220:223], v[112:115]
	v_mfma_f32_16x16x32_bf16 v[224:227], v[138:141], v[162:165], v[108:111]
	v_mfma_f32_16x16x32_bf16 v[104:107], v[138:141], v[166:169], v[104:107]
	v_mfma_f32_16x16x32_bf16 v[100:103], v[138:141], v[216:219], v[100:103]
	v_mfma_f32_16x16x32_bf16 v[96:99], v[138:141], v[220:223], v[96:99]
	v_mfma_f32_16x16x32_bf16 v[228:231], v[154:157], v[162:165], v[88:91]
	v_mfma_f32_16x16x32_bf16 v[232:235], v[154:157], v[166:169], v[76:79]
	v_mfma_f32_16x16x32_bf16 v[68:71], v[154:157], v[216:219], v[68:71]
	v_mfma_f32_16x16x32_bf16 v[64:67], v[154:157], v[220:223], v[64:67]
	v_mfma_f32_16x16x32_bf16 v[44:47], v[158:161], v[162:165], v[44:47]
	v_mfma_f32_16x16x32_bf16 v[40:43], v[158:161], v[166:169], v[40:43]
	v_mfma_f32_16x16x32_bf16 v[36:39], v[158:161], v[216:219], v[36:39]
	v_mfma_f32_16x16x32_bf16 v[32:35], v[158:161], v[220:223], v[32:35]
	ds_read_b128 v[76:79], v173
	ds_read_b128 v[88:91], v174
	s_waitcnt lgkmcnt(0)
	v_mfma_f32_16x16x32_bf16 v[162:165], v[134:137], v[76:79], v[92:95]
	s_nop 2
	ds_read_b128 v[92:95], v178
	v_mfma_f32_16x16x32_bf16 v[166:169], v[134:137], v[88:91], v[84:87]
	s_nop 2
	ds_read_b128 v[84:87], v175
	s_waitcnt lgkmcnt(0)
	v_mfma_f32_16x16x32_bf16 v[172:175], v[134:137], v[84:87], v[80:83]
	v_mfma_f32_16x16x32_bf16 v[134:137], v[134:137], v[92:95], v[72:75]
	v_mfma_f32_16x16x32_bf16 v[216:219], v[138:141], v[76:79], v[60:63]
	v_mfma_f32_16x16x32_bf16 v[220:223], v[138:141], v[88:91], v[56:59]
	v_mfma_f32_16x16x32_bf16 v[52:55], v[138:141], v[84:87], v[52:55]
	v_mfma_f32_16x16x32_bf16 v[48:51], v[138:141], v[92:95], v[48:51]
	v_mfma_f32_16x16x32_bf16 v[138:141], v[154:157], v[76:79], v[28:31]
	v_mfma_f32_16x16x32_bf16 v[236:239], v[154:157], v[88:91], v[24:27]
	v_mfma_f32_16x16x32_bf16 v[20:23], v[154:157], v[84:87], v[20:23]
	v_mfma_f32_16x16x32_bf16 v[16:19], v[154:157], v[92:95], v[16:19]
	v_mfma_f32_16x16x32_bf16 v[154:157], v[158:161], v[76:79], v[12:15]
	v_mfma_f32_16x16x32_bf16 v[240:243], v[158:161], v[88:91], v[8:11]
	v_mfma_f32_16x16x32_bf16 v[244:247], v[158:161], v[84:87], v[4:7]
	v_mfma_f32_16x16x32_bf16 v[0:3], v[158:161], v[92:95], v[0:3]
	s_waitcnt vmcnt(0)
	s_barrier
	s_nop 0
	ds_read_b128 v[4:7], v176
	ds_read_b128 v[8:11], v176 offset:1024
	ds_read_b128 v[158:161], v176 offset:2048
	ds_read_b128 v[248:251], v176 offset:3072
	ds_read_b128 v[12:15], v179
	ds_read_b128 v[24:27], v180
	ds_read_b128 v[28:31], v181
	ds_read_b128 v[56:59], v182
	s_waitcnt lgkmcnt(0)
	v_mfma_f32_16x16x32_bf16 v[124:127], v[4:7], v[12:15], v[124:127]
	v_mfma_f32_16x16x32_bf16 v[108:111], v[4:7], v[24:27], v[120:123]
	v_mfma_f32_16x16x32_bf16 v[92:95], v[4:7], v[28:31], v[116:119]
	v_mfma_f32_16x16x32_bf16 v[76:79], v[4:7], v[56:59], v[112:115]
	v_mfma_f32_16x16x32_bf16 v[112:115], v[8:11], v[12:15], v[224:227]
	v_mfma_f32_16x16x32_bf16 v[104:107], v[8:11], v[24:27], v[104:107]
	v_mfma_f32_16x16x32_bf16 v[88:91], v[8:11], v[28:31], v[100:103]
	v_mfma_f32_16x16x32_bf16 v[72:75], v[8:11], v[56:59], v[96:99]
	v_mfma_f32_16x16x32_bf16 v[120:123], v[158:161], v[12:15], v[228:231]
	v_mfma_f32_16x16x32_bf16 v[100:103], v[158:161], v[24:27], v[232:235]
	v_mfma_f32_16x16x32_bf16 v[84:87], v[158:161], v[28:31], v[68:71]
	v_mfma_f32_16x16x32_bf16 v[68:71], v[158:161], v[56:59], v[64:67]
	v_mfma_f32_16x16x32_bf16 v[178:181], v[248:251], v[12:15], v[44:47]
	v_mfma_f32_16x16x32_bf16 v[96:99], v[248:251], v[24:27], v[40:43]
	v_mfma_f32_16x16x32_bf16 v[80:83], v[248:251], v[28:31], v[36:39]
	v_mfma_f32_16x16x32_bf16 v[64:67], v[248:251], v[56:59], v[32:35]
	s_nop 2
	ds_read_b128 v[32:35], v142
	ds_read_b128 v[116:119], v143
	s_waitcnt lgkmcnt(0)
	v_mfma_f32_16x16x32_bf16 v[60:63], v[4:7], v[32:35], v[162:165]
	s_nop 2
	ds_read_b128 v[162:165], v144
	ds_read_b128 v[142:145], v145
	v_mfma_f32_16x16x32_bf16 v[44:47], v[4:7], v[116:119], v[166:169]
	s_waitcnt lgkmcnt(0)
	v_mfma_f32_16x16x32_bf16 v[28:31], v[4:7], v[162:165], v[172:175]
	v_mfma_f32_16x16x32_bf16 v[12:15], v[4:7], v[142:145], v[134:137]
	v_mfma_f32_16x16x32_bf16 v[56:59], v[8:11], v[32:35], v[216:219]
	v_mfma_f32_16x16x32_bf16 v[40:43], v[8:11], v[116:119], v[220:223]
	v_mfma_f32_16x16x32_bf16 v[24:27], v[8:11], v[162:165], v[52:55]
	v_mfma_f32_16x16x32_bf16 v[8:11], v[8:11], v[142:145], v[48:51]
	v_mfma_f32_16x16x32_bf16 v[52:55], v[158:161], v[32:35], v[138:141]
	v_mfma_f32_16x16x32_bf16 v[36:39], v[158:161], v[116:119], v[236:239]
	v_mfma_f32_16x16x32_bf16 v[20:23], v[158:161], v[162:165], v[20:23]
	v_mfma_f32_16x16x32_bf16 v[4:7], v[158:161], v[142:145], v[16:19]
	v_mfma_f32_16x16x32_bf16 v[48:51], v[248:251], v[32:35], v[154:157]
	v_mfma_f32_16x16x32_bf16 v[32:35], v[248:251], v[116:119], v[240:243]
	v_mfma_f32_16x16x32_bf16 v[16:19], v[248:251], v[162:165], v[244:247]
	v_mfma_f32_16x16x32_bf16 v[0:3], v[248:251], v[142:145], v[0:3]
	v_mov_b32_e32 v116, v215
	s_lshl_b32 s10, s10, 8
	v_and_b32_e32 v117, 16, v116
	v_lshrrev_b32_e32 v118, 2, v116
	v_and_or_b32 v136, v118, 8, v117
	v_lshlrev_b32_e32 v117, 1, v116
	v_and_b32_e32 v119, 15, v116
	v_and_b32_e32 v117, 0x80, v117
	v_lshl_or_b32 v134, s15, 8, v117
	v_or_b32_e32 v117, v117, v119
	v_ashrrev_i32_e32 v116, 1, v116
	v_lshlrev_b32_e32 v118, 2, v117
	v_and_b32_e32 v116, 0xffffffc0, v116
	v_add3_u32 v135, s10, v150, v116
	v_or_b32_e32 v116, 0x20000, v118
	ds_read_b32 v137, v116
	v_lshlrev_b32_e32 v152, 6, v119
	v_or_b32_e32 v119, 0x20040, v118
	v_readlane_b32 s64, v252, 4
	ds_read_b32 v119, v119
	s_waitcnt lgkmcnt(0)
; __device__ __forceinline__ int widen_off(int fq) { return ((fq & 1) << 4) + ((fq >> 1) << 3); }
; template <int MODE, int NSUB>
; __device__ __forceinline__ void epilogue(const Params& p, int layer, f32x4 (&acc)[4][NSUB], int tm, int tn, int g,
;                                          const float* s_rstd, const int tid_in) {
;     ...
;   } else if constexpr (MODE == EPI_UP) {
;     const int woff = widen_off(fq);
; #pragma unroll
;     for (int n = 0; n < NSUB; ++n) {
;       const int nl = wc * (NSUB * 16) + n * 16 + fr;
;       const int t = tn * (NSUB * 32) + nl;
;       const float rs = s_rstd[nl];
; #pragma unroll
;       for (int mp = 0; mp < 2; ++mp) {
;         bf16x4 pk[2];
; #pragma unroll
;         for (int h2 = 0; h2 < 2; ++h2) {
;           const int m = mp * 2 + h2;
;           float v[4];
; #pragma unroll
;           for (int j = 0; j < 4; ++j) {
;             float a = fmaxf(acc[m][n][j] * rs, 0.f);
;             v[j] = a * a;
;           }
;           pk[h2] = pack4(v[0], v[1], v[2], v[3]);
;         }
;         const int f = tm * 128 + wr * 64 + mp * 32 + woff;
;         __builtin_nontemporal_store(widen_pair(pk[0], pk[1]), reinterpret_cast<u32x4*>(p.hm + blk(t, f, 128)));
;       }
;     }
	v_mul_f32_e32 v116, v124, v137
	v_mul_f32_e32 v117, v125, v137
	v_mul_f32_e32 v124, v126, v137
	v_mul_f32_e32 v125, v127, v137
	v_mul_f32_e32 v112, v112, v137
	v_mul_f32_e32 v113, v113, v137
	v_max_f32_e32 v124, 0, v124
	v_max_f32_e32 v125, 0, v125
	v_max_f32_e32 v112, 0, v112
	v_max_f32_e32 v113, 0, v113
	v_mul_f32_e32 v114, v114, v137
	v_mul_f32_e32 v115, v115, v137
	v_pk_mul_f32 v[126:127], v[124:125], v[124:125]
	v_pk_mul_f32 v[112:113], v[112:113], v[112:113]
	v_max_f32_e32 v114, 0, v114
	v_max_f32_e32 v115, 0, v115
	v_cvt_pk_bf16_f32 v125, v126, v127
	v_pk_mul_f32 v[114:115], v[114:115], v[114:115]
	v_cvt_pk_bf16_f32 v126, v112, v113
	v_ashrrev_i32_e32 v112, 5, v135
	v_cvt_pk_bf16_f32 v127, v114, v115
	v_add_u32_e32 v114, v112, v134
	v_ashrrev_i32_e32 v115, 31, v114
	v_lshlrev_b64 v[112:113], 13, v[114:115]
	v_mul_f32_e32 v115, v120, v137
	v_max_f32_e32 v120, 0, v115
	v_mul_f32_e32 v115, v121, v137
	v_max_f32_e32 v121, 0, v115
	v_mul_f32_e32 v115, v122, v137
	v_max_f32_e32 v116, 0, v116
	v_max_f32_e32 v117, 0, v117
	v_max_f32_e32 v122, 0, v115
	v_mul_f32_e32 v115, v123, v137
	v_pk_mul_f32 v[116:117], v[116:117], v[116:117]
	v_readlane_b32 s78, v252, 18
	v_readlane_b32 s79, v252, 19
	v_max_f32_e32 v123, 0, v115
	v_cvt_pk_bf16_f32 v124, v116, v117
	v_lshl_add_u64 v[116:117], s[78:79], 0, v[112:113]
	v_pk_mul_f32 v[120:121], v[120:121], v[120:121]
	v_pk_mul_f32 v[122:123], v[122:123], v[122:123]
	v_mul_f32_e32 v115, v178, v137
	v_lshl_add_u64 v[134:135], v[116:117], 0, v[152:153]
	v_lshlrev_b32_e32 v112, 1, v136
	v_mov_b32_e32 v113, v153
	v_cvt_pk_bf16_f32 v120, v120, v121
	v_cvt_pk_bf16_f32 v121, v122, v123
	v_max_f32_e32 v122, 0, v115
	v_mul_f32_e32 v115, v179, v137
	v_permlane16_swap_b32_e32 v124, v126
	v_permlane16_swap_b32_e32 v125, v127
	v_lshl_add_u64 v[134:135], v[134:135], 0, v[112:113]
	v_max_f32_e32 v123, 0, v115
	v_mul_f32_e32 v115, v180, v137
	global_store_dwordx4 v[134:135], v[124:127], off nt
	v_add_u32_e32 v114, 1, v114
	v_mul_f32_e32 v108, v108, v119
	v_max_f32_e32 v124, 0, v115
	v_mul_f32_e32 v115, v181, v137
	v_mul_f32_e32 v109, v109, v119
	v_mul_f32_e32 v110, v110, v119
	v_mul_f32_e32 v111, v111, v119
	v_mul_f32_e32 v104, v104, v119
	v_mul_f32_e32 v105, v105, v119
	v_max_f32_e32 v125, 0, v115
	v_ashrrev_i32_e32 v115, 31, v114
	v_max_f32_e32 v108, 0, v108
	v_max_f32_e32 v109, 0, v109
	v_max_f32_e32 v110, 0, v110
	v_max_f32_e32 v111, 0, v111
	v_max_f32_e32 v104, 0, v104
	v_max_f32_e32 v105, 0, v105
	v_mul_f32_e32 v100, v100, v119
	v_mul_f32_e32 v101, v101, v119
	v_mul_f32_e32 v102, v102, v119
	v_mul_f32_e32 v103, v103, v119
	v_mul_f32_e32 v96, v96, v119
	v_mul_f32_e32 v97, v97, v119
	v_mul_f32_e32 v98, v98, v119
	v_mul_f32_e32 v99, v99, v119
	v_lshlrev_b64 v[114:115], 13, v[114:115]
	v_pk_mul_f32 v[108:109], v[108:109], v[108:109]
	v_pk_mul_f32 v[110:111], v[110:111], v[110:111]
	v_pk_mul_f32 v[104:105], v[104:105], v[104:105]
	v_max_f32_e32 v100, 0, v100
	v_max_f32_e32 v101, 0, v101
	v_max_f32_e32 v102, 0, v102
	v_max_f32_e32 v103, 0, v103
	v_max_f32_e32 v96, 0, v96
	v_max_f32_e32 v97, 0, v97
	v_max_f32_e32 v98, 0, v98
	v_max_f32_e32 v99, 0, v99
	v_lshl_add_u64 v[114:115], s[78:79], 0, v[114:115]
	v_cvt_pk_bf16_f32 v108, v108, v109
	v_cvt_pk_bf16_f32 v109, v110, v111
	v_cvt_pk_bf16_f32 v110, v104, v105
	v_or_b32_e32 v104, 0x400, v152
	v_mov_b32_e32 v105, v153
	v_pk_mul_f32 v[100:101], v[100:101], v[100:101]
	v_pk_mul_f32 v[102:103], v[102:103], v[102:103]
	v_pk_mul_f32 v[96:97], v[96:97], v[96:97]
	v_pk_mul_f32 v[98:99], v[98:99], v[98:99]
	v_cvt_pk_bf16_f32 v100, v100, v101
	v_cvt_pk_bf16_f32 v101, v102, v103
	v_cvt_pk_bf16_f32 v102, v96, v97
	v_cvt_pk_bf16_f32 v103, v98, v99
	v_lshl_add_u64 v[96:97], v[114:115], 0, v[104:105]
	v_permlane16_swap_b32_e32 v100, v102
	v_permlane16_swap_b32_e32 v101, v103
	v_lshl_add_u64 v[96:97], v[96:97], 0, v[112:113]
	global_store_dwordx4 v[96:97], v[100:103], off nt
	v_or_b32_e32 v96, 0x20080, v118
	ds_read_b32 v96, v96
	v_mul_f32_e32 v106, v106, v119
	v_mul_f32_e32 v107, v107, v119
	v_pk_mul_f32 v[122:123], v[122:123], v[122:123]
	v_pk_mul_f32 v[124:125], v[124:125], v[124:125]
	s_waitcnt lgkmcnt(0)
	v_mul_f32_e32 v92, v92, v96
	v_mul_f32_e32 v93, v93, v96
	v_mul_f32_e32 v94, v94, v96
	v_mul_f32_e32 v95, v95, v96
	v_mul_f32_e32 v88, v88, v96
	v_mul_f32_e32 v89, v89, v96
	v_max_f32_e32 v92, 0, v92
	v_max_f32_e32 v93, 0, v93
	v_max_f32_e32 v94, 0, v94
	v_max_f32_e32 v95, 0, v95
	v_max_f32_e32 v88, 0, v88
	v_max_f32_e32 v89, 0, v89
	v_mul_f32_e32 v84, v84, v96
	v_mul_f32_e32 v85, v85, v96
	v_mul_f32_e32 v86, v86, v96
	v_mul_f32_e32 v87, v87, v96
	v_mul_f32_e32 v80, v80, v96
	v_mul_f32_e32 v81, v81, v96
	v_mul_f32_e32 v82, v82, v96
	v_mul_f32_e32 v83, v83, v96
	v_pk_mul_f32 v[92:93], v[92:93], v[92:93]
	v_pk_mul_f32 v[94:95], v[94:95], v[94:95]
	v_pk_mul_f32 v[88:89], v[88:89], v[88:89]
	v_max_f32_e32 v84, 0, v84
	v_max_f32_e32 v85, 0, v85
	v_max_f32_e32 v86, 0, v86
	v_max_f32_e32 v87, 0, v87
	v_max_f32_e32 v80, 0, v80
	v_max_f32_e32 v81, 0, v81
	v_max_f32_e32 v82, 0, v82
	v_max_f32_e32 v83, 0, v83
	v_cvt_pk_bf16_f32 v92, v92, v93
	v_cvt_pk_bf16_f32 v93, v94, v95
	v_cvt_pk_bf16_f32 v94, v88, v89
	v_or_b32_e32 v88, 0x800, v152
	v_mov_b32_e32 v89, v153
	v_pk_mul_f32 v[84:85], v[84:85], v[84:85]
	v_pk_mul_f32 v[86:87], v[86:87], v[86:87]
	v_pk_mul_f32 v[80:81], v[80:81], v[80:81]
	v_pk_mul_f32 v[82:83], v[82:83], v[82:83]
	v_cvt_pk_bf16_f32 v84, v84, v85
	v_cvt_pk_bf16_f32 v85, v86, v87
	v_cvt_pk_bf16_f32 v86, v80, v81
	v_cvt_pk_bf16_f32 v87, v82, v83
	v_lshl_add_u64 v[80:81], v[114:115], 0, v[88:89]
	v_permlane16_swap_b32_e32 v84, v86
	v_permlane16_swap_b32_e32 v85, v87
	v_lshl_add_u64 v[80:81], v[80:81], 0, v[112:113]
	global_store_dwordx4 v[80:81], v[84:87], off nt
	v_or_b32_e32 v80, 0x200c0, v118
	ds_read_b32 v80, v80
	v_mul_f32_e32 v90, v90, v96
	v_mul_f32_e32 v91, v91, v96
	v_max_f32_e32 v106, 0, v106
	v_max_f32_e32 v107, 0, v107
	s_waitcnt lgkmcnt(0)
; __device__ __forceinline__ int widen_off(int fq) { return ((fq & 1) << 4) + ((fq >> 1) << 3); }
; template <int MODE, int NSUB>
; __device__ __forceinline__ void epilogue(const Params& p, int layer, f32x4 (&acc)[4][NSUB], int tm, int tn, int g,
;                                          const float* s_rstd, const int tid_in) {
;     ...
;   } else if constexpr (MODE == EPI_UP) {
;     const int woff = widen_off(fq);
; #pragma unroll
;     for (int n = 0; n < NSUB; ++n) {
;       const int nl = wc * (NSUB * 16) + n * 16 + fr;
;       const int t = tn * (NSUB * 32) + nl;
;       const float rs = s_rstd[nl];
; #pragma unroll
;       for (int mp = 0; mp < 2; ++mp) {
;         bf16x4 pk[2];
; #pragma unroll
;         for (int h2 = 0; h2 < 2; ++h2) {
;           const int m = mp * 2 + h2;
;           float v[4];
; #pragma unroll
;           for (int j = 0; j < 4; ++j) {
;             float a = fmaxf(acc[m][n][j] * rs, 0.f);
;             v[j] = a * a;
;           }
;           pk[h2] = pack4(v[0], v[1], v[2], v[3]);
;         }
;         const int f = tm * 128 + wr * 64 + mp * 32 + woff;
;         __builtin_nontemporal_store(widen_pair(pk[0], pk[1]), reinterpret_cast<u32x4*>(p.hm + blk(t, f, 128)));
;       }
;     }
	v_mul_f32_e32 v76, v76, v80
	v_mul_f32_e32 v77, v77, v80
	v_mul_f32_e32 v78, v78, v80
	v_mul_f32_e32 v79, v79, v80
	v_mul_f32_e32 v72, v72, v80
	v_mul_f32_e32 v73, v73, v80
	v_max_f32_e32 v76, 0, v76
	v_max_f32_e32 v77, 0, v77
	v_max_f32_e32 v78, 0, v78
	v_max_f32_e32 v79, 0, v79
	v_max_f32_e32 v72, 0, v72
	v_max_f32_e32 v73, 0, v73
	v_mul_f32_e32 v68, v68, v80
	v_mul_f32_e32 v69, v69, v80
	v_mul_f32_e32 v70, v70, v80
	v_mul_f32_e32 v71, v71, v80
	v_mul_f32_e32 v64, v64, v80
	v_mul_f32_e32 v65, v65, v80
	v_mul_f32_e32 v66, v66, v80
	v_mul_f32_e32 v67, v67, v80
	v_pk_mul_f32 v[76:77], v[76:77], v[76:77]
	v_pk_mul_f32 v[78:79], v[78:79], v[78:79]
	v_pk_mul_f32 v[72:73], v[72:73], v[72:73]
	v_max_f32_e32 v68, 0, v68
	v_max_f32_e32 v69, 0, v69
	v_max_f32_e32 v70, 0, v70
	v_max_f32_e32 v71, 0, v71
	v_max_f32_e32 v64, 0, v64
	v_max_f32_e32 v65, 0, v65
	v_max_f32_e32 v66, 0, v66
	v_max_f32_e32 v67, 0, v67
	v_cvt_pk_bf16_f32 v76, v76, v77
	v_cvt_pk_bf16_f32 v77, v78, v79
	v_cvt_pk_bf16_f32 v78, v72, v73
	v_or_b32_e32 v72, 0xc00, v152
	v_mov_b32_e32 v73, v153
	v_pk_mul_f32 v[68:69], v[68:69], v[68:69]
	v_pk_mul_f32 v[70:71], v[70:71], v[70:71]
	v_pk_mul_f32 v[64:65], v[64:65], v[64:65]
	v_pk_mul_f32 v[66:67], v[66:67], v[66:67]
	v_cvt_pk_bf16_f32 v68, v68, v69
	v_cvt_pk_bf16_f32 v69, v70, v71
	v_cvt_pk_bf16_f32 v70, v64, v65
	v_cvt_pk_bf16_f32 v71, v66, v67
	v_lshl_add_u64 v[64:65], v[114:115], 0, v[72:73]
	v_permlane16_swap_b32_e32 v68, v70
	v_permlane16_swap_b32_e32 v69, v71
	v_lshl_add_u64 v[64:65], v[64:65], 0, v[112:113]
	global_store_dwordx4 v[64:65], v[68:71], off nt
	v_or_b32_e32 v64, 0x20100, v118
	ds_read_b32 v64, v64
	v_mul_f32_e32 v74, v74, v80
	v_mul_f32_e32 v75, v75, v80
	v_max_f32_e32 v90, 0, v90
	v_max_f32_e32 v91, 0, v91
	s_waitcnt lgkmcnt(0)
	v_mul_f32_e32 v60, v60, v64
	v_mul_f32_e32 v61, v61, v64
	v_mul_f32_e32 v62, v62, v64
	v_mul_f32_e32 v63, v63, v64
	v_mul_f32_e32 v56, v56, v64
	v_mul_f32_e32 v57, v57, v64
	v_max_f32_e32 v60, 0, v60
	v_max_f32_e32 v61, 0, v61
	v_max_f32_e32 v62, 0, v62
	v_max_f32_e32 v63, 0, v63
	v_max_f32_e32 v56, 0, v56
	v_max_f32_e32 v57, 0, v57
	v_mul_f32_e32 v52, v52, v64
	v_mul_f32_e32 v53, v53, v64
	v_mul_f32_e32 v54, v54, v64
	v_mul_f32_e32 v55, v55, v64
	v_mul_f32_e32 v48, v48, v64
	v_mul_f32_e32 v49, v49, v64
	v_mul_f32_e32 v50, v50, v64
	v_mul_f32_e32 v51, v51, v64
	v_pk_mul_f32 v[60:61], v[60:61], v[60:61]
	v_pk_mul_f32 v[62:63], v[62:63], v[62:63]
	v_pk_mul_f32 v[56:57], v[56:57], v[56:57]
	v_max_f32_e32 v52, 0, v52
	v_max_f32_e32 v53, 0, v53
	v_max_f32_e32 v54, 0, v54
	v_max_f32_e32 v55, 0, v55
	v_max_f32_e32 v48, 0, v48
	v_max_f32_e32 v49, 0, v49
	v_max_f32_e32 v50, 0, v50
	v_max_f32_e32 v51, 0, v51
	v_cvt_pk_bf16_f32 v60, v60, v61
	v_cvt_pk_bf16_f32 v61, v62, v63
	v_cvt_pk_bf16_f32 v62, v56, v57
	v_or_b32_e32 v56, 0x1000, v152
	v_mov_b32_e32 v57, v153
	v_pk_mul_f32 v[52:53], v[52:53], v[52:53]
	v_pk_mul_f32 v[54:55], v[54:55], v[54:55]
	v_pk_mul_f32 v[48:49], v[48:49], v[48:49]
	v_pk_mul_f32 v[50:51], v[50:51], v[50:51]
	v_cvt_pk_bf16_f32 v52, v52, v53
	v_cvt_pk_bf16_f32 v53, v54, v55
	v_cvt_pk_bf16_f32 v54, v48, v49
	v_cvt_pk_bf16_f32 v55, v50, v51
	v_lshl_add_u64 v[48:49], v[114:115], 0, v[56:57]
	v_permlane16_swap_b32_e32 v52, v54
	v_permlane16_swap_b32_e32 v53, v55
	v_lshl_add_u64 v[48:49], v[48:49], 0, v[112:113]
	global_store_dwordx4 v[48:49], v[52:55], off nt
	v_or_b32_e32 v48, 0x20140, v118
	ds_read_b32 v48, v48
	v_mul_f32_e32 v58, v58, v64
	v_mul_f32_e32 v59, v59, v64
	v_max_f32_e32 v74, 0, v74
	v_max_f32_e32 v75, 0, v75
	s_waitcnt lgkmcnt(0)
	v_mul_f32_e32 v44, v44, v48
	v_mul_f32_e32 v45, v45, v48
	v_mul_f32_e32 v46, v46, v48
	v_mul_f32_e32 v47, v47, v48
	v_mul_f32_e32 v40, v40, v48
	v_mul_f32_e32 v41, v41, v48
	v_max_f32_e32 v44, 0, v44
	v_max_f32_e32 v45, 0, v45
	v_max_f32_e32 v46, 0, v46
	v_max_f32_e32 v47, 0, v47
	v_max_f32_e32 v40, 0, v40
	v_max_f32_e32 v41, 0, v41
	v_mul_f32_e32 v36, v36, v48
	v_mul_f32_e32 v37, v37, v48
	v_mul_f32_e32 v38, v38, v48
	v_mul_f32_e32 v39, v39, v48
	v_mul_f32_e32 v32, v32, v48
	v_mul_f32_e32 v33, v33, v48
	v_mul_f32_e32 v34, v34, v48
	v_mul_f32_e32 v35, v35, v48
	v_pk_mul_f32 v[44:45], v[44:45], v[44:45]
	v_pk_mul_f32 v[46:47], v[46:47], v[46:47]
	v_pk_mul_f32 v[40:41], v[40:41], v[40:41]
	v_max_f32_e32 v36, 0, v36
	v_max_f32_e32 v37, 0, v37
	v_max_f32_e32 v38, 0, v38
	v_max_f32_e32 v39, 0, v39
	v_max_f32_e32 v32, 0, v32
	v_max_f32_e32 v33, 0, v33
	v_max_f32_e32 v34, 0, v34
	v_max_f32_e32 v35, 0, v35
	v_cvt_pk_bf16_f32 v44, v44, v45
	v_cvt_pk_bf16_f32 v45, v46, v47
	v_cvt_pk_bf16_f32 v46, v40, v41
	v_or_b32_e32 v40, 0x1400, v152
	v_mov_b32_e32 v41, v153
	v_pk_mul_f32 v[36:37], v[36:37], v[36:37]
	v_pk_mul_f32 v[38:39], v[38:39], v[38:39]
	v_pk_mul_f32 v[32:33], v[32:33], v[32:33]
	v_pk_mul_f32 v[34:35], v[34:35], v[34:35]
	v_cvt_pk_bf16_f32 v36, v36, v37
	v_cvt_pk_bf16_f32 v37, v38, v39
	v_cvt_pk_bf16_f32 v38, v32, v33
	v_cvt_pk_bf16_f32 v39, v34, v35
	v_lshl_add_u64 v[32:33], v[114:115], 0, v[40:41]
	v_permlane16_swap_b32_e32 v36, v38
	v_permlane16_swap_b32_e32 v37, v39
	v_lshl_add_u64 v[32:33], v[32:33], 0, v[112:113]
	global_store_dwordx4 v[32:33], v[36:39], off nt
	v_or_b32_e32 v32, 0x20180, v118
	ds_read_b32 v32, v32
	v_mul_f32_e32 v42, v42, v48
	v_mul_f32_e32 v43, v43, v48
	v_max_f32_e32 v58, 0, v58
	v_max_f32_e32 v59, 0, v59
	s_waitcnt lgkmcnt(0)
; template <int MODE, int NSUB>
; __device__ __forceinline__ void epilogue(const Params& p, int layer, f32x4 (&acc)[4][NSUB], int tm, int tn, int g,
;                                          const float* s_rstd, const int tid_in) {
;     ...
; #pragma unroll
;       for (int mp = 0; mp < 2; ++mp) {
;         bf16x4 pk[2];
; #pragma unroll
;         for (int h2 = 0; h2 < 2; ++h2) {
;           const int m = mp * 2 + h2;
;           float v[4];
; #pragma unroll
;           for (int j = 0; j < 4; ++j) {
;             float a = fmaxf(acc[m][n][j] * rs, 0.f);
;             v[j] = a * a;
;           }
;           pk[h2] = pack4(v[0], v[1], v[2], v[3]);
;         }
;         const int f = tm * 128 + wr * 64 + mp * 32 + woff;
;         __builtin_nontemporal_store(widen_pair(pk[0], pk[1]), reinterpret_cast<u32x4*>(p.hm + blk(t, f, 128)));
;       }
;     }
; __global__ void __launch_bounds__(NTHREADS) fwd_megakernel(Params p) {
;     ...
;           for (int id = rvid; id < 16 * CHUNK_TT; id += Greal) {
;             int ftb, ttl;
;             tile_decode_fb(id, 16, 4, ftb, ttl);
;             compute_rstd(p.part, 16, 1.0f / 1024.f, (chunk * CHUNK_TT + ttl) * 256, 256, s_rstd_b, tid_full);
;             f32x4 acc[4][8];
;             gemm_big<32>(acc, W + (long)ftb * 256 * 1024, 128 * 1024, p.xb + (long)(chunk * CHUNK_TT + ttl) * 256 * 1024, 128 * 1024, smem_all, tid_full);
;             const int ft = ftb * 2 + (widf >> 2);
;             epilogue<EPI_UP, 8>(p, l, acc, ft, ttl, 0, s_rstd_b, tid_e);
;             __syncthreads();
;           }
	v_mul_f32_e32 v28, v28, v32
	v_mul_f32_e32 v29, v29, v32
	v_mul_f32_e32 v30, v30, v32
	v_mul_f32_e32 v31, v31, v32
	v_mul_f32_e32 v24, v24, v32
	v_mul_f32_e32 v25, v25, v32
	v_max_f32_e32 v28, 0, v28
	v_max_f32_e32 v29, 0, v29
	v_max_f32_e32 v30, 0, v30
	v_max_f32_e32 v31, 0, v31
	v_max_f32_e32 v24, 0, v24
	v_max_f32_e32 v25, 0, v25
	v_mul_f32_e32 v20, v20, v32
	v_mul_f32_e32 v21, v21, v32
	v_mul_f32_e32 v22, v22, v32
	v_mul_f32_e32 v23, v23, v32
	v_mul_f32_e32 v16, v16, v32
	v_mul_f32_e32 v17, v17, v32
	v_mul_f32_e32 v18, v18, v32
	v_mul_f32_e32 v19, v19, v32
	v_pk_mul_f32 v[28:29], v[28:29], v[28:29]
	v_pk_mul_f32 v[30:31], v[30:31], v[30:31]
	v_pk_mul_f32 v[24:25], v[24:25], v[24:25]
	v_max_f32_e32 v20, 0, v20
	v_max_f32_e32 v21, 0, v21
	v_max_f32_e32 v22, 0, v22
	v_max_f32_e32 v23, 0, v23
	v_max_f32_e32 v16, 0, v16
	v_max_f32_e32 v17, 0, v17
	v_max_f32_e32 v18, 0, v18
	v_max_f32_e32 v19, 0, v19
	v_cvt_pk_bf16_f32 v28, v28, v29
	v_cvt_pk_bf16_f32 v29, v30, v31
	v_cvt_pk_bf16_f32 v30, v24, v25
	v_or_b32_e32 v24, 0x1800, v152
	v_mov_b32_e32 v25, v153
	v_pk_mul_f32 v[20:21], v[20:21], v[20:21]
	v_pk_mul_f32 v[22:23], v[22:23], v[22:23]
	v_pk_mul_f32 v[16:17], v[16:17], v[16:17]
	v_pk_mul_f32 v[18:19], v[18:19], v[18:19]
	v_cvt_pk_bf16_f32 v20, v20, v21
	v_cvt_pk_bf16_f32 v21, v22, v23
	v_cvt_pk_bf16_f32 v22, v16, v17
	v_cvt_pk_bf16_f32 v23, v18, v19
	v_lshl_add_u64 v[16:17], v[114:115], 0, v[24:25]
	v_permlane16_swap_b32_e32 v20, v22
	v_permlane16_swap_b32_e32 v21, v23
	v_lshl_add_u64 v[16:17], v[16:17], 0, v[112:113]
	global_store_dwordx4 v[16:17], v[20:23], off nt
	v_or_b32_e32 v16, 0x201c0, v118
	ds_read_b32 v16, v16
	v_mul_f32_e32 v26, v26, v32
	v_mul_f32_e32 v27, v27, v32
	v_max_f32_e32 v42, 0, v42
	v_max_f32_e32 v43, 0, v43
	s_waitcnt lgkmcnt(0)
	v_mul_f32_e32 v12, v12, v16
	v_mul_f32_e32 v13, v13, v16
	v_mul_f32_e32 v14, v14, v16
	v_mul_f32_e32 v15, v15, v16
	v_mul_f32_e32 v8, v8, v16
	v_mul_f32_e32 v9, v9, v16
	v_mul_f32_e32 v10, v10, v16
	v_mul_f32_e32 v11, v11, v16
	v_mul_f32_e32 v4, v4, v16
	v_mul_f32_e32 v5, v5, v16
	v_mul_f32_e32 v6, v6, v16
	v_mul_f32_e32 v7, v7, v16
	v_mul_f32_e32 v0, v0, v16
	v_mul_f32_e32 v1, v1, v16
	v_mul_f32_e32 v2, v2, v16
	v_mul_f32_e32 v3, v3, v16
	v_max_f32_e32 v26, 0, v26
	v_max_f32_e32 v27, 0, v27
	v_max_f32_e32 v12, 0, v12
	v_max_f32_e32 v13, 0, v13
	v_max_f32_e32 v14, 0, v14
	v_max_f32_e32 v15, 0, v15
	v_max_f32_e32 v8, 0, v8
	v_max_f32_e32 v9, 0, v9
	v_max_f32_e32 v10, 0, v10
	v_max_f32_e32 v11, 0, v11
	v_max_f32_e32 v4, 0, v4
	v_max_f32_e32 v5, 0, v5
	v_max_f32_e32 v6, 0, v6
	v_max_f32_e32 v7, 0, v7
	v_max_f32_e32 v0, 0, v0
	v_max_f32_e32 v1, 0, v1
	v_max_f32_e32 v2, 0, v2
	v_max_f32_e32 v3, 0, v3
	v_cvt_pk_bf16_f32 v122, v122, v123
	v_cvt_pk_bf16_f32 v123, v124, v125
	v_lshl_add_u64 v[124:125], v[114:115], 0, v[152:153]
	v_pk_mul_f32 v[106:107], v[106:107], v[106:107]
	v_pk_mul_f32 v[90:91], v[90:91], v[90:91]
	v_pk_mul_f32 v[74:75], v[74:75], v[74:75]
	v_pk_mul_f32 v[58:59], v[58:59], v[58:59]
	v_pk_mul_f32 v[42:43], v[42:43], v[42:43]
	v_pk_mul_f32 v[26:27], v[26:27], v[26:27]
	v_pk_mul_f32 v[12:13], v[12:13], v[12:13]
	v_pk_mul_f32 v[14:15], v[14:15], v[14:15]
	v_pk_mul_f32 v[8:9], v[8:9], v[8:9]
	v_pk_mul_f32 v[10:11], v[10:11], v[10:11]
	v_or_b32_e32 v152, 0x1c00, v152
	v_pk_mul_f32 v[4:5], v[4:5], v[4:5]
	v_pk_mul_f32 v[6:7], v[6:7], v[6:7]
	v_pk_mul_f32 v[0:1], v[0:1], v[0:1]
	v_pk_mul_f32 v[2:3], v[2:3], v[2:3]
	v_cvt_pk_bf16_f32 v111, v106, v107
	v_lshl_add_u64 v[106:107], v[116:117], 0, v[104:105]
	v_cvt_pk_bf16_f32 v95, v90, v91
	v_lshl_add_u64 v[90:91], v[116:117], 0, v[88:89]
	v_cvt_pk_bf16_f32 v79, v74, v75
	v_lshl_add_u64 v[74:75], v[116:117], 0, v[72:73]
	v_cvt_pk_bf16_f32 v63, v58, v59
	v_lshl_add_u64 v[58:59], v[116:117], 0, v[56:57]
	v_cvt_pk_bf16_f32 v47, v42, v43
	v_lshl_add_u64 v[42:43], v[116:117], 0, v[40:41]
	v_cvt_pk_bf16_f32 v31, v26, v27
	v_lshl_add_u64 v[26:27], v[116:117], 0, v[24:25]
	v_cvt_pk_bf16_f32 v12, v12, v13
	v_cvt_pk_bf16_f32 v13, v14, v15
	v_cvt_pk_bf16_f32 v14, v8, v9
	v_cvt_pk_bf16_f32 v15, v10, v11
	v_lshl_add_u64 v[8:9], v[116:117], 0, v[152:153]
	v_cvt_pk_bf16_f32 v4, v4, v5
	v_cvt_pk_bf16_f32 v5, v6, v7
	v_cvt_pk_bf16_f32 v6, v0, v1
	v_cvt_pk_bf16_f32 v7, v2, v3
	v_lshl_add_u64 v[0:1], v[114:115], 0, v[152:153]
	s_add_i32 s9, s9, s26
	v_permlane16_swap_b32_e32 v120, v122
	v_permlane16_swap_b32_e32 v121, v123
	v_lshl_add_u64 v[124:125], v[124:125], 0, v[112:113]
	v_permlane16_swap_b32_e32 v108, v110
	v_permlane16_swap_b32_e32 v109, v111
	v_lshl_add_u64 v[106:107], v[106:107], 0, v[112:113]
	v_permlane16_swap_b32_e32 v92, v94
	v_permlane16_swap_b32_e32 v93, v95
	v_lshl_add_u64 v[90:91], v[90:91], 0, v[112:113]
	v_permlane16_swap_b32_e32 v76, v78
	v_permlane16_swap_b32_e32 v77, v79
	v_lshl_add_u64 v[74:75], v[74:75], 0, v[112:113]
	v_permlane16_swap_b32_e32 v60, v62
	v_permlane16_swap_b32_e32 v61, v63
	v_lshl_add_u64 v[58:59], v[58:59], 0, v[112:113]
	v_permlane16_swap_b32_e32 v44, v46
	v_permlane16_swap_b32_e32 v45, v47
	v_lshl_add_u64 v[42:43], v[42:43], 0, v[112:113]
	v_permlane16_swap_b32_e32 v28, v30
	v_permlane16_swap_b32_e32 v29, v31
	v_lshl_add_u64 v[26:27], v[26:27], 0, v[112:113]
	v_permlane16_swap_b32_e32 v12, v14
	v_permlane16_swap_b32_e32 v13, v15
	v_lshl_add_u64 v[8:9], v[8:9], 0, v[112:113]
	v_permlane16_swap_b32_e32 v4, v6
	v_permlane16_swap_b32_e32 v5, v7
	v_lshl_add_u64 v[0:1], v[0:1], 0, v[112:113]
	s_cmpk_gt_i32 s9, 0x13ff
	v_readlane_b32 s65, v252, 5
	v_readlane_b32 s66, v252, 6
	v_readlane_b32 s67, v252, 7
	v_readlane_b32 s68, v252, 8
	v_readlane_b32 s69, v252, 9
	v_readlane_b32 s70, v252, 10
	v_readlane_b32 s71, v252, 11
	v_readlane_b32 s72, v252, 12
	v_readlane_b32 s73, v252, 13
	v_readlane_b32 s74, v252, 14
	v_readlane_b32 s75, v252, 15
	v_readlane_b32 s76, v252, 16
	v_readlane_b32 s77, v252, 17
	global_store_dwordx4 v[124:125], v[120:123], off nt
	global_store_dwordx4 v[106:107], v[108:111], off nt
	global_store_dwordx4 v[90:91], v[92:95], off nt
	global_store_dwordx4 v[74:75], v[76:79], off nt
	global_store_dwordx4 v[58:59], v[60:63], off nt
	global_store_dwordx4 v[42:43], v[44:47], off nt
	global_store_dwordx4 v[26:27], v[28:31], off nt
	global_store_dwordx4 v[8:9], v[12:15], off nt
	global_store_dwordx4 v[0:1], v[4:7], off nt
	s_barrier
	s_cbranch_scc0 .LBB0_287

; template <int NK, bool BNT = false> ...
;     ...
; #pragma unroll
;   for (int m = 0; m < 4; ++m)
; #pragma unroll
;     for (int n = 0; n < 8; ++n) acc[m][n] = f32x4{0.f, 0.f, 0.f, 0.f};
;   const int sb0 = tidf * 16;
;   const int sr0 = sb0 >> 6;
;   const unsigned soff = (unsigned)(sr0 * 64 + ((((sb0 >> 4) & 3) ^ (((sr0 >> 3) & 1) << 1)) * 16));
;   const unsigned char* Abase = reinterpret_cast<const unsigned char*>(A);
;   const unsigned char* Bbase = reinterpret_cast<const unsigned char*>(B);
;   auto stage = [&](int kt, int bufc) {
;     unsigned char* sa = smem + bufc * BIG_STAGE;
;     const unsigned char* Ab = Abase + (long)kt * 8192 + soff;
;     const unsigned char* Bb = Bbase + (long)kt * 8192 + soff;
;     glds16(Ab, sa + sb0);
;     glds16(Ab + astride * 2, sa + 8192 + sb0);
;     if constexpr (BNT) {
;       glds16_nt(Bb, sa + 16384 + sb0);
;       glds16_nt(Bb + bstride * 2, sa + 24576 + sb0);
;     } else {
;       glds16(Bb, sa + 16384 + sb0);
;       glds16(Bb + bstride * 2, sa + 24576 + sb0);
;     }
;   };
; __device__ __forceinline__ void compute_rstd(const float* __restrict__ part, int nslot, float invn, int t0, int ntok,
;                                              float* s_rstd, const int tid_in) {
;   int tid = tid_in;
;   asm volatile("" : "+v"(tid));
;   if (tid < ntok) {
;     const float* pp = part + (long)(t0 + tid) * nslot;
;     float s = 0.f;
;     for (int i = 0; i < nslot; ++i) s += pp[i];
;     s_rstd[tid] = rsqrtf(s * invn + 1e-6f);
;   }
; }
; __global__ void __launch_bounds__(NTHREADS) fwd_megakernel(Params p) {
;     ...
;           for (int id = rvid; id < 4 * 320; id += Greal) {
;             int ftb, ttl;
;             tile_decode(id, 4, ftb, ttl);
;             compute_rstd(p.part, 16, 1.0f / 1024.f, ttl * 256, 256, s_rstd_b, tid_full);
;             f32x4 acc[4][8];
;             gemm_big<32>(acc, W + (long)ftb * 256 * 1024, 128 * 1024, p.xb + (long)ttl * 256 * 1024, 128 * 1024, smem_all, tid_full);
.LBB0_298:
	s_or_b64 exec, exec, s[4:5]
	s_add_i32 s47, s47, s26
	s_cmpk_gt_i32 s47, 0x4ff
	s_waitcnt lgkmcnt(0)
	s_barrier
	s_cbranch_scc1 .LBB0_479
.LBB0_299:
	s_ashr_i32 s4, s47, 31
	s_lshr_b32 s4, s4, 27
	s_add_i32 s4, s47, s4
	s_ashr_i32 s5, s4, 5
	s_and_b32 s4, s4, 0xffe0
	s_sub_i32 s6, s47, s4
	s_bfe_i32 s4, s6, 0x80000
	s_bfe_u32 s4, s4, 0x2000d
	s_add_i32 s4, s6, s4
	s_bfe_i32 s4, s4, 0x80000
	s_sext_i32_i16 s7, s4
	s_lshl_b32 s4, s5, 3
	s_ashr_i32 s5, s7, 2
	s_add_i32 s90, s4, s5
	v_mov_b32_e32 v232, v214
	s_lshl_b32 s48, s90, 8
	s_nop 0
	v_cmp_gt_i32_e32 vcc, s30, v232
	s_and_saveexec_b64 s[4:5], vcc
	s_cbranch_execz .LBB0_301
	v_add_u32_e32 v234, s48, v232
	v_ashrrev_i32_e32 v235, 31, v234
	v_readlane_b32 s64, v253, 25
	v_lshlrev_b64 v[234:235], 6, v[234:235]
	v_readlane_b32 s70, v253, 31
	v_readlane_b32 s71, v253, 32
	s_mov_b32 s8, 0x800000
	v_lshl_add_u32 v232, v232, 2, v200
	v_lshl_add_u64 v[236:237], s[70:71], 0, v[234:235]
	s_waitcnt lgkmcnt(0)
	global_load_dwordx4 v[216:219], v[236:237], off
	global_load_dwordx4 v[220:223], v[236:237], off offset:16
	global_load_dwordx4 v[224:227], v[236:237], off offset:32
	s_nop 0
	global_load_dwordx4 v[228:231], v[236:237], off offset:48
	v_readlane_b32 s65, v253, 26
	v_readlane_b32 s66, v253, 27
	v_readlane_b32 s67, v253, 28
	v_readlane_b32 s68, v253, 29
	v_readlane_b32 s69, v253, 30
	v_readlane_b32 s72, v253, 33
	v_readlane_b32 s73, v253, 34
	v_readlane_b32 s74, v253, 35
	v_readlane_b32 s75, v253, 36
	v_readlane_b32 s76, v253, 37
	v_readlane_b32 s77, v253, 38
	v_readlane_b32 s78, v253, 39
	v_readlane_b32 s79, v253, 40
.LBB0_301:
	s_or_b64 exec, exec, s[4:5]
	s_lshr_b32 s4, s7, 2
	s_lshl_b32 s4, s4, 2
	s_sub_i32 s4, s6, s4
	s_bfe_i64 s[6:7], s[4:5], 0x80000
	s_lshl_b64 s[6:7], s[6:7], 19
	s_add_u32 s8, s88, s6
	s_addc_u32 s9, s89, s7
	s_ashr_i32 s91, s90, 31
	v_readlane_b32 s64, v253, 25
	s_lshl_b64 s[10:11], s[90:91], 19
	v_readlane_b32 s68, v253, 29
	v_readfirstlane_b32 s5, v147
	v_add_u32_e32 v146, 0x2000, v147
	v_readlane_b32 s69, v253, 30
	s_add_u32 s12, s68, s10
	v_lshl_add_u64 v[136:137], s[8:9], 0, v[128:129]
	s_mov_b32 m0, s5
	s_mov_b64 s[8:9], 0x40000
	v_readfirstlane_b32 s5, v146
	v_add_u32_e32 v152, 0x4000, v147
	s_addc_u32 s13, s69, s11
	global_load_lds_dwordx4 v[136:137], off
	v_lshl_add_u64 v[0:1], v[136:137], 0, s[8:9]
	s_mov_b32 m0, s5
	v_readfirstlane_b32 s5, v152
	v_add_u32_e32 v154, 0x6000, v147
	v_lshl_add_u64 v[134:135], s[12:13], 0, v[128:129]
	global_load_lds_dwordx4 v[0:1], off
	s_mov_b32 m0, s5
	v_readfirstlane_b32 s5, v154
	v_add_u32_e32 v155, 0x8000, v147
	global_load_lds_dwordx4 v[134:135], off
	v_lshl_add_u64 v[0:1], v[134:135], 0, s[8:9]
	s_mov_b32 m0, s5
	s_mov_b64 s[8:9], 0x2000
	v_readfirstlane_b32 s5, v155
	v_add_u32_e32 v156, 0xa000, v147
	global_load_lds_dwordx4 v[0:1], off
	v_lshl_add_u64 v[0:1], v[136:137], 0, s[8:9]
	v_lshl_add_u64 v[2:3], v[134:135], 0, s[8:9]
	s_mov_b32 m0, s5
	s_mov_b64 s[8:9], 0x42000
	v_readfirstlane_b32 s5, v156
	v_add_u32_e32 v157, 0xc000, v147
	global_load_lds_dwordx4 v[0:1], off
	v_lshl_add_u64 v[0:1], v[136:137], 0, s[8:9]
	s_mov_b32 m0, s5
	v_readfirstlane_b32 s5, v157
	v_add_u32_e32 v158, 0xe000, v147
	global_load_lds_dwordx4 v[0:1], off
	s_mov_b32 m0, s5
	v_readfirstlane_b32 s5, v158
	v_add_u32_e32 v159, 0x10000, v147
	global_load_lds_dwordx4 v[2:3], off
	v_lshl_add_u64 v[0:1], v[134:135], 0, s[8:9]
	s_mov_b32 m0, s5
	v_readfirstlane_b32 s5, v159
	v_add_u32_e32 v160, 0x12000, v147
	global_load_lds_dwordx4 v[0:1], off
	v_lshl_add_u64 v[0:1], v[136:137], 0, s[94:95]
	s_mov_b32 m0, s5
	s_mov_b64 s[8:9], 0x44000
	v_readfirstlane_b32 s5, v160
	v_add_u32_e32 v161, 0x14000, v147
	global_load_lds_dwordx4 v[0:1], off
	v_lshl_add_u64 v[0:1], v[136:137], 0, s[8:9]
	s_mov_b32 m0, s5
	v_readfirstlane_b32 s5, v161
	v_add_u32_e32 v162, 0x16000, v147
	v_lshl_add_u64 v[2:3], v[134:135], 0, s[94:95]
	global_load_lds_dwordx4 v[0:1], off
	s_mov_b32 m0, s5
	v_readfirstlane_b32 s5, v162
	global_load_lds_dwordx4 v[2:3], off
	v_lshl_add_u64 v[0:1], v[134:135], 0, s[8:9]
	s_mov_b32 m0, s5
	v_mov_b32_e32 v56, 0
	global_load_lds_dwordx4 v[0:1], off
	v_lshl_add_u64 v[138:139], v[130:131], 0, s[6:7]
	v_lshl_add_u64 v[140:141], v[132:133], 0, s[10:11]
	s_mov_b64 s[6:7], 0
	v_mov_b32_e32 v57, v56
	v_mov_b32_e32 v58, v56
	v_mov_b32_e32 v59, v56
	v_mov_b32_e32 v64, v56
	v_mov_b32_e32 v65, v56
	v_mov_b32_e32 v66, v56
	v_mov_b32_e32 v67, v56
	v_mov_b32_e32 v52, v56
	v_mov_b32_e32 v53, v56
	v_mov_b32_e32 v54, v56
	v_mov_b32_e32 v55, v56
	v_mov_b32_e32 v48, v56
	v_mov_b32_e32 v49, v56
	v_mov_b32_e32 v50, v56
	v_mov_b32_e32 v51, v56
	v_mov_b32_e32 v0, v56
	v_mov_b32_e32 v1, v56
	v_mov_b32_e32 v2, v56
	v_mov_b32_e32 v3, v56
	v_mov_b32_e32 v4, v56
	s_waitcnt lgkmcnt(0)
; #define BIG_SYNC(N)                                              \
;   asm volatile("s_waitcnt vmcnt(%0)" ::"n"(N) : "memory");       \
;   __builtin_amdgcn_s_barrier();                                  \
;   asm volatile("" ::: "memory");                                 \
;   __builtin_amdgcn_sched_barrier(0);
; template <int NK, bool BNT = false> ...
;     ...
; #pragma unroll
;   for (int m = 0; m < 4; ++m)
; #pragma unroll
;     for (int n = 0; n < 8; ++n) acc[m][n] = f32x4{0.f, 0.f, 0.f, 0.f};
;     ...
;     BIG_SYNC(2 * NG); kstep(t, 0, 3, true);
; __device__ __forceinline__ void compute_rstd(const float* __restrict__ part, int nslot, float invn, int t0, int ntok,
;                                              float* s_rstd, const int tid_in) {
;   int tid = tid_in;
;   asm volatile("" : "+v"(tid));
;   if (tid < ntok) {
;     const float* pp = part + (long)(t0 + tid) * nslot;
;     float s = 0.f;
;     for (int i = 0; i < nslot; ++i) s += pp[i];
;     s_rstd[tid] = rsqrtf(s * invn + 1e-6f);
;   }
; }
	v_mov_b32_e32 v5, v56
	v_mov_b32_e32 v6, v56
	v_mov_b32_e32 v7, v56
	v_mov_b32_e32 v8, v56
	v_mov_b32_e32 v9, v56
	v_mov_b32_e32 v10, v56
	v_mov_b32_e32 v11, v56
	v_mov_b32_e32 v12, v56
	v_mov_b32_e32 v13, v56
	v_mov_b32_e32 v14, v56
	v_mov_b32_e32 v15, v56
	v_mov_b32_e32 v100, v56
	v_mov_b32_e32 v101, v56
	v_mov_b32_e32 v102, v56
	v_mov_b32_e32 v103, v56
	v_mov_b32_e32 v80, v56
	v_mov_b32_e32 v81, v56
	v_mov_b32_e32 v82, v56
	v_mov_b32_e32 v83, v56
	v_mov_b32_e32 v68, v56
	v_mov_b32_e32 v69, v56
	v_mov_b32_e32 v70, v56
	v_mov_b32_e32 v71, v56
	v_mov_b32_e32 v72, v56
	v_mov_b32_e32 v73, v56
	v_mov_b32_e32 v74, v56
	v_mov_b32_e32 v75, v56
	v_mov_b32_e32 v16, v56
	v_mov_b32_e32 v17, v56
	v_mov_b32_e32 v18, v56
	v_mov_b32_e32 v19, v56
	v_mov_b32_e32 v20, v56
	v_mov_b32_e32 v21, v56
	v_mov_b32_e32 v22, v56
	v_mov_b32_e32 v23, v56
	v_mov_b32_e32 v24, v56
	v_mov_b32_e32 v25, v56
	v_mov_b32_e32 v26, v56
	v_mov_b32_e32 v27, v56
	v_mov_b32_e32 v28, v56
	v_mov_b32_e32 v29, v56
	v_mov_b32_e32 v30, v56
	v_mov_b32_e32 v31, v56
	v_mov_b32_e32 v104, v56
	v_mov_b32_e32 v105, v56
	v_mov_b32_e32 v106, v56
	v_mov_b32_e32 v107, v56
	v_mov_b32_e32 v96, v56
	v_mov_b32_e32 v97, v56
	v_mov_b32_e32 v98, v56
	v_mov_b32_e32 v99, v56
	v_mov_b32_e32 v108, v56
	v_mov_b32_e32 v109, v56
	v_mov_b32_e32 v110, v56
	v_mov_b32_e32 v111, v56
	v_mov_b32_e32 v88, v56
	v_mov_b32_e32 v89, v56
	v_mov_b32_e32 v90, v56
	v_mov_b32_e32 v91, v56
	v_mov_b32_e32 v32, v56
	v_mov_b32_e32 v33, v56
	v_mov_b32_e32 v34, v56
	v_mov_b32_e32 v35, v56
	v_mov_b32_e32 v36, v56
	v_mov_b32_e32 v37, v56
	v_mov_b32_e32 v38, v56
	v_mov_b32_e32 v39, v56
	v_mov_b32_e32 v40, v56
	v_mov_b32_e32 v41, v56
	v_mov_b32_e32 v42, v56
	v_mov_b32_e32 v43, v56
	v_mov_b32_e32 v44, v56
	v_mov_b32_e32 v45, v56
	v_mov_b32_e32 v46, v56
	v_mov_b32_e32 v47, v56
	v_mov_b32_e32 v112, v56
	v_mov_b32_e32 v113, v56
	v_mov_b32_e32 v114, v56
	v_mov_b32_e32 v115, v56
	v_mov_b32_e32 v116, v56
	v_mov_b32_e32 v117, v56
	v_mov_b32_e32 v118, v56
	v_mov_b32_e32 v119, v56
	v_mov_b32_e32 v120, v56
	v_mov_b32_e32 v121, v56
	v_mov_b32_e32 v122, v56
	v_mov_b32_e32 v123, v56
	v_mov_b32_e32 v124, v56
	v_mov_b32_e32 v125, v56
	v_mov_b32_e32 v126, v56
	v_mov_b32_e32 v127, v56
	v_mov_b32_e32 v60, v56
	v_mov_b32_e32 v61, v56
	v_mov_b32_e32 v62, v56
	v_mov_b32_e32 v63, v56
	v_mov_b32_e32 v76, v56
	v_mov_b32_e32 v77, v56
	v_mov_b32_e32 v78, v56
	v_mov_b32_e32 v79, v56
	v_mov_b32_e32 v84, v56
	v_mov_b32_e32 v85, v56
	v_mov_b32_e32 v86, v56
	v_mov_b32_e32 v87, v56
	v_mov_b32_e32 v92, v56
	v_mov_b32_e32 v93, v56
	v_mov_b32_e32 v94, v56
	v_mov_b32_e32 v95, v56
	v_readlane_b32 s65, v253, 26
	v_readlane_b32 s66, v253, 27
	v_readlane_b32 s67, v253, 28
	v_readlane_b32 s70, v253, 31
	v_readlane_b32 s71, v253, 32
	v_readlane_b32 s72, v253, 33
	v_readlane_b32 s73, v253, 34
	v_readlane_b32 s74, v253, 35
	v_readlane_b32 s75, v253, 36
	v_readlane_b32 s76, v253, 37
	v_readlane_b32 s77, v253, 38
	v_readlane_b32 s78, v253, 39
	v_readlane_b32 s79, v253, 40
	v_cmp_gt_i32_e32 vcc, s30, v214
	s_and_saveexec_b64 s[100:101], vcc
	s_cbranch_execz .Lmy_g1_rsdone
	s_waitcnt vmcnt(15)
	v_add_f32_e32 v233, 0, v216
	v_add_f32_e32 v233, v233, v217
	v_add_f32_e32 v233, v233, v218
	v_add_f32_e32 v233, v233, v219
	s_waitcnt vmcnt(14)
	v_add_f32_e32 v233, v233, v220
	v_add_f32_e32 v233, v233, v221
	v_add_f32_e32 v233, v233, v222
	v_add_f32_e32 v233, v233, v223
	s_waitcnt vmcnt(13)
	v_add_f32_e32 v233, v233, v224
	v_add_f32_e32 v233, v233, v225
	v_add_f32_e32 v233, v233, v226
	v_add_f32_e32 v233, v233, v227
	s_waitcnt vmcnt(12)
	v_add_f32_e32 v233, v233, v228
	v_add_f32_e32 v233, v233, v229
	v_add_f32_e32 v233, v233, v230
	v_add_f32_e32 v233, v233, v231
	v_fmamk_f32 v233, v233, 0x3a800000, v184
	v_mul_f32_e32 v234, 0x4b800000, v233
	v_cmp_gt_f32_e32 vcc, 0x800000, v233
	s_nop 1
	v_cndmask_b32_e32 v233, v233, v234, vcc
	v_rsq_f32_e32 v233, v233
	s_nop 0
	v_mul_f32_e32 v234, 0x45800000, v233
	v_cndmask_b32_e32 v233, v233, v234, vcc
	ds_write_b32 v232, v233
.Lmy_g1_rsdone:
	s_or_b64 exec, exec, s[100:101]
	s_waitcnt vmcnt(8)
	s_barrier
	v_add_u32_e32 v167, 0x10000, v148
	v_or_b32_e32 v168, 0x10000, v150
	v_add_u32_e32 v176, 0x18000, v148
	v_or_b32_e32 v179, 0x18000, v150
	ds_read_b128 v[216:219], v148
	ds_read_b128 v[220:223], v148 offset:1024
	ds_read_b128 v[224:227], v148 offset:2048
	ds_read_b128 v[228:231], v148 offset:3072
	ds_read_b128 v[232:235], v149 offset:16384
	ds_read_b128 v[236:239], v149 offset:17408
	ds_read_b128 v[240:243], v149 offset:18432
	ds_read_b128 v[244:247], v149 offset:19456
; #define BIG_SYNC(N)                                              \
;   asm volatile("s_waitcnt vmcnt(%0)" ::"n"(N) : "memory");       \
;   __builtin_amdgcn_s_barrier();                                  \
;   asm volatile("" ::: "memory");                                 \
;   __builtin_amdgcn_sched_barrier(0);
; template <int NK, bool BNT = false> ...
;     ...
;   auto kstep = [&](int T, int cur, int nxt, bool do_stage) {
;     const unsigned char* sa = smem + cur * BIG_STAGE;
;     bf16x8 af[4], bfr[4];
; #pragma unroll
;     for (int m = 0; m < 4; ++m) af[m] = *reinterpret_cast<const bf16x8*>(sa + aoff + m * 1024);
; #pragma unroll
;     for (int n = 0; n < 4; ++n) bfr[n] = *reinterpret_cast<const bf16x8*>(sa + boff + n * 1024);
;     __builtin_amdgcn_sched_barrier(0);
;     if (do_stage) stage(T + 3, nxt);
; #pragma unroll
;     for (int m = 0; m < 4; ++m)
; #pragma unroll
;       for (int n = 0; n < 4; ++n) acc[m][n] = __builtin_amdgcn_mfma_f32_16x16x32_bf16(af[m], bfr[n], acc[m][n], 0, 0, 0);
;     if (do_stage) {
; #pragma unroll
;       for (int q = 0; q < NG; ++q) {
;         __builtin_amdgcn_sched_group_barrier(0x008, 3, 0);
;         __builtin_amdgcn_sched_group_barrier(0x010, 1, 0);
;       }
;       __builtin_amdgcn_sched_group_barrier(0x008, 16 - 3 * NG, 0);
;     }
;     __builtin_amdgcn_sched_barrier(0);
; #pragma unroll
;     for (int n = 0; n < 4; ++n) bfr[n] = *reinterpret_cast<const bf16x8*>(sa + boff + (4 + n) * 1024);
; #pragma unroll
;     for (int m = 0; m < 4; ++m)
; #pragma unroll
;       for (int n = 0; n < 4; ++n)
;         acc[m][4 + n] = __builtin_amdgcn_mfma_f32_16x16x32_bf16(af[m], bfr[n], acc[m][4 + n], 0, 0, 0);
;     __builtin_amdgcn_sched_barrier(0);
;   };
;     ...
;   for (int it = 0; it < NK / 4 - 1; ++it) {
;     const int t = it * 4;
;     BIG_SYNC(2 * NG); kstep(t, 0, 3, true);
;     BIG_SYNC(2 * NG); kstep(t + 1, 1, 0, true);
;     BIG_SYNC(2 * NG); kstep(t + 2, 2, 1, true);
;     BIG_SYNC(2 * NG); kstep(t + 3, 3, 2, true);
;   }
.LBB0_302:
	s_waitcnt vmcnt(4)
	s_barrier
	v_add_u32_e32 v163, 0x18000, v147
	v_lshl_add_u64 v[144:145], v[138:139], 0, s[6:7]
	v_readfirstlane_b32 s5, v163
	v_lshl_add_u64 v[164:165], v[144:145], 0, s[60:61]
	s_mov_b32 m0, s5
	s_waitcnt lgkmcnt(3)
	v_mfma_f32_16x16x32_bf16 v[56:59], v[216:219], v[232:235], v[56:59]
	v_lshl_add_u64 v[142:143], v[140:141], 0, s[6:7]
	v_lshl_add_u64 v[168:169], v[144:145], 0, s[80:81]
	v_lshl_add_u64 v[166:167], v[142:143], 0, s[60:61]
	v_mfma_f32_16x16x32_bf16 v[100:103], v[220:223], v[232:235], v[100:103]
	v_mfma_f32_16x16x32_bf16 v[104:107], v[224:227], v[232:235], v[104:107]
	global_load_lds_dwordx4 v[164:165], off
	v_add_u32_e32 v164, 0x1a000, v147
	v_add_u32_e32 v165, 0x1c000, v147
	v_readfirstlane_b32 s5, v164
	s_mov_b32 m0, s5
	v_readfirstlane_b32 s5, v165
	v_mfma_f32_16x16x32_bf16 v[112:115], v[228:231], v[232:235], v[112:115]
	s_waitcnt lgkmcnt(2)
	v_mfma_f32_16x16x32_bf16 v[64:67], v[216:219], v[236:239], v[64:67]
	ds_read_b128 v[232:235], v149 offset:20480
	v_mfma_f32_16x16x32_bf16 v[80:83], v[220:223], v[236:239], v[80:83]
	global_load_lds_dwordx4 v[168:169], off
	s_mov_b32 m0, s5
	v_mfma_f32_16x16x32_bf16 v[96:99], v[224:227], v[236:239], v[96:99]
	v_lshl_add_u64 v[168:169], v[142:143], 0, s[80:81]
	v_mfma_f32_16x16x32_bf16 v[116:119], v[228:231], v[236:239], v[116:119]
	s_waitcnt lgkmcnt(2)
	v_mfma_f32_16x16x32_bf16 v[52:55], v[216:219], v[240:243], v[52:55]
	ds_read_b128 v[236:239], v149 offset:21504
	global_load_lds_dwordx4 v[166:167], off
	v_add_u32_e32 v166, 0x1e000, v147
	v_mfma_f32_16x16x32_bf16 v[68:71], v[220:223], v[240:243], v[68:71]
	v_readfirstlane_b32 s5, v166
	s_mov_b32 m0, s5
	v_mfma_f32_16x16x32_bf16 v[108:111], v[224:227], v[240:243], v[108:111]
	v_mfma_f32_16x16x32_bf16 v[120:123], v[228:231], v[240:243], v[120:123]
	global_load_lds_dwordx4 v[168:169], off
	s_waitcnt lgkmcnt(2)
	v_mfma_f32_16x16x32_bf16 v[48:51], v[216:219], v[244:247], v[48:51]
	ds_read_b128 v[240:243], v149 offset:22528
	v_mfma_f32_16x16x32_bf16 v[72:75], v[220:223], v[244:247], v[72:75]
	v_mfma_f32_16x16x32_bf16 v[88:91], v[224:227], v[244:247], v[88:91]
	v_mfma_f32_16x16x32_bf16 v[124:127], v[228:231], v[244:247], v[124:127]
	s_waitcnt lgkmcnt(2)
	v_mfma_f32_16x16x32_bf16 v[0:3], v[216:219], v[232:235], v[0:3]
	ds_read_b128 v[244:247], v149 offset:23552
	v_mfma_f32_16x16x32_bf16 v[16:19], v[220:223], v[232:235], v[16:19]
	ds_read_b128 v[186:189], v148 offset:32768
	v_mfma_f32_16x16x32_bf16 v[32:35], v[224:227], v[232:235], v[32:35]
	ds_read_b128 v[190:193], v148 offset:33792
	v_mfma_f32_16x16x32_bf16 v[60:63], v[228:231], v[232:235], v[60:63]
	ds_read_b128 v[194:197], v148 offset:34816
	s_waitcnt lgkmcnt(5)
	v_mfma_f32_16x16x32_bf16 v[4:7], v[216:219], v[236:239], v[4:7]
	ds_read_b128 v[202:205], v148 offset:35840
	ds_read_b128 v[232:235], v149 offset:49152
	v_mfma_f32_16x16x32_bf16 v[20:23], v[220:223], v[236:239], v[20:23]
	v_mfma_f32_16x16x32_bf16 v[36:39], v[224:227], v[236:239], v[36:39]
	v_mfma_f32_16x16x32_bf16 v[76:79], v[228:231], v[236:239], v[76:79]
	s_waitcnt lgkmcnt(6)
	v_mfma_f32_16x16x32_bf16 v[8:11], v[216:219], v[240:243], v[8:11]
	ds_read_b128 v[236:239], v149 offset:50176
	v_mfma_f32_16x16x32_bf16 v[24:27], v[220:223], v[240:243], v[24:27]
	v_mfma_f32_16x16x32_bf16 v[40:43], v[224:227], v[240:243], v[40:43]
	v_mfma_f32_16x16x32_bf16 v[84:87], v[228:231], v[240:243], v[84:87]
	s_waitcnt lgkmcnt(6)
	v_mfma_f32_16x16x32_bf16 v[12:15], v[216:219], v[244:247], v[12:15]
	ds_read_b128 v[240:243], v149 offset:51200
	v_mfma_f32_16x16x32_bf16 v[28:31], v[220:223], v[244:247], v[28:31]
	v_mfma_f32_16x16x32_bf16 v[44:47], v[224:227], v[244:247], v[44:47]
	v_mfma_f32_16x16x32_bf16 v[92:95], v[228:231], v[244:247], v[92:95]
	ds_read_b128 v[244:247], v149 offset:52224
	s_waitcnt vmcnt(4)
	s_barrier
	v_readfirstlane_b32 s5, v147
	v_lshl_add_u64 v[168:169], v[144:145], 0, s[62:63]
	s_mov_b32 m0, s5
	v_readfirstlane_b32 s5, v146
	s_waitcnt lgkmcnt(3)
	v_mfma_f32_16x16x32_bf16 v[56:59], v[186:189], v[232:235], v[56:59]
	v_lshl_add_u64 v[182:183], v[142:143], 0, s[62:63]
	v_mfma_f32_16x16x32_bf16 v[100:103], v[190:193], v[232:235], v[100:103]
	v_mfma_f32_16x16x32_bf16 v[104:107], v[194:197], v[232:235], v[104:107]
	global_load_lds_dwordx4 v[168:169], off
	v_lshl_add_u64 v[168:169], v[144:145], 0, s[0:1]
	s_mov_b32 m0, s5
	v_readfirstlane_b32 s5, v152
	v_mfma_f32_16x16x32_bf16 v[112:115], v[202:205], v[232:235], v[112:115]
	s_waitcnt lgkmcnt(2)
	v_mfma_f32_16x16x32_bf16 v[64:67], v[186:189], v[236:239], v[64:67]
	ds_read_b128 v[232:235], v149 offset:53248
	v_mfma_f32_16x16x32_bf16 v[80:83], v[190:193], v[236:239], v[80:83]
	global_load_lds_dwordx4 v[168:169], off
	s_mov_b32 m0, s5
	v_readfirstlane_b32 s5, v154
	v_lshl_add_u64 v[168:169], v[142:143], 0, s[0:1]
	v_mfma_f32_16x16x32_bf16 v[96:99], v[194:197], v[236:239], v[96:99]
	v_mfma_f32_16x16x32_bf16 v[116:119], v[202:205], v[236:239], v[116:119]
	s_waitcnt lgkmcnt(2)
	v_mfma_f32_16x16x32_bf16 v[52:55], v[186:189], v[240:243], v[52:55]
	ds_read_b128 v[236:239], v149 offset:54272
	global_load_lds_dwordx4 v[182:183], off
	s_mov_b32 m0, s5
	v_mfma_f32_16x16x32_bf16 v[68:71], v[190:193], v[240:243], v[68:71]
	v_mfma_f32_16x16x32_bf16 v[108:111], v[194:197], v[240:243], v[108:111]
	v_mfma_f32_16x16x32_bf16 v[120:123], v[202:205], v[240:243], v[120:123]
	global_load_lds_dwordx4 v[168:169], off
	s_waitcnt lgkmcnt(2)
	v_mfma_f32_16x16x32_bf16 v[48:51], v[186:189], v[244:247], v[48:51]
	ds_read_b128 v[240:243], v149 offset:55296
	v_mfma_f32_16x16x32_bf16 v[72:75], v[190:193], v[244:247], v[72:75]
	v_mfma_f32_16x16x32_bf16 v[88:91], v[194:197], v[244:247], v[88:91]
	v_mfma_f32_16x16x32_bf16 v[124:127], v[202:205], v[244:247], v[124:127]
	v_add_u32_e32 v167, 0x10000, v148
	v_or_b32_e32 v168, 0x10000, v150
	s_waitcnt lgkmcnt(2)
; #define BIG_SYNC(N)                                              \
;   asm volatile("s_waitcnt vmcnt(%0)" ::"n"(N) : "memory");       \
;   __builtin_amdgcn_s_barrier();                                  \
;   asm volatile("" ::: "memory");                                 \
;   __builtin_amdgcn_sched_barrier(0);
; template <int NK, bool BNT = false> ...
;     ...
;   auto kstep = [&](int T, int cur, int nxt, bool do_stage) {
;     const unsigned char* sa = smem + cur * BIG_STAGE;
;     bf16x8 af[4], bfr[4];
; #pragma unroll
;     for (int m = 0; m < 4; ++m) af[m] = *reinterpret_cast<const bf16x8*>(sa + aoff + m * 1024);
; #pragma unroll
;     for (int n = 0; n < 4; ++n) bfr[n] = *reinterpret_cast<const bf16x8*>(sa + boff + n * 1024);
;     __builtin_amdgcn_sched_barrier(0);
;     if (do_stage) stage(T + 3, nxt);
; #pragma unroll
;     for (int m = 0; m < 4; ++m)
; #pragma unroll
;       for (int n = 0; n < 4; ++n) acc[m][n] = __builtin_amdgcn_mfma_f32_16x16x32_bf16(af[m], bfr[n], acc[m][n], 0, 0, 0);
;     if (do_stage) {
; #pragma unroll
;       for (int q = 0; q < NG; ++q) {
;         __builtin_amdgcn_sched_group_barrier(0x008, 3, 0);
;         __builtin_amdgcn_sched_group_barrier(0x010, 1, 0);
;       }
;       __builtin_amdgcn_sched_group_barrier(0x008, 16 - 3 * NG, 0);
;     }
;     __builtin_amdgcn_sched_barrier(0);
; #pragma unroll
;     for (int n = 0; n < 4; ++n) bfr[n] = *reinterpret_cast<const bf16x8*>(sa + boff + (4 + n) * 1024);
; #pragma unroll
;     for (int m = 0; m < 4; ++m)
; #pragma unroll
;       for (int n = 0; n < 4; ++n)
;         acc[m][4 + n] = __builtin_amdgcn_mfma_f32_16x16x32_bf16(af[m], bfr[n], acc[m][4 + n], 0, 0, 0);
;     __builtin_amdgcn_sched_barrier(0);
;   };
;     ...
;   for (int it = 0; it < NK / 4 - 1; ++it) {
;     const int t = it * 4;
;     BIG_SYNC(2 * NG); kstep(t, 0, 3, true);
;     BIG_SYNC(2 * NG); kstep(t + 1, 1, 0, true);
;     BIG_SYNC(2 * NG); kstep(t + 2, 2, 1, true);
;     BIG_SYNC(2 * NG); kstep(t + 3, 3, 2, true);
;   }
	v_mfma_f32_16x16x32_bf16 v[0:3], v[186:189], v[232:235], v[0:3]
	ds_read_b128 v[244:247], v149 offset:56320
	v_mfma_f32_16x16x32_bf16 v[16:19], v[190:193], v[232:235], v[16:19]
	ds_read_b128 v[216:219], v167
	v_mfma_f32_16x16x32_bf16 v[32:35], v[194:197], v[232:235], v[32:35]
	ds_read_b128 v[220:223], v167 offset:1024
	v_mfma_f32_16x16x32_bf16 v[60:63], v[202:205], v[232:235], v[60:63]
	ds_read_b128 v[224:227], v167 offset:2048
	s_waitcnt lgkmcnt(5)
	v_mfma_f32_16x16x32_bf16 v[4:7], v[186:189], v[236:239], v[4:7]
	ds_read_b128 v[228:231], v167 offset:3072
	ds_read_b128 v[232:235], v168
	v_mfma_f32_16x16x32_bf16 v[20:23], v[190:193], v[236:239], v[20:23]
	v_mfma_f32_16x16x32_bf16 v[36:39], v[194:197], v[236:239], v[36:39]
	v_mfma_f32_16x16x32_bf16 v[76:79], v[202:205], v[236:239], v[76:79]
	s_waitcnt lgkmcnt(6)
	v_mfma_f32_16x16x32_bf16 v[8:11], v[186:189], v[240:243], v[8:11]
	ds_read_b128 v[236:239], v168 offset:1024
	v_mfma_f32_16x16x32_bf16 v[24:27], v[190:193], v[240:243], v[24:27]
	v_mfma_f32_16x16x32_bf16 v[40:43], v[194:197], v[240:243], v[40:43]
	v_mfma_f32_16x16x32_bf16 v[84:87], v[202:205], v[240:243], v[84:87]
	s_waitcnt lgkmcnt(6)
	v_mfma_f32_16x16x32_bf16 v[12:15], v[186:189], v[244:247], v[12:15]
	ds_read_b128 v[240:243], v168 offset:2048
	v_mfma_f32_16x16x32_bf16 v[28:31], v[190:193], v[244:247], v[28:31]
	v_mfma_f32_16x16x32_bf16 v[44:47], v[194:197], v[244:247], v[44:47]
	v_mfma_f32_16x16x32_bf16 v[92:95], v[202:205], v[244:247], v[92:95]
	ds_read_b128 v[244:247], v168 offset:3072
	s_waitcnt vmcnt(4)
	s_barrier
	v_add_u32_e32 v167, 0x10000, v148
	v_or_b32_e32 v168, 0x10000, v150
	v_add_u32_e32 v169, 0x10400, v150
	v_add_u32_e32 v170, 0x10800, v150
	v_add_u32_e32 v172, 0x10c00, v150
	v_readfirstlane_b32 s5, v155
	v_lshl_add_u64 v[174:175], v[144:145], 0, s[2:3]
	s_mov_b32 m0, s5
	v_readfirstlane_b32 s5, v156
	s_waitcnt lgkmcnt(3)
	v_mfma_f32_16x16x32_bf16 v[56:59], v[216:219], v[232:235], v[56:59]
	v_lshl_add_u64 v[178:179], v[142:143], 0, s[2:3]
	v_mfma_f32_16x16x32_bf16 v[100:103], v[220:223], v[232:235], v[100:103]
	v_mfma_f32_16x16x32_bf16 v[104:107], v[224:227], v[232:235], v[104:107]
	global_load_lds_dwordx4 v[174:175], off
	v_lshl_add_u64 v[174:175], v[144:145], 0, s[52:53]
	s_mov_b32 m0, s5
	v_readfirstlane_b32 s5, v157
	v_mfma_f32_16x16x32_bf16 v[112:115], v[228:231], v[232:235], v[112:115]
	s_waitcnt lgkmcnt(2)
	v_mfma_f32_16x16x32_bf16 v[64:67], v[216:219], v[236:239], v[64:67]
	ds_read_b128 v[232:235], v168 offset:4096
	v_mfma_f32_16x16x32_bf16 v[80:83], v[220:223], v[236:239], v[80:83]
	global_load_lds_dwordx4 v[174:175], off
	s_mov_b32 m0, s5
	v_readfirstlane_b32 s5, v158
	v_lshl_add_u64 v[174:175], v[142:143], 0, s[52:53]
	v_mfma_f32_16x16x32_bf16 v[96:99], v[224:227], v[236:239], v[96:99]
	v_mfma_f32_16x16x32_bf16 v[116:119], v[228:231], v[236:239], v[116:119]
	s_waitcnt lgkmcnt(2)
	v_mfma_f32_16x16x32_bf16 v[52:55], v[216:219], v[240:243], v[52:55]
	ds_read_b128 v[236:239], v168 offset:5120
	global_load_lds_dwordx4 v[178:179], off
	s_mov_b32 m0, s5
	v_mfma_f32_16x16x32_bf16 v[68:71], v[220:223], v[240:243], v[68:71]
	v_mfma_f32_16x16x32_bf16 v[108:111], v[224:227], v[240:243], v[108:111]
	v_mfma_f32_16x16x32_bf16 v[120:123], v[228:231], v[240:243], v[120:123]
	global_load_lds_dwordx4 v[174:175], off
	s_waitcnt lgkmcnt(2)
	v_mfma_f32_16x16x32_bf16 v[48:51], v[216:219], v[244:247], v[48:51]
	ds_read_b128 v[240:243], v168 offset:6144
	v_mfma_f32_16x16x32_bf16 v[72:75], v[220:223], v[244:247], v[72:75]
	v_mfma_f32_16x16x32_bf16 v[88:91], v[224:227], v[244:247], v[88:91]
	v_mfma_f32_16x16x32_bf16 v[124:127], v[228:231], v[244:247], v[124:127]
	v_add_u32_e32 v173, 0x11000, v150
	v_add_u32_e32 v174, 0x11400, v150
	v_add_u32_e32 v175, 0x11800, v150
	v_add_u32_e32 v178, 0x11c00, v150
	v_add_u32_e32 v167, 0x10000, v148
	v_or_b32_e32 v168, 0x10000, v150
	s_waitcnt lgkmcnt(2)
	v_mfma_f32_16x16x32_bf16 v[0:3], v[216:219], v[232:235], v[0:3]
	ds_read_b128 v[244:247], v168 offset:7168
	v_mfma_f32_16x16x32_bf16 v[16:19], v[220:223], v[232:235], v[16:19]
	ds_read_b128 v[186:189], v167 offset:32768
	v_mfma_f32_16x16x32_bf16 v[32:35], v[224:227], v[232:235], v[32:35]
	ds_read_b128 v[190:193], v167 offset:33792
	v_mfma_f32_16x16x32_bf16 v[60:63], v[228:231], v[232:235], v[60:63]
	ds_read_b128 v[194:197], v167 offset:34816
	s_waitcnt lgkmcnt(5)
	v_mfma_f32_16x16x32_bf16 v[4:7], v[216:219], v[236:239], v[4:7]
	ds_read_b128 v[202:205], v167 offset:35840
	ds_read_b128 v[232:235], v168 offset:32768
	v_mfma_f32_16x16x32_bf16 v[20:23], v[220:223], v[236:239], v[20:23]
	v_mfma_f32_16x16x32_bf16 v[36:39], v[224:227], v[236:239], v[36:39]
	v_mfma_f32_16x16x32_bf16 v[76:79], v[228:231], v[236:239], v[76:79]
	s_waitcnt lgkmcnt(6)
	v_mfma_f32_16x16x32_bf16 v[8:11], v[216:219], v[240:243], v[8:11]
	ds_read_b128 v[236:239], v168 offset:33792
	v_mfma_f32_16x16x32_bf16 v[24:27], v[220:223], v[240:243], v[24:27]
	v_mfma_f32_16x16x32_bf16 v[40:43], v[224:227], v[240:243], v[40:43]
	v_mfma_f32_16x16x32_bf16 v[84:87], v[228:231], v[240:243], v[84:87]
	s_waitcnt lgkmcnt(6)
	v_mfma_f32_16x16x32_bf16 v[12:15], v[216:219], v[244:247], v[12:15]
	ds_read_b128 v[240:243], v168 offset:34816
	v_mfma_f32_16x16x32_bf16 v[28:31], v[220:223], v[244:247], v[28:31]
	v_mfma_f32_16x16x32_bf16 v[44:47], v[224:227], v[244:247], v[44:47]
	v_mfma_f32_16x16x32_bf16 v[92:95], v[228:231], v[244:247], v[92:95]
	ds_read_b128 v[244:247], v168 offset:35840
	s_waitcnt vmcnt(4)
	s_barrier
; #define BIG_SYNC(N)                                              \
;   asm volatile("s_waitcnt vmcnt(%0)" ::"n"(N) : "memory");       \
;   __builtin_amdgcn_s_barrier();                                  \
;   asm volatile("" ::: "memory");                                 \
;   __builtin_amdgcn_sched_barrier(0);
; template <int NK, bool BNT = false> ...
;     ...
;   auto kstep = [&](int T, int cur, int nxt, bool do_stage) {
;     const unsigned char* sa = smem + cur * BIG_STAGE;
;     bf16x8 af[4], bfr[4];
; #pragma unroll
;     for (int m = 0; m < 4; ++m) af[m] = *reinterpret_cast<const bf16x8*>(sa + aoff + m * 1024);
; #pragma unroll
;     for (int n = 0; n < 4; ++n) bfr[n] = *reinterpret_cast<const bf16x8*>(sa + boff + n * 1024);
;     __builtin_amdgcn_sched_barrier(0);
;     if (do_stage) stage(T + 3, nxt);
; #pragma unroll
;     for (int m = 0; m < 4; ++m)
; #pragma unroll
;       for (int n = 0; n < 4; ++n) acc[m][n] = __builtin_amdgcn_mfma_f32_16x16x32_bf16(af[m], bfr[n], acc[m][n], 0, 0, 0);
;     if (do_stage) {
; #pragma unroll
;       for (int q = 0; q < NG; ++q) {
;         __builtin_amdgcn_sched_group_barrier(0x008, 3, 0);
;         __builtin_amdgcn_sched_group_barrier(0x010, 1, 0);
;       }
;       __builtin_amdgcn_sched_group_barrier(0x008, 16 - 3 * NG, 0);
;     }
;     __builtin_amdgcn_sched_barrier(0);
; #pragma unroll
;     for (int n = 0; n < 4; ++n) bfr[n] = *reinterpret_cast<const bf16x8*>(sa + boff + (4 + n) * 1024);
; #pragma unroll
;     for (int m = 0; m < 4; ++m)
; #pragma unroll
;       for (int n = 0; n < 4; ++n)
;         acc[m][4 + n] = __builtin_amdgcn_mfma_f32_16x16x32_bf16(af[m], bfr[n], acc[m][4 + n], 0, 0, 0);
;     __builtin_amdgcn_sched_barrier(0);
;   };
;     ...
;   stage(0, 0);
;   stage(1, 1);
;   stage(2, 2);
;   for (int it = 0; it < NK / 4 - 1; ++it) {
;     const int t = it * 4;
;     BIG_SYNC(2 * NG); kstep(t, 0, 3, true);
;     BIG_SYNC(2 * NG); kstep(t + 1, 1, 0, true);
;     BIG_SYNC(2 * NG); kstep(t + 2, 2, 1, true);
;     BIG_SYNC(2 * NG); kstep(t + 3, 3, 2, true);
;   }
;   BIG_SYNC(2 * NG); kstep(NK - 4, 0, 3, true);
;   BIG_SYNC(2 * NG); kstep(NK - 3, 1, 0, false);
;   BIG_SYNC(NG);     kstep(NK - 2, 2, 0, false);
;   BIG_SYNC(0);      kstep(NK - 1, 3, 0, false);
	v_add_u32_e32 v176, 0x18000, v148
	v_or_b32_e32 v179, 0x18000, v150
	v_add_u32_e32 v180, 0x18400, v150
	v_add_u32_e32 v181, 0x18800, v150
	v_add_u32_e32 v182, 0x18c00, v150
	v_readfirstlane_b32 s5, v159
	v_lshl_add_u64 v[248:249], v[144:145], 0, s[54:55]
	s_mov_b32 m0, s5
	v_readfirstlane_b32 s5, v160
	v_lshl_add_u64 v[144:145], v[144:145], 0, s[56:57]
	s_waitcnt lgkmcnt(3)
	v_mfma_f32_16x16x32_bf16 v[56:59], v[186:189], v[232:235], v[56:59]
	v_lshl_add_u64 v[250:251], v[142:143], 0, s[54:55]
	v_lshl_add_u64 v[142:143], v[142:143], 0, s[56:57]
	v_mfma_f32_16x16x32_bf16 v[100:103], v[190:193], v[232:235], v[100:103]
	v_mfma_f32_16x16x32_bf16 v[104:107], v[194:197], v[232:235], v[104:107]
	global_load_lds_dwordx4 v[248:249], off
	s_mov_b32 m0, s5
	v_readfirstlane_b32 s5, v161
	v_mfma_f32_16x16x32_bf16 v[112:115], v[202:205], v[232:235], v[112:115]
	s_waitcnt lgkmcnt(2)
	v_mfma_f32_16x16x32_bf16 v[64:67], v[186:189], v[236:239], v[64:67]
	ds_read_b128 v[232:235], v168 offset:36864
	v_mfma_f32_16x16x32_bf16 v[80:83], v[190:193], v[236:239], v[80:83]
	global_load_lds_dwordx4 v[144:145], off
	s_mov_b32 m0, s5
	v_readfirstlane_b32 s5, v162
	v_mfma_f32_16x16x32_bf16 v[96:99], v[194:197], v[236:239], v[96:99]
	v_mfma_f32_16x16x32_bf16 v[116:119], v[202:205], v[236:239], v[116:119]
	s_waitcnt lgkmcnt(2)
	v_mfma_f32_16x16x32_bf16 v[52:55], v[186:189], v[240:243], v[52:55]
	ds_read_b128 v[236:239], v168 offset:37888
	global_load_lds_dwordx4 v[250:251], off
	s_mov_b32 m0, s5
	v_mfma_f32_16x16x32_bf16 v[68:71], v[190:193], v[240:243], v[68:71]
	v_mfma_f32_16x16x32_bf16 v[108:111], v[194:197], v[240:243], v[108:111]
	v_mfma_f32_16x16x32_bf16 v[120:123], v[202:205], v[240:243], v[120:123]
	global_load_lds_dwordx4 v[142:143], off
	s_waitcnt lgkmcnt(2)
	v_mfma_f32_16x16x32_bf16 v[48:51], v[186:189], v[244:247], v[48:51]
	ds_read_b128 v[240:243], v168 offset:38912
	v_mfma_f32_16x16x32_bf16 v[72:75], v[190:193], v[244:247], v[72:75]
	v_mfma_f32_16x16x32_bf16 v[88:91], v[194:197], v[244:247], v[88:91]
	v_mfma_f32_16x16x32_bf16 v[124:127], v[202:205], v[244:247], v[124:127]
	v_add_u32_e32 v142, 0x19000, v150
	v_add_u32_e32 v143, 0x19400, v150
	v_add_u32_e32 v144, 0x19800, v150
	v_add_u32_e32 v145, 0x19c00, v150
	s_waitcnt lgkmcnt(2)
	v_mfma_f32_16x16x32_bf16 v[0:3], v[186:189], v[232:235], v[0:3]
	ds_read_b128 v[244:247], v168 offset:39936
	v_mfma_f32_16x16x32_bf16 v[16:19], v[190:193], v[232:235], v[16:19]
	ds_read_b128 v[216:219], v148
	v_mfma_f32_16x16x32_bf16 v[32:35], v[194:197], v[232:235], v[32:35]
	ds_read_b128 v[220:223], v148 offset:1024
	v_mfma_f32_16x16x32_bf16 v[60:63], v[202:205], v[232:235], v[60:63]
	ds_read_b128 v[224:227], v148 offset:2048
	s_waitcnt lgkmcnt(5)
	v_mfma_f32_16x16x32_bf16 v[4:7], v[186:189], v[236:239], v[4:7]
	ds_read_b128 v[228:231], v148 offset:3072
	ds_read_b128 v[232:235], v149 offset:16384
	v_mfma_f32_16x16x32_bf16 v[20:23], v[190:193], v[236:239], v[20:23]
	v_mfma_f32_16x16x32_bf16 v[36:39], v[194:197], v[236:239], v[36:39]
	v_mfma_f32_16x16x32_bf16 v[76:79], v[202:205], v[236:239], v[76:79]
	s_waitcnt lgkmcnt(6)
	v_mfma_f32_16x16x32_bf16 v[8:11], v[186:189], v[240:243], v[8:11]
	ds_read_b128 v[236:239], v149 offset:17408
	v_mfma_f32_16x16x32_bf16 v[24:27], v[190:193], v[240:243], v[24:27]
	v_mfma_f32_16x16x32_bf16 v[40:43], v[194:197], v[240:243], v[40:43]
	v_mfma_f32_16x16x32_bf16 v[84:87], v[202:205], v[240:243], v[84:87]
	s_waitcnt lgkmcnt(6)
	v_mfma_f32_16x16x32_bf16 v[12:15], v[186:189], v[244:247], v[12:15]
	ds_read_b128 v[240:243], v149 offset:18432
	v_mfma_f32_16x16x32_bf16 v[28:31], v[190:193], v[244:247], v[28:31]
	v_mfma_f32_16x16x32_bf16 v[44:47], v[194:197], v[244:247], v[44:47]
	v_mfma_f32_16x16x32_bf16 v[92:95], v[202:205], v[244:247], v[92:95]
	ds_read_b128 v[244:247], v149 offset:19456
	s_add_u32 s6, s6, 0x8000
	s_addc_u32 s7, s7, 0
	s_cmp_lg_u32 s6, 0x38000
	s_cbranch_scc1 .LBB0_302
	s_waitcnt vmcnt(4)
	s_barrier
	s_sext_i32_i8 s4, s4
	s_mov_b64 s[6:7], 0x3e000
	v_readfirstlane_b32 s5, v163
	v_lshl_add_u64 v[198:199], v[136:137], 0, s[6:7]
	v_lshl_add_u64 v[200:201], v[134:135], 0, s[6:7]
	s_mov_b32 m0, s5
	s_mov_b64 s[6:7], 0x7e000
	v_readfirstlane_b32 s5, v164
	v_lshl_add_u64 v[136:137], v[136:137], 0, s[6:7]
	s_waitcnt lgkmcnt(3)
	v_mfma_f32_16x16x32_bf16 v[56:59], v[216:219], v[232:235], v[56:59]
	v_lshl_add_u64 v[134:135], v[134:135], 0, s[6:7]
	v_mfma_f32_16x16x32_bf16 v[100:103], v[220:223], v[232:235], v[100:103]
	v_mfma_f32_16x16x32_bf16 v[104:107], v[224:227], v[232:235], v[104:107]
	global_load_lds_dwordx4 v[198:199], off
	s_mov_b32 m0, s5
	v_readfirstlane_b32 s5, v165
	v_mfma_f32_16x16x32_bf16 v[112:115], v[228:231], v[232:235], v[112:115]
	s_waitcnt lgkmcnt(2)
	v_mfma_f32_16x16x32_bf16 v[64:67], v[216:219], v[236:239], v[64:67]
	ds_read_b128 v[232:235], v149 offset:20480
	v_mfma_f32_16x16x32_bf16 v[80:83], v[220:223], v[236:239], v[80:83]
	global_load_lds_dwordx4 v[136:137], off
	s_mov_b32 m0, s5
	v_readfirstlane_b32 s5, v166
	v_mfma_f32_16x16x32_bf16 v[96:99], v[224:227], v[236:239], v[96:99]
	v_mfma_f32_16x16x32_bf16 v[116:119], v[228:231], v[236:239], v[116:119]
	s_waitcnt lgkmcnt(2)
	v_mfma_f32_16x16x32_bf16 v[52:55], v[216:219], v[240:243], v[52:55]
	ds_read_b128 v[236:239], v149 offset:21504
	global_load_lds_dwordx4 v[200:201], off
	s_mov_b32 m0, s5
	v_mfma_f32_16x16x32_bf16 v[68:71], v[220:223], v[240:243], v[68:71]
	v_mfma_f32_16x16x32_bf16 v[108:111], v[224:227], v[240:243], v[108:111]
	v_mfma_f32_16x16x32_bf16 v[120:123], v[228:231], v[240:243], v[120:123]
	global_load_lds_dwordx4 v[134:135], off
	s_waitcnt lgkmcnt(2)
; #define BIG_SYNC(N)                                              \
;   asm volatile("s_waitcnt vmcnt(%0)" ::"n"(N) : "memory");       \
;   __builtin_amdgcn_s_barrier();                                  \
;   asm volatile("" ::: "memory");                                 \
;   __builtin_amdgcn_sched_barrier(0);
; template <int NK, bool BNT = false> ...
;     ...
;   auto kstep = [&](int T, int cur, int nxt, bool do_stage) {
;     const unsigned char* sa = smem + cur * BIG_STAGE;
;     bf16x8 af[4], bfr[4];
; #pragma unroll
;     for (int m = 0; m < 4; ++m) af[m] = *reinterpret_cast<const bf16x8*>(sa + aoff + m * 1024);
; #pragma unroll
;     for (int n = 0; n < 4; ++n) bfr[n] = *reinterpret_cast<const bf16x8*>(sa + boff + n * 1024);
;     __builtin_amdgcn_sched_barrier(0);
;     if (do_stage) stage(T + 3, nxt);
; #pragma unroll
;     for (int m = 0; m < 4; ++m)
; #pragma unroll
;       for (int n = 0; n < 4; ++n) acc[m][n] = __builtin_amdgcn_mfma_f32_16x16x32_bf16(af[m], bfr[n], acc[m][n], 0, 0, 0);
;     if (do_stage) {
; #pragma unroll
;       for (int q = 0; q < NG; ++q) {
;         __builtin_amdgcn_sched_group_barrier(0x008, 3, 0);
;         __builtin_amdgcn_sched_group_barrier(0x010, 1, 0);
;       }
;       __builtin_amdgcn_sched_group_barrier(0x008, 16 - 3 * NG, 0);
;     }
;     __builtin_amdgcn_sched_barrier(0);
; #pragma unroll
;     for (int n = 0; n < 4; ++n) bfr[n] = *reinterpret_cast<const bf16x8*>(sa + boff + (4 + n) * 1024);
; #pragma unroll
;     for (int m = 0; m < 4; ++m)
; #pragma unroll
;       for (int n = 0; n < 4; ++n)
;         acc[m][4 + n] = __builtin_amdgcn_mfma_f32_16x16x32_bf16(af[m], bfr[n], acc[m][4 + n], 0, 0, 0);
;     __builtin_amdgcn_sched_barrier(0);
;   };
;     ...
;   BIG_SYNC(2 * NG); kstep(NK - 4, 0, 3, true);
;   BIG_SYNC(2 * NG); kstep(NK - 3, 1, 0, false);
;   BIG_SYNC(NG);     kstep(NK - 2, 2, 0, false);
;   BIG_SYNC(0);      kstep(NK - 1, 3, 0, false);
	v_mfma_f32_16x16x32_bf16 v[48:51], v[216:219], v[244:247], v[48:51]
	ds_read_b128 v[240:243], v149 offset:22528
	v_mfma_f32_16x16x32_bf16 v[72:75], v[220:223], v[244:247], v[72:75]
	v_mfma_f32_16x16x32_bf16 v[88:91], v[224:227], v[244:247], v[88:91]
	v_mfma_f32_16x16x32_bf16 v[124:127], v[228:231], v[244:247], v[124:127]
	s_waitcnt lgkmcnt(2)
	v_mfma_f32_16x16x32_bf16 v[0:3], v[216:219], v[232:235], v[0:3]
	ds_read_b128 v[244:247], v149 offset:23552
	v_mfma_f32_16x16x32_bf16 v[16:19], v[220:223], v[232:235], v[16:19]
	ds_read_b128 v[186:189], v148 offset:32768
	v_mfma_f32_16x16x32_bf16 v[32:35], v[224:227], v[232:235], v[32:35]
	ds_read_b128 v[190:193], v148 offset:33792
	v_mfma_f32_16x16x32_bf16 v[60:63], v[228:231], v[232:235], v[60:63]
	ds_read_b128 v[194:197], v148 offset:34816
	s_waitcnt lgkmcnt(5)
	v_mfma_f32_16x16x32_bf16 v[4:7], v[216:219], v[236:239], v[4:7]
	ds_read_b128 v[202:205], v148 offset:35840
	ds_read_b128 v[232:235], v149 offset:49152
	v_mfma_f32_16x16x32_bf16 v[20:23], v[220:223], v[236:239], v[20:23]
	v_mfma_f32_16x16x32_bf16 v[36:39], v[224:227], v[236:239], v[36:39]
	v_mfma_f32_16x16x32_bf16 v[76:79], v[228:231], v[236:239], v[76:79]
	s_waitcnt lgkmcnt(6)
	v_mfma_f32_16x16x32_bf16 v[8:11], v[216:219], v[240:243], v[8:11]
	ds_read_b128 v[236:239], v149 offset:50176
	v_mfma_f32_16x16x32_bf16 v[24:27], v[220:223], v[240:243], v[24:27]
	v_mfma_f32_16x16x32_bf16 v[40:43], v[224:227], v[240:243], v[40:43]
	v_mfma_f32_16x16x32_bf16 v[84:87], v[228:231], v[240:243], v[84:87]
	s_waitcnt lgkmcnt(6)
	v_mfma_f32_16x16x32_bf16 v[12:15], v[216:219], v[244:247], v[12:15]
	ds_read_b128 v[240:243], v149 offset:51200
	v_mfma_f32_16x16x32_bf16 v[28:31], v[220:223], v[244:247], v[28:31]
	v_mfma_f32_16x16x32_bf16 v[44:47], v[224:227], v[244:247], v[44:47]
	v_mfma_f32_16x16x32_bf16 v[92:95], v[228:231], v[244:247], v[92:95]
	ds_read_b128 v[244:247], v149 offset:52224
	s_waitcnt vmcnt(4)
	s_barrier
	s_waitcnt lgkmcnt(3)
	v_mfma_f32_16x16x32_bf16 v[56:59], v[186:189], v[232:235], v[56:59]
	v_mfma_f32_16x16x32_bf16 v[100:103], v[190:193], v[232:235], v[100:103]
	v_mfma_f32_16x16x32_bf16 v[104:107], v[194:197], v[232:235], v[104:107]
	v_mfma_f32_16x16x32_bf16 v[112:115], v[202:205], v[232:235], v[112:115]
	s_waitcnt lgkmcnt(2)
	v_mfma_f32_16x16x32_bf16 v[64:67], v[186:189], v[236:239], v[64:67]
	ds_read_b128 v[232:235], v149 offset:53248
	v_mfma_f32_16x16x32_bf16 v[80:83], v[190:193], v[236:239], v[80:83]
	v_mfma_f32_16x16x32_bf16 v[96:99], v[194:197], v[236:239], v[96:99]
	v_mfma_f32_16x16x32_bf16 v[116:119], v[202:205], v[236:239], v[116:119]
	s_waitcnt lgkmcnt(2)
	v_mfma_f32_16x16x32_bf16 v[52:55], v[186:189], v[240:243], v[52:55]
	ds_read_b128 v[236:239], v149 offset:54272
	v_mfma_f32_16x16x32_bf16 v[68:71], v[190:193], v[240:243], v[68:71]
	v_mfma_f32_16x16x32_bf16 v[108:111], v[194:197], v[240:243], v[108:111]
	v_mfma_f32_16x16x32_bf16 v[120:123], v[202:205], v[240:243], v[120:123]
	s_waitcnt lgkmcnt(2)
	v_mfma_f32_16x16x32_bf16 v[48:51], v[186:189], v[244:247], v[48:51]
	ds_read_b128 v[240:243], v149 offset:55296
	v_mfma_f32_16x16x32_bf16 v[72:75], v[190:193], v[244:247], v[72:75]
	v_mfma_f32_16x16x32_bf16 v[88:91], v[194:197], v[244:247], v[88:91]
	v_mfma_f32_16x16x32_bf16 v[124:127], v[202:205], v[244:247], v[124:127]
	s_waitcnt lgkmcnt(2)
	v_mfma_f32_16x16x32_bf16 v[0:3], v[186:189], v[232:235], v[0:3]
	ds_read_b128 v[244:247], v149 offset:56320
	v_mfma_f32_16x16x32_bf16 v[16:19], v[190:193], v[232:235], v[16:19]
	v_mfma_f32_16x16x32_bf16 v[32:35], v[194:197], v[232:235], v[32:35]
	v_mfma_f32_16x16x32_bf16 v[60:63], v[202:205], v[232:235], v[60:63]
	s_waitcnt lgkmcnt(2)
	v_mfma_f32_16x16x32_bf16 v[4:7], v[186:189], v[236:239], v[4:7]
	v_mfma_f32_16x16x32_bf16 v[20:23], v[190:193], v[236:239], v[20:23]
	v_mfma_f32_16x16x32_bf16 v[36:39], v[194:197], v[236:239], v[36:39]
	v_mfma_f32_16x16x32_bf16 v[76:79], v[202:205], v[236:239], v[76:79]
	s_waitcnt lgkmcnt(1)
	v_mfma_f32_16x16x32_bf16 v[8:11], v[186:189], v[240:243], v[8:11]
	v_mfma_f32_16x16x32_bf16 v[24:27], v[190:193], v[240:243], v[24:27]
	v_mfma_f32_16x16x32_bf16 v[40:43], v[194:197], v[240:243], v[40:43]
	v_mfma_f32_16x16x32_bf16 v[84:87], v[202:205], v[240:243], v[84:87]
	s_waitcnt lgkmcnt(0)
	v_mfma_f32_16x16x32_bf16 v[12:15], v[186:189], v[244:247], v[12:15]
	v_mfma_f32_16x16x32_bf16 v[28:31], v[190:193], v[244:247], v[28:31]
	v_mfma_f32_16x16x32_bf16 v[44:47], v[194:197], v[244:247], v[44:47]
	v_mfma_f32_16x16x32_bf16 v[92:95], v[202:205], v[244:247], v[92:95]
	v_mov_b32_e32 v186, 0xf149f2ca
	v_mov_b32_e32 v187, 0x3c0881c4
	v_mov_b32_e32 v188, 0xbab64f3b
	v_mov_b32_e32 v189, 0x24800
	v_mov_b32_e32 v190, 1
	v_mov_b32_e32 v191, 0x24804
	v_mov_b32_e32 v192, 0xfcf
	v_mov_b32_e32 v193, 0x7cf
	v_mov_b32_e32 v194, 0xfdf
	v_mov_b32_e32 v195, 0x7df
	v_mov_b32_e32 v196, 0xfef
	v_mov_b32_e32 v197, 0x7ef
	v_mov_b32_e32 v198, 0xfff
	v_mov_b32_e32 v199, 0x7ff
	v_mov_b32_e32 v200, 0x20000
	v_mov_b32_e32 v201, 0xf8f
	v_mov_b32_e32 v202, 0x78f
	v_mov_b32_e32 v203, 0xf9f
	v_mov_b32_e32 v204, 0x79f
	v_mov_b32_e32 v205, 0xfaf
	s_waitcnt vmcnt(4)
	s_barrier
; #define BIG_SYNC(N)                                              \
;   asm volatile("s_waitcnt vmcnt(%0)" ::"n"(N) : "memory");       \
;   __builtin_amdgcn_s_barrier();                                  \
;   asm volatile("" ::: "memory");                                 \
;   __builtin_amdgcn_sched_barrier(0);
; template <int NK, bool BNT = false> ...
;     ...
;   BIG_SYNC(NG);     kstep(NK - 2, 2, 0, false);
;   BIG_SYNC(0);      kstep(NK - 1, 3, 0, false);
; template <int MODE, int NSUB>
; __device__ __forceinline__ void epilogue(const Params& p, int layer, f32x4 (&acc)[4][NSUB], int tm, int tn, int g,
;                                          const float* s_rstd, const int tid_in) {
;     ...
;   if constexpr (MODE == EPI_G1) {
;     const int ft = tm;
; #pragma unroll
;     for (int n = 0; n < NSUB; ++n) {
;       const int nl = wc * (NSUB * 16) + n * 16 + fr;
;       const int t = tn * (NSUB * 32) + nl;
;       const float rs = s_rstd[nl];
;       if (ft < 2) {
; #pragma unroll
;         for (int m = 0; m < 4; ++m) {
;           int gg = ft * 8 + wr * 4 + m;
;           bf16x4 v = pack4(acc[m][n][0] * rs, acc[m][n][1] * rs, acc[m][n][2] * rs, acc[m][n][3] * rs);
;           *reinterpret_cast<bf16x4*>(p.ug + (long)gg * NT * 16 + blk(t >> 5, (t & 31) * 16 + fq * 4, 16)) = v;
;         }
;       } else if (ft < 4) {
	ds_read_b128 v[134:137], v167
	ds_read_b128 v[138:141], v167 offset:1024
	ds_read_b128 v[154:157], v167 offset:2048
	ds_read_b128 v[158:161], v167 offset:3072
	ds_read_b128 v[162:165], v168
	ds_read_b128 v[166:169], v169
	ds_read_b128 v[216:219], v170
	ds_read_b128 v[220:223], v172
	s_waitcnt lgkmcnt(0)
	v_mfma_f32_16x16x32_bf16 v[56:59], v[134:137], v[162:165], v[56:59]
	v_mfma_f32_16x16x32_bf16 v[64:67], v[134:137], v[166:169], v[64:67]
	v_mfma_f32_16x16x32_bf16 v[52:55], v[134:137], v[216:219], v[52:55]
	v_mfma_f32_16x16x32_bf16 v[48:51], v[134:137], v[220:223], v[48:51]
	v_mfma_f32_16x16x32_bf16 v[100:103], v[138:141], v[162:165], v[100:103]
	v_mfma_f32_16x16x32_bf16 v[80:83], v[138:141], v[166:169], v[80:83]
	v_mfma_f32_16x16x32_bf16 v[68:71], v[138:141], v[216:219], v[68:71]
	v_mfma_f32_16x16x32_bf16 v[72:75], v[138:141], v[220:223], v[72:75]
	v_mfma_f32_16x16x32_bf16 v[96:99], v[154:157], v[166:169], v[96:99]
	v_mfma_f32_16x16x32_bf16 v[112:115], v[158:161], v[162:165], v[112:115]
	v_mfma_f32_16x16x32_bf16 v[224:227], v[154:157], v[162:165], v[104:107]
	v_mfma_f32_16x16x32_bf16 v[228:231], v[154:157], v[216:219], v[108:111]
	v_mfma_f32_16x16x32_bf16 v[232:235], v[154:157], v[220:223], v[88:91]
	v_mfma_f32_16x16x32_bf16 v[162:165], v[158:161], v[166:169], v[116:119]
	v_mfma_f32_16x16x32_bf16 v[166:169], v[158:161], v[216:219], v[120:123]
	v_mfma_f32_16x16x32_bf16 v[216:219], v[158:161], v[220:223], v[124:127]
	ds_read_b128 v[88:91], v173
	ds_read_b128 v[104:107], v174
	ds_read_b128 v[108:111], v175
	ds_read_b128 v[116:119], v178
	s_waitcnt lgkmcnt(0)
	v_mfma_f32_16x16x32_bf16 v[0:3], v[134:137], v[88:91], v[0:3]
	v_mfma_f32_16x16x32_bf16 v[4:7], v[134:137], v[104:107], v[4:7]
	v_mfma_f32_16x16x32_bf16 v[8:11], v[134:137], v[108:111], v[8:11]
	v_mfma_f32_16x16x32_bf16 v[12:15], v[134:137], v[116:119], v[12:15]
	v_mfma_f32_16x16x32_bf16 v[16:19], v[138:141], v[88:91], v[16:19]
	v_mfma_f32_16x16x32_bf16 v[20:23], v[138:141], v[104:107], v[20:23]
	v_mfma_f32_16x16x32_bf16 v[24:27], v[138:141], v[108:111], v[24:27]
	v_mfma_f32_16x16x32_bf16 v[134:137], v[138:141], v[116:119], v[28:31]
	v_mfma_f32_16x16x32_bf16 v[32:35], v[154:157], v[88:91], v[32:35]
	v_mfma_f32_16x16x32_bf16 v[36:39], v[154:157], v[104:107], v[36:39]
	v_mfma_f32_16x16x32_bf16 v[138:141], v[154:157], v[108:111], v[40:43]
	v_mfma_f32_16x16x32_bf16 v[154:157], v[154:157], v[116:119], v[44:47]
	v_mfma_f32_16x16x32_bf16 v[172:175], v[158:161], v[88:91], v[60:63]
	v_mfma_f32_16x16x32_bf16 v[220:223], v[158:161], v[104:107], v[76:79]
	v_mfma_f32_16x16x32_bf16 v[236:239], v[158:161], v[108:111], v[84:87]
	v_mfma_f32_16x16x32_bf16 v[158:161], v[158:161], v[116:119], v[92:95]
	s_waitcnt vmcnt(0)
	s_barrier
	ds_read_b128 v[40:43], v176
	ds_read_b128 v[28:31], v179
	ds_read_b128 v[44:47], v180
	ds_read_b128 v[60:63], v181
	ds_read_b128 v[240:243], v176 offset:1024
	ds_read_b128 v[244:247], v176 offset:2048
	ds_read_b128 v[248:251], v176 offset:3072
	ds_read_b128 v[178:181], v182
	s_waitcnt lgkmcnt(0)
	v_mfma_f32_16x16x32_bf16 v[124:127], v[40:43], v[28:31], v[56:59]
	v_mfma_f32_16x16x32_bf16 v[108:111], v[40:43], v[44:47], v[64:67]
	v_mfma_f32_16x16x32_bf16 v[92:95], v[40:43], v[60:63], v[52:55]
	v_mfma_f32_16x16x32_bf16 v[76:79], v[40:43], v[178:181], v[48:51]
	v_mfma_f32_16x16x32_bf16 v[120:123], v[240:243], v[28:31], v[100:103]
	v_mfma_f32_16x16x32_bf16 v[104:107], v[240:243], v[44:47], v[80:83]
	v_mfma_f32_16x16x32_bf16 v[88:91], v[240:243], v[60:63], v[68:71]
	v_mfma_f32_16x16x32_bf16 v[72:75], v[240:243], v[178:181], v[72:75]
	v_mfma_f32_16x16x32_bf16 v[116:119], v[244:247], v[28:31], v[224:227]
	v_mfma_f32_16x16x32_bf16 v[100:103], v[244:247], v[44:47], v[96:99]
	v_mfma_f32_16x16x32_bf16 v[84:87], v[244:247], v[60:63], v[228:231]
	v_mfma_f32_16x16x32_bf16 v[68:71], v[244:247], v[178:181], v[232:235]
	v_mfma_f32_16x16x32_bf16 v[112:115], v[248:251], v[28:31], v[112:115]
	v_mfma_f32_16x16x32_bf16 v[96:99], v[248:251], v[44:47], v[162:165]
	v_mfma_f32_16x16x32_bf16 v[80:83], v[248:251], v[60:63], v[166:169]
	v_mfma_f32_16x16x32_bf16 v[64:67], v[248:251], v[178:181], v[216:219]
	ds_read_b128 v[48:51], v142
	ds_read_b128 v[162:165], v143
	s_waitcnt lgkmcnt(0)
	v_mfma_f32_16x16x32_bf16 v[60:63], v[40:43], v[48:51], v[0:3]
	s_nop 2
	ds_read_b128 v[0:3], v144
	ds_read_b128 v[142:145], v145
	v_mfma_f32_16x16x32_bf16 v[44:47], v[40:43], v[162:165], v[4:7]
	s_waitcnt lgkmcnt(0)
	v_mfma_f32_16x16x32_bf16 v[28:31], v[40:43], v[0:3], v[8:11]
	v_mfma_f32_16x16x32_bf16 v[12:15], v[40:43], v[142:145], v[12:15]
	v_mfma_f32_16x16x32_bf16 v[56:59], v[240:243], v[48:51], v[16:19]
	v_mfma_f32_16x16x32_bf16 v[40:43], v[240:243], v[162:165], v[20:23]
	v_mfma_f32_16x16x32_bf16 v[24:27], v[240:243], v[0:3], v[24:27]
	v_mfma_f32_16x16x32_bf16 v[8:11], v[240:243], v[142:145], v[134:137]
	v_mfma_f32_16x16x32_bf16 v[52:55], v[244:247], v[48:51], v[32:35]
	v_mfma_f32_16x16x32_bf16 v[36:39], v[244:247], v[162:165], v[36:39]
	v_mfma_f32_16x16x32_bf16 v[20:23], v[244:247], v[0:3], v[138:141]
	v_mfma_f32_16x16x32_bf16 v[4:7], v[244:247], v[142:145], v[154:157]
	v_mfma_f32_16x16x32_bf16 v[48:51], v[248:251], v[48:51], v[172:175]
	v_mfma_f32_16x16x32_bf16 v[32:35], v[248:251], v[162:165], v[220:223]
	v_mfma_f32_16x16x32_bf16 v[16:19], v[248:251], v[0:3], v[236:239]
	v_mfma_f32_16x16x32_bf16 v[0:3], v[248:251], v[142:145], v[158:161]
	v_mov_b32_e32 v141, v215
	v_lshl_add_u32 v142, s4, 1, v151
	v_and_b32_e32 v140, 15, v141
	v_lshlrev_b32_e32 v134, 1, v141
	v_and_or_b32 v155, v134, s34, v140
	v_lshl_or_b32 v139, v155, 2, v200
	v_and_b32_e32 v134, 16, v141
	v_lshrrev_b32_e32 v138, 2, v141
	ds_read_b32 v146, v139
	v_ashrrev_i32_e32 v136, 7, v141
	v_and_or_b32 v134, v138, 8, v134
	v_lshlrev_b32_e32 v138, 7, v142
	v_lshl_add_u32 v138, v136, 6, v138
	v_bfe_u32 v137, v141, 4, 2
	v_add_u32_e32 v154, 0xfffffe00, v138
	v_or_b32_e32 v138, v138, v134
	v_cmp_lt_i32_e64 s[14:15], 1, v142
	v_cmp_lt_u32_e64 s[12:13], 3, v142
	v_cmp_lt_u32_e64 s[10:11], 5, v142
	v_cmp_ne_u32_e64 s[8:9], 6, v142
	v_cmp_gt_u32_e64 s[6:7], s34, v141
	v_lshlrev_b32_e32 v135, 2, v137
	v_cmp_eq_u32_e64 s[4:5], 0, v137
	v_ashrrev_i32_e32 v137, 31, v136
	v_lshlrev_b32_e32 v152, 1, v142
	v_add_u32_e32 v138, 0xffffff00, v138
	v_or_b32_e32 v144, s48, v155
	s_and_saveexec_b64 s[18:19], s[14:15]
	s_xor_b64 s[36:37], exec, s[18:19]
	s_cbranch_execz .LBB0_323
; __device__ __forceinline__ int widen_off(int fq) { return ((fq & 1) << 4) + ((fq >> 1) << 3); }
; template <int MODE, int NSUB>
; __device__ __forceinline__ void epilogue(const Params& p, int layer, f32x4 (&acc)[4][NSUB], int tm, int tn, int g,
;                                          const float* s_rstd, const int tid_in) {
;     ...
;       } else {
;         if (wr == 0) {
;           const int pos = tok_pos(t);
;           float o1[4], o2[4];
; #pragma unroll
;           for (int j = 0; j < 4; ++j) {
;             float2 cs = p.rope[pos * 16 + fq * 4 + j];
;             float x1 = acc[0][n][j] * rs, x2 = acc[1][n][j] * rs;
;             o1[j] = x1 * cs.x - x2 * cs.y;
;             o2[j] = x1 * cs.y + x2 * cs.x;
;           }
;           const u32x4 w = widen_pair(pack4(o1[0], o1[1], o1[2], o1[3]), pack4(o2[0], o2[1], o2[2], o2[3]));
; #pragma unroll
;           for (int hh = 0; hh < 8; ++hh)
;             __builtin_nontemporal_store(w, reinterpret_cast<u32x4*>(p.Kb + ((long)hh * NT + t) * 96 + 64 + widen_off(fq)));
;         }
	s_and_saveexec_b64 s[18:19], s[12:13]
	s_xor_b64 s[38:39], exec, s[18:19]
	s_cbranch_execz .LBB0_320
	s_and_saveexec_b64 s[18:19], s[10:11]
	s_xor_b64 s[40:41], exec, s[18:19]
	s_cbranch_execz .LBB0_315
	s_and_saveexec_b64 s[18:19], s[8:9]
	s_xor_b64 s[42:43], exec, s[18:19]
	s_cbranch_execz .LBB0_310
	s_and_saveexec_b64 s[44:45], s[6:7]
	s_cbranch_execz .LBB0_309
	s_mov_b32 s17, 0x10000
	v_cmp_gt_i32_e32 vcc, s17, v144
	v_lshlrev_b32_e32 v113, 3, v135
	v_readlane_b32 s64, v254, 51
	v_cndmask_b32_e32 v112, v201, v202, vcc
	v_and_b32_e32 v112, v112, v144
	v_lshl_or_b32 v116, v112, 7, v113
	v_readlane_b32 s70, v254, 57
	v_readlane_b32 s71, v254, 58
	s_nop 4
	global_load_dwordx4 v[112:115], v116, s[70:71] offset:16
	s_nop 0
	global_load_dwordx4 v[116:119], v116, s[70:71]
	v_mov_b32_e32 v161, v121
	v_mov_b32_e32 v121, v125
	v_mov_b32_e32 v160, v124
	s_waitcnt lgkmcnt(0)
	v_pk_mul_f32 v[120:121], v[120:121], v[146:147] op_sel_hi:[1,0]
	v_pk_mul_f32 v[160:161], v[160:161], v[146:147] op_sel_hi:[1,0]
	v_readlane_b32 s65, v254, 52
	v_readlane_b32 s66, v254, 53
	v_readlane_b32 s67, v254, 54
	v_readlane_b32 s68, v254, 55
	v_readlane_b32 s69, v254, 56
	v_readlane_b32 s72, v254, 59
	v_readlane_b32 s73, v254, 60
	v_readlane_b32 s74, v254, 61
	v_readlane_b32 s75, v254, 62
	v_readlane_b32 s76, v254, 63
	v_readlane_b32 s77, v252, 0
	v_readlane_b32 s78, v252, 1
	v_readlane_b32 s79, v252, 2
	v_readlane_b32 s64, v252, 4
	v_readlane_b32 s68, v252, 8
	v_readlane_b32 s69, v252, 9
	s_movk_i32 s17, 0xc0
	v_readlane_b32 s65, v252, 5
	v_readlane_b32 s66, v252, 6
	v_readlane_b32 s67, v252, 7
	v_readlane_b32 s70, v252, 10
	v_readlane_b32 s71, v252, 11
	v_readlane_b32 s72, v252, 12
	v_readlane_b32 s73, v252, 13
	v_readlane_b32 s74, v252, 14
	v_readlane_b32 s75, v252, 15
	v_readlane_b32 s76, v252, 16
	v_readlane_b32 s77, v252, 17
	v_readlane_b32 s78, v252, 18
	v_readlane_b32 s79, v252, 19
	s_waitcnt vmcnt(0)
	v_mov_b32_e32 v159, v114
	v_mov_b32_e32 v124, v116
	v_mov_b32_e32 v125, v119
	v_mov_b32_e32 v156, v117
	v_mov_b32_e32 v157, v118
	v_pk_mul_f32 v[124:125], v[120:121], v[124:125]
	v_mov_b32_e32 v163, v118
	v_pk_fma_f32 v[124:125], v[160:161], v[156:157], v[124:125]
	v_mov_b32_e32 v157, v121
	v_mov_b32_e32 v121, v161
	v_mov_b32_e32 v118, v117
	v_mov_b32_e32 v162, v116
	v_pk_mul_f32 v[116:117], v[120:121], v[118:119]
	v_mov_b32_e32 v118, v126
	v_mov_b32_e32 v119, v123
	v_mov_b32_e32 v123, v127
	v_mov_b32_e32 v156, v160
	v_pk_mul_f32 v[118:119], v[118:119], v[146:147] op_sel_hi:[1,0]
	v_pk_mul_f32 v[120:121], v[122:123], v[146:147] op_sel_hi:[1,0]
	v_mov_b32_e32 v122, v112
	v_mov_b32_e32 v123, v115
	v_pk_fma_f32 v[116:117], v[156:157], v[162:163], v[116:117] neg_lo:[0,0,1] neg_hi:[0,0,1]
	v_pk_mul_f32 v[122:123], v[120:121], v[122:123]
	v_mov_b32_e32 v127, v121
	v_mov_b32_e32 v157, v114
	v_mov_b32_e32 v121, v119
	v_mov_b32_e32 v114, v113
	v_mov_b32_e32 v158, v113
	v_mov_b32_e32 v126, v118
	v_mov_b32_e32 v156, v112
	v_pk_mul_f32 v[112:113], v[120:121], v[114:115]
	v_pk_fma_f32 v[122:123], v[118:119], v[158:159], v[122:123]
	v_pk_fma_f32 v[114:115], v[126:127], v[156:157], v[112:113] neg_lo:[0,0,1] neg_hi:[0,0,1]
	v_cvt_pk_bf16_f32 v112, v116, v117
	v_mov_b64_e32 v[116:117], s[68:69]
	v_mad_i64_i32 v[116:117], s[18:19], v144, s17, v[116:117]
	v_lshlrev_b32_e32 v118, 1, v134
	v_mov_b32_e32 v119, v153
	v_lshl_add_u64 v[116:117], v[116:117], 0, v[118:119]
	s_mov_b32 s17, 0xf00000
	v_cvt_pk_bf16_f32 v113, v114, v115
	v_cvt_pk_bf16_f32 v114, v124, v125
	v_cvt_pk_bf16_f32 v115, v122, v123
	v_add_co_u32_e32 v118, vcc, s17, v116
	v_permlane16_swap_b32_e32 v112, v114
	v_permlane16_swap_b32_e32 v113, v115
	v_addc_co_u32_e32 v119, vcc, 0, v117, vcc
	s_mov_b32 s17, 0x1e00000
	global_store_dwordx4 v[118:119], v[112:115], off offset:128 nt
	v_add_co_u32_e32 v118, vcc, s17, v116
	s_mov_b32 s17, 0x2d00000
	s_nop 0
	v_addc_co_u32_e32 v119, vcc, 0, v117, vcc
	global_store_dwordx4 v[118:119], v[112:115], off offset:128 nt
	v_add_co_u32_e32 v118, vcc, s17, v116
	global_store_dwordx4 v[116:117], v[112:115], off offset:128 nt
	s_nop 0
	v_addc_co_u32_e32 v119, vcc, 0, v117, vcc
	global_store_dwordx4 v[118:119], v[112:115], off offset:128 nt
	v_add_co_u32_e32 v118, vcc, 0x3c00000, v116
	s_nop 1
	v_addc_co_u32_e32 v119, vcc, 0, v117, vcc
	global_store_dwordx4 v[118:119], v[112:115], off offset:128 nt
	v_add_co_u32_e32 v118, vcc, 0x4b00000, v116
	s_nop 1
	v_addc_co_u32_e32 v119, vcc, 0, v117, vcc
	global_store_dwordx4 v[118:119], v[112:115], off offset:128 nt
	v_add_co_u32_e32 v118, vcc, 0x5a00000, v116
	s_nop 1
	v_addc_co_u32_e32 v119, vcc, 0, v117, vcc
	v_add_co_u32_e32 v116, vcc, 0x6900000, v116
	global_store_dwordx4 v[118:119], v[112:115], off offset:128 nt
	s_nop 0
	v_addc_co_u32_e32 v117, vcc, 0, v117, vcc
	global_store_dwordx4 v[116:117], v[112:115], off offset:128 nt

; __global__ void __launch_bounds__(NTHREADS) fwd_megakernel(Params p) {
;   __shared__ __attribute__((aligned(16))) unsigned char smem_all[2 * VSZ + 16];
	.amdhsa_kernel _Z14fwd_megakernel6Params
		.amdhsa_group_segment_fixed_size 149520
		.amdhsa_private_segment_fixed_size 0
		.amdhsa_kernarg_size 728
		.amdhsa_user_sgpr_count 2
		.amdhsa_user_sgpr_dispatch_ptr 0
		.amdhsa_user_sgpr_queue_ptr 0
		.amdhsa_user_sgpr_kernarg_segment_ptr 1
		.amdhsa_user_sgpr_dispatch_id 0
		.amdhsa_user_sgpr_kernarg_preload_length 0
		.amdhsa_user_sgpr_kernarg_preload_offset 0
		.amdhsa_user_sgpr_private_segment_size 0
		.amdhsa_uses_dynamic_stack 0
		.amdhsa_enable_private_segment 0
		.amdhsa_system_sgpr_workgroup_id_x 1
		.amdhsa_system_sgpr_workgroup_id_y 0
		.amdhsa_system_sgpr_workgroup_id_z 0
		.amdhsa_system_sgpr_workgroup_info 0
		.amdhsa_system_vgpr_workitem_id 2
		.amdhsa_next_free_vgpr 255
		.amdhsa_next_free_sgpr 102
		.amdhsa_accum_offset 256
		.amdhsa_reserve_vcc 1
		.amdhsa_float_round_mode_32 0
		.amdhsa_float_round_mode_16_64 0
		.amdhsa_float_denorm_mode_32 3
		.amdhsa_float_denorm_mode_16_64 3
		.amdhsa_dx10_clamp 1
		.amdhsa_ieee_mode 1
		.amdhsa_fp16_overflow 0
		.amdhsa_tg_split 0
		.amdhsa_exception_fp_ieee_invalid_op 0
		.amdhsa_exception_fp_denorm_src 0
		.amdhsa_exception_fp_ieee_div_zero 0
		.amdhsa_exception_fp_ieee_overflow 0
		.amdhsa_exception_fp_ieee_underflow 0
		.amdhsa_exception_fp_ieee_inexact 0
		.amdhsa_exception_int_div_zero 0
	.end_amdhsa_kernel

; __global__ void __launch_bounds__(NTHREADS) fwd_megakernel(Params p) {
;   __shared__ __attribute__((aligned(16))) unsigned char smem_all[2 * VSZ + 16];
amdhsa.kernels:
  - .agpr_count:     0
    .args:
      - .offset:         0
        .size:           472
        .value_kind:     by_value
      - .offset:         472
        .size:           4
        .value_kind:     hidden_block_count_x
      - .offset:         476
        .size:           4
        .value_kind:     hidden_block_count_y
      - .offset:         480
        .size:           4
        .value_kind:     hidden_block_count_z
      - .offset:         484
        .size:           2
        .value_kind:     hidden_group_size_x
      - .offset:         486
        .size:           2
        .value_kind:     hidden_group_size_y
      - .offset:         488
        .size:           2
        .value_kind:     hidden_group_size_z
      - .offset:         490
        .size:           2
        .value_kind:     hidden_remainder_x
      - .offset:         492
        .size:           2
        .value_kind:     hidden_remainder_y
      - .offset:         494
        .size:           2
        .value_kind:     hidden_remainder_z
      - .offset:         512
        .size:           8
        .value_kind:     hidden_global_offset_x
      - .offset:         520
        .size:           8
        .value_kind:     hidden_global_offset_y
      - .offset:         528
        .size:           8
        .value_kind:     hidden_global_offset_z
      - .offset:         536
        .size:           2
        .value_kind:     hidden_grid_dims
      - .offset:         560
        .size:           8
        .value_kind:     hidden_multigrid_sync_arg
    .group_segment_fixed_size: 149520
    .kernarg_segment_align: 8
    .kernarg_segment_size: 728
    .language:       OpenCL C
    .language_version:
      - 2
      - 0
    .max_flat_workgroup_size: 512
    .name:           _Z14fwd_megakernel6Params
    .private_segment_fixed_size: 0
    .sgpr_count:     108
    .sgpr_spill_count: 161
    .symbol:         _Z14fwd_megakernel6Params.kd
    .uniform_work_group_size: 1
    .uses_dynamic_stack: false
    .vgpr_count:     255
    .vgpr_spill_count: 0
    .wavefront_size: 64
